# K-loop first iteration after an epilogue: vmcnt(8)->vmcnt(24) on the first two waits (epilogue stores may stay in flight), all 6 GEMM phases
# speedup vs baseline: 1.0144x; 1.0144x over previous
; #define PG8_STAGE(bufoff, gbase, voff) do { _Pragma("unroll") for (int _i = 0; _i < 2; ++_i) \
;         __builtin_amdgcn_global_load_lds((const unsigned*)((const char*)(gbase) + (voff)[_i]), (PG8_LAS unsigned*)(lds + (bufoff) + ldsw + _i * 8192), 16, 0, 0); } while (0)
; #define PG8_WAIT_V(n) asm volatile("s_waitcnt vmcnt(" #n ")" ::: "memory")
; #define PG8_BAR __builtin_amdgcn_s_barrier()
; template <class Epi, class Sched, bool ALIGN_EPI = false, bool SP2 = false>
; __device__ __forceinline__ void gemm_phase(PG8_LAS unsigned char* lds, const Gemm g, const Sched& S, const Epi& E) {
;     ...
;     const int tid = tid_, wid = __builtin_amdgcn_readfirstlane(tid >> 6), lane = tid & 63, wr = wid >> 2, wc = wid & 3, fr = lane & 15, fq = lane >> 4;
;     const int K = g.K, nt = K / BK;
;     unsigned voffA[2], voffB[2];
; #pragma unroll
;     for (int i = 0; i < 2; ++i) { int R, C; stage_rc(tid * 16 + i * 8192, R, C); const int Rb = Epi::PERM ? ((R & ~31) + perm32(R & 31)) : R;
;         voffA[i] = (unsigned)(R * K + C) * 2u; voffB[i] = (unsigned)(Rb * K + C) * 2u; }
;     const size_t kstep = (size_t)(BK * 2);
;     const size_t hstep = (size_t)HALF * K * 2;
;     const size_t tstep = 2 * hstep;
;     const unsigned ldsw = (unsigned)wid * 1024u;
;     const int aoff = lds_byte(wr * 64 + fr, fq * 8), boff = lds_byte(wc * 32 + fr, fq * 8);
;     ...
;         PG8_STAGE(PG8_SB(0, 0), cB, voffB); PG8_STAGE(PG8_SB(0, 1), cB + hstep, voffB); PG8_STAGE(PG8_SA(0, 0), cA, voffA); PG8_STAGE(PG8_SA(0, 1), cA + hstep, voffA);
;         if (wr == 1) PG8_BAR;
;         PG8_WAIT_V(2); PG8_BAR;
;         PG8_STAGE(PG8_SB(1, 0), cB + kstep, voffB); PG8_STAGE(PG8_SA(1, 0), cA + kstep, voffA); PG8_STAGE(PG8_SB(1, 1), cB + hstep + kstep, voffB);
;         PG8_WAIT_V(6); PG8_BAR;
.LBB0_111:
	v_readlane_b32 s12, v254, 6
	v_readlane_b32 s13, v254, 7
	s_and_b64 s[12:13], s[12:13], exec
	s_cselect_b32 s80, 0xf7, s3
	s_add_u32 s20, s86, 0x26f00000
	s_addc_u32 s21, s87, 0
	s_add_u32 s81, s86, 0x2b000000
	s_addc_u32 s82, s87, 0
	s_add_u32 s1, s86, 0x31200000
	v_writelane_b32 v254, s1, 11
	s_addc_u32 s1, s87, 0
	v_writelane_b32 v254, s1, 12
	s_add_u32 s1, s86, 0x37200000
	v_writelane_b32 v254, s1, 14
	s_addc_u32 s1, s87, 0
	s_mov_b64 s[22:23], 0x80
	v_writelane_b32 v254, s1, 16
	s_and_b32 s1, s9, 3
	s_add_i32 m0, s37, 0x18000
	v_lshl_add_u64 v[4:5], v[4:5], 0, s[22:23]
	s_lshl_b32 s68, s10, 6
	s_lshl_b32 s12, s10, 13
	s_lshl_b32 s13, s1, 5
	s_lshl_b32 s16, s1, 12
	s_waitcnt vmcnt(2)
	s_barrier
	global_load_lds_dwordx4 v[4:5], off
	v_lshl_add_u64 v[2:3], v[2:3], 0, s[22:23]
	s_add_i32 m0, s37, 0x1a000
	s_add_i32 s95, s37, 0x8000
	s_add_i32 s96, s37, 0xa000
	global_load_lds_dwordx4 v[2:3], off
	v_lshl_add_u64 v[0:1], v[0:1], 0, s[22:23]
	s_mov_b32 m0, s95
	s_add_u32 s10, s6, 0x40080
	global_load_lds_dwordx4 v[0:1], off
	v_lshl_add_u64 v[0:1], v[6:7], 0, s[22:23]
	s_mov_b32 m0, s96
	s_addc_u32 s11, s7, 0
	global_load_lds_dwordx4 v[0:1], off
	s_add_i32 m0, s37, 0x1c000
	v_lshl_add_u64 v[0:1], s[10:11], 0, v[158:159]
	global_load_lds_dwordx4 v[0:1], off
	v_lshl_add_u64 v[0:1], s[10:11], 0, v[162:163]
	s_add_i32 m0, s37, 0x1e000
	v_and_b32_e32 v153, 15, v8
	global_load_lds_dwordx4 v[0:1], off
	v_lshrrev_b32_e32 v0, 1, v8
	v_and_b32_e32 v166, 24, v0
	v_lshlrev_b32_e32 v0, 1, v166
	v_lshlrev_b32_e32 v1, 2, v8
	v_lshl_or_b32 v0, v153, 6, v0
	v_and_b32_e32 v1, 32, v1
	v_bitop3_b32 v2, v0, s12, v1 bitop3:0xde
	v_bitop3_b32 v169, v0, s16, v1 bitop3:0xde
	v_lshlrev_b32_e32 v0, 14, v9
	s_cmpk_lt_u32 s8, 0x100
	v_and_b32_e32 v0, 0xffff8000, v0
	s_cselect_b64 s[70:71], -1, 0
	s_bfe_u32 s8, s9, 0x10001
	v_lshl_add_u32 v0, v10, 11, v0
	v_and_b32_e32 v1, 1, v9
	v_writelane_b32 v254, s8, 18
	s_bfe_u32 s8, s1, 0x1a0001
	v_lshl_or_b32 v0, v1, 6, v0
	s_or_b32 s8, s8, 2
	v_lshl_add_u32 v176, v11, 1, v0
	v_lshlrev_b32_e32 v0, 14, v12
	v_writelane_b32 v254, s8, 20
	v_and_b32_e32 v0, 0xffff8000, v0
	s_waitcnt vmcnt(6)
	v_lshl_add_u32 v0, v13, 11, v0
	v_and_b32_e32 v1, 1, v12
	v_writelane_b32 v254, s46, 21
	v_and_b32_e32 v171, 7, v8
	s_lshl_b32 s18, s1, 6
	v_lshl_or_b32 v0, v1, 6, v0
	s_add_i32 s33, 0, 0x10000
	s_add_i32 s83, 0, 0x14000
	v_writelane_b32 v254, s68, 22
	v_or_b32_e32 v168, s13, v166
	v_bitop3_b32 v170, s13, 56, v166 bitop3:0xc8
	v_or_b32_e32 v172, s18, v166
	v_add_u32_e32 v174, 7, v171
	s_ashr_i32 s19, s80, 31
	s_ashr_i32 s97, s2, 31
	v_mov_b32_e32 v177, v165
	v_lshl_add_u32 v178, v14, 1, v0
	v_mov_b32_e32 v179, v165
	v_mov_b64_e32 v[180:181], 0x134c
	v_mov_b64_e32 v[182:183], 0x134b
	v_add_u32_e32 v173, s33, v169
	v_add_u32_e32 v175, s83, v169
	v_add_u32_e32 v194, 0, v2
	v_mov_b32_e32 v195, 0x358637bd
	s_movk_i32 s40, 0x7f0
	v_mbcnt_hi_u32_b32 v196, -1, v227
	v_mov_b32_e32 v197, 0x7cf
	v_mov_b32_e32 v198, 0x7df
	v_mov_b32_e32 v199, 0x7ef
	v_mov_b32_e32 v200, 0x7ff
	s_mov_b32 s91, 0
	v_writelane_b32 v254, s70, 23
	s_barrier
	s_nop 0
	v_writelane_b32 v254, s71, 24
	s_mov_b32 s99, 0
	s_branch .LBB0_114

; #define PG8_BAR __builtin_amdgcn_s_barrier()
; template <class Epi, class Sched, bool ALIGN_EPI = false, bool SP2 = false>
; __device__ __forceinline__ void gemm_phase(PG8_LAS unsigned char* lds, const Gemm g, const Sched& S, const Epi& E) {
;     ...
;         if (!has_next) break;
; #pragma unroll
;         for (int a = 0; a < 2; ++a)
; #pragma unroll
;             for (int b = 0; b < 2; ++b)
; #pragma unroll
;                 for (int m = 0; m < 4; ++m)
; #pragma unroll
;                     for (int n = 0; n < 2; ++n) acc[a][b][m][n] = (f32x4){0.f, 0.f, 0.f, 0.f};
;         cur = nxt; cA = nA; cB = nB; ++ui;
;         if constexpr (ALIGN_EPI) { if (wr == 1) PG8_BAR; }
.LBB0_113:
	s_mov_b32 s99, 1
	s_andn2_b64 vcc, exec, s[0:1]
	s_mov_b32 s36, s26
	s_mov_b32 s0, s28
	s_mov_b64 s[6:7], s[34:35]
	s_mov_b64 s[4:5], s[30:31]
	s_cbranch_vccz .LBB0_426

; #define PG8_STAGE(bufoff, gbase, voff) do { _Pragma("unroll") for (int _i = 0; _i < 2; ++_i) \
;         __builtin_amdgcn_global_load_lds((const unsigned*)((const char*)(gbase) + (voff)[_i]), (PG8_LAS unsigned*)(lds + (bufoff) + ldsw + _i * 8192), 16, 0, 0); } while (0)
; #define PG8_LDA(dst, b, h) do { _Pragma("unroll") for (int m = 0; m < 4; ++m) _Pragma("unroll") for (int k = 0; k < 2; ++k) dst[m][k] = *(const PG8_LAS bf16x8*)(lds + PG8_SA(b, h) + aoff + m * 2048 + k * 1024); } while (0)
; #define PG8_LDB(dst, b, h) do { _Pragma("unroll") for (int n = 0; n < 2; ++n) _Pragma("unroll") for (int k = 0; k < 2; ++k) dst[n][k] = *(const PG8_LAS bf16x8*)(lds + PG8_SB(b, h) + boff + n * 2048 + k * 1024); } while (0)
; #define PG8_MMA(ai, bj, At, Bt) do { __builtin_amdgcn_s_setprio(1); _Pragma("unroll") for (int m = 0; m < 4; ++m) _Pragma("unroll") for (int n = 0; n < 2; ++n) _Pragma("unroll") for (int k = 0; k < 2; ++k) \
;         acc[ai][bj][m][n] = __builtin_amdgcn_mfma_f32_16x16x32_bf16(Bt[n][k], At[m][k], acc[ai][bj][m][n], 0, 0, 0); __builtin_amdgcn_s_setprio(0); } while (0)
; #define PG8_BAR __builtin_amdgcn_s_barrier()
; template <class Epi, class Sched, bool ALIGN_EPI = false, bool SP2 = false>
; __device__ __forceinline__ void gemm_phase(PG8_LAS unsigned char* lds, const Gemm g, const Sched& S, const Epi& E) {
;     ...
;         const bool has_next = S.next(ui + 1, nxt);
;         const char* nA = has_next ? (const char*)g.A + (size_t)nxt.pm * tstep : cA; const char* nB = has_next ? (const char*)g.Bt + (size_t)nxt.pn * tstep : cB;
;         for (int t = 0; t < nt; t += 2) {
;             const bool last = (t == nt - 2);
;             const char* a1 = cA + (size_t)(t + 1) * kstep;
;             const char* a2 = last ? nA : cA + (size_t)(t + 2) * kstep; const char* b2 = last ? nB : cB + (size_t)(t + 2) * kstep;
;             const char* a3 = a2 + kstep; const char* b3 = b2 + kstep;
;             if (last && has_next) S.a_ready(nxt);
;             if constexpr (SP2) {
;             PG8_LDB(B0, 0, 0); PG8_LDB(B1, 0, 1); PG8_SCHED; PG8_LDA(At, 0, 0); PG8_STAGE(PG8_SA(1, 1), a1 + hstep, voffA);
;             PG8_WAIT_V(8); PG8_WAIT_L(0); PG8_BAR; PG8_MMA(0, 0, At, B0); PG8_MMA(0, 1, At, B1); PG8_BAR; PG8_SCHED;
;             PG8_LDA(At, 0, 1); PG8_STAGE(PG8_SB(0, 0), b2, voffB); PG8_STAGE(PG8_SB(0, 1), b2 + hstep, voffB); PG8_STAGE(PG8_SA(0, 0), a2, voffA);
.LBB0_121:
	ds_read_b128 v[128:131], v173
	ds_read_b128 v[132:135], v173 offset:1024
	ds_read_b128 v[136:139], v173 offset:2048
	ds_read_b128 v[140:143], v173 offset:3072
	ds_read_b128 v[144:147], v175
	ds_read_b128 v[148:151], v175 offset:1024
	ds_read_b128 v[184:187], v175 offset:2048
	ds_read_b128 v[188:191], v175 offset:3072
	s_add_u32 s6, s4, 0xfffc0080
	s_addc_u32 s7, s5, -1
	s_cmp_eq_u32 s27, 12
	s_cselect_b32 s9, s1, s7
	s_cselect_b32 s8, s10, s6
	s_cselect_b32 s7, s11, s25
	s_cselect_b32 s6, s16, s24
	v_lshl_add_u64 v[192:193], s[4:5], 0, v[176:177]
	s_add_i32 m0, s37, 0xc000
	ds_read_b128 v[202:205], v194
	ds_read_b128 v[206:209], v194 offset:1024
	ds_read_b128 v[210:213], v194 offset:2048
	ds_read_b128 v[214:217], v194 offset:3072
	ds_read_b128 v[218:221], v194 offset:4096
	ds_read_b128 v[222:225], v194 offset:5120
	ds_read_b128 v[230:233], v194 offset:6144
	ds_read_b128 v[234:237], v194 offset:7168
	global_load_lds_dwordx4 v[192:193], off
	v_lshl_add_u64 v[192:193], s[4:5], 0, v[178:179]
	s_add_i32 m0, s37, 0xe000
	s_nop 0
	global_load_lds_dwordx4 v[192:193], off
	s_cmp_eq_u32 s99, 1
	s_cbranch_scc1 .Lrw_P1_0
	s_waitcnt vmcnt(8)
	s_branch .Lrj_P1_0
.Lrw_P1_0:
	s_waitcnt vmcnt(24)
.Lrj_P1_0:
	s_waitcnt lgkmcnt(0)
	s_barrier
	s_setprio 1
	s_waitcnt lgkmcnt(0)
	v_mfma_f32_16x16x32_bf16 v[124:127], v[128:131], v[202:205], v[124:127]
	v_mfma_f32_16x16x32_bf16 v[120:123], v[136:139], v[202:205], v[120:123]
	v_mfma_f32_16x16x32_bf16 v[108:111], v[128:131], v[210:213], v[108:111]
	v_mfma_f32_16x16x32_bf16 v[104:107], v[136:139], v[210:213], v[104:107]
	v_mfma_f32_16x16x32_bf16 v[92:95], v[128:131], v[218:221], v[92:95]
	v_mfma_f32_16x16x32_bf16 v[88:91], v[136:139], v[218:221], v[88:91]
	v_mfma_f32_16x16x32_bf16 v[76:79], v[128:131], v[230:233], v[76:79]
	v_mfma_f32_16x16x32_bf16 v[72:75], v[136:139], v[230:233], v[72:75]
	v_mfma_f32_16x16x32_bf16 v[124:127], v[132:135], v[206:209], v[124:127]
	v_mfma_f32_16x16x32_bf16 v[120:123], v[140:143], v[206:209], v[120:123]
	v_mfma_f32_16x16x32_bf16 v[108:111], v[132:135], v[214:217], v[108:111]
	v_mfma_f32_16x16x32_bf16 v[104:107], v[140:143], v[214:217], v[104:107]
	v_mfma_f32_16x16x32_bf16 v[92:95], v[132:135], v[222:225], v[92:95]
	v_mfma_f32_16x16x32_bf16 v[88:91], v[140:143], v[222:225], v[88:91]
	v_mfma_f32_16x16x32_bf16 v[76:79], v[132:135], v[234:237], v[76:79]
	v_mfma_f32_16x16x32_bf16 v[72:75], v[140:143], v[234:237], v[72:75]
	s_setprio 0
	s_setprio 1
	v_mfma_f32_16x16x32_bf16 v[116:119], v[144:147], v[202:205], v[116:119]
	v_mfma_f32_16x16x32_bf16 v[112:115], v[184:187], v[202:205], v[112:115]
	v_mfma_f32_16x16x32_bf16 v[100:103], v[144:147], v[210:213], v[100:103]
	v_mfma_f32_16x16x32_bf16 v[96:99], v[184:187], v[210:213], v[96:99]
	v_mfma_f32_16x16x32_bf16 v[84:87], v[144:147], v[218:221], v[84:87]
	v_mfma_f32_16x16x32_bf16 v[80:83], v[184:187], v[218:221], v[80:83]
	v_mfma_f32_16x16x32_bf16 v[68:71], v[144:147], v[230:233], v[68:71]
	v_mfma_f32_16x16x32_bf16 v[64:67], v[184:187], v[230:233], v[64:67]
	v_mfma_f32_16x16x32_bf16 v[116:119], v[148:151], v[206:209], v[116:119]
	v_mfma_f32_16x16x32_bf16 v[112:115], v[188:191], v[206:209], v[112:115]
	v_mfma_f32_16x16x32_bf16 v[100:103], v[148:151], v[214:217], v[100:103]
	v_mfma_f32_16x16x32_bf16 v[96:99], v[188:191], v[214:217], v[96:99]
	v_mfma_f32_16x16x32_bf16 v[84:87], v[148:151], v[222:225], v[84:87]
	v_mfma_f32_16x16x32_bf16 v[80:83], v[188:191], v[222:225], v[80:83]
	v_mfma_f32_16x16x32_bf16 v[68:71], v[148:151], v[234:237], v[68:71]
	v_mfma_f32_16x16x32_bf16 v[64:67], v[188:191], v[234:237], v[64:67]
	s_setprio 0
	s_barrier
	s_add_i32 s29, s33, s74
	v_lshl_add_u64 v[192:193], s[6:7], 0, v[158:159]
	s_mov_b32 m0, s29
	ds_read_b128 v[202:205], v194 offset:16384
	ds_read_b128 v[206:209], v194 offset:17408
	ds_read_b128 v[210:213], v194 offset:18432
	ds_read_b128 v[214:217], v194 offset:19456
	ds_read_b128 v[218:221], v194 offset:20480
	ds_read_b128 v[222:225], v194 offset:21504
	ds_read_b128 v[230:233], v194 offset:22528
	ds_read_b128 v[234:237], v194 offset:23552
	global_load_lds_dwordx4 v[192:193], off
	s_add_i32 m0, s29, 0x2000
	s_add_u32 s38, s6, 0x40000
	v_lshl_add_u64 v[238:239], s[6:7], 0, v[162:163]
	s_addc_u32 s39, s7, 0
	s_add_i32 s29, s83, s74
	global_load_lds_dwordx4 v[238:239], off
	v_lshl_add_u64 v[240:241], s[38:39], 0, v[158:159]
	s_mov_b32 m0, s29
	v_lshl_add_u64 v[242:243], s[8:9], 0, v[160:161]
	global_load_lds_dwordx4 v[240:241], off
	v_lshl_add_u64 v[240:241], s[38:39], 0, v[162:163]
	s_add_i32 m0, s29, 0x2000
	s_nop 0
	global_load_lds_dwordx4 v[240:241], off
	v_lshl_add_u64 v[240:241], s[8:9], 0, v[156:157]
	s_mov_b32 m0, s37
	s_nop 0
	global_load_lds_dwordx4 v[240:241], off
	s_mov_b32 m0, s75
	s_nop 0
	global_load_lds_dwordx4 v[242:243], off
	s_cmp_eq_u32 s99, 1
	s_cbranch_scc1 .Lrw_P1_1
	s_waitcnt vmcnt(8)
	s_branch .Lrj_P1_1

; #define PG8_STAGE(bufoff, gbase, voff) do { _Pragma("unroll") for (int _i = 0; _i < 2; ++_i) \
;         __builtin_amdgcn_global_load_lds((const unsigned*)((const char*)(gbase) + (voff)[_i]), (PG8_LAS unsigned*)(lds + (bufoff) + ldsw + _i * 8192), 16, 0, 0); } while (0)
; #define PG8_LDA(dst, b, h) do { _Pragma("unroll") for (int m = 0; m < 4; ++m) _Pragma("unroll") for (int k = 0; k < 2; ++k) dst[m][k] = *(const PG8_LAS bf16x8*)(lds + PG8_SA(b, h) + aoff + m * 2048 + k * 1024); } while (0)
; #define PG8_LDB(dst, b, h) do { _Pragma("unroll") for (int n = 0; n < 2; ++n) _Pragma("unroll") for (int k = 0; k < 2; ++k) dst[n][k] = *(const PG8_LAS bf16x8*)(lds + PG8_SB(b, h) + boff + n * 2048 + k * 1024); } while (0)
; #define PG8_MMA(ai, bj, At, Bt) do { __builtin_amdgcn_s_setprio(1); _Pragma("unroll") for (int m = 0; m < 4; ++m) _Pragma("unroll") for (int n = 0; n < 2; ++n) _Pragma("unroll") for (int k = 0; k < 2; ++k) \
;         acc[ai][bj][m][n] = __builtin_amdgcn_mfma_f32_16x16x32_bf16(Bt[n][k], At[m][k], acc[ai][bj][m][n], 0, 0, 0); __builtin_amdgcn_s_setprio(0); } while (0)
; #define PG8_WAIT_V(n) asm volatile("s_waitcnt vmcnt(" #n ")" ::: "memory")
; #define PG8_WAIT_L(n) asm volatile("s_waitcnt lgkmcnt(" #n ")" ::: "memory")
; #define PG8_BAR __builtin_amdgcn_s_barrier()
; #define PG8_SCHED __builtin_amdgcn_sched_barrier(0)
; template <class Epi, class Sched, bool ALIGN_EPI = false, bool SP2 = false>
; __device__ __forceinline__ void gemm_phase(PG8_LAS unsigned char* lds, const Gemm g, const Sched& S, const Epi& E) {
;     ...
;             PG8_WAIT_V(8); PG8_WAIT_L(0); PG8_BAR; PG8_MMA(1, 0, At, B0); PG8_MMA(1, 1, At, B1); PG8_BAR; PG8_SCHED;
;             PG8_LDB(B0, 1, 0); PG8_LDB(B1, 1, 1); PG8_SCHED; PG8_LDA(At, 1, 0); PG8_STAGE(PG8_SA(0, 1), a2 + hstep, voffA);
;             PG8_WAIT_V(8); PG8_WAIT_L(0); PG8_BAR; PG8_MMA(0, 0, At, B0); PG8_MMA(0, 1, At, B1); PG8_BAR; PG8_SCHED;
.Lrj_P1_1:
	s_waitcnt lgkmcnt(0)
	s_barrier
	s_setprio 1
	s_waitcnt lgkmcnt(0)
	v_mfma_f32_16x16x32_bf16 v[60:63], v[128:131], v[202:205], v[60:63]
	v_mfma_f32_16x16x32_bf16 v[56:59], v[136:139], v[202:205], v[56:59]
	v_mfma_f32_16x16x32_bf16 v[44:47], v[128:131], v[210:213], v[44:47]
	v_mfma_f32_16x16x32_bf16 v[40:43], v[136:139], v[210:213], v[40:43]
	v_mfma_f32_16x16x32_bf16 v[28:31], v[128:131], v[218:221], v[28:31]
	v_mfma_f32_16x16x32_bf16 v[24:27], v[136:139], v[218:221], v[24:27]
	v_mfma_f32_16x16x32_bf16 v[12:15], v[128:131], v[230:233], v[12:15]
	v_mfma_f32_16x16x32_bf16 v[8:11], v[136:139], v[230:233], v[8:11]
	v_mfma_f32_16x16x32_bf16 v[60:63], v[132:135], v[206:209], v[60:63]
	v_mfma_f32_16x16x32_bf16 v[56:59], v[140:143], v[206:209], v[56:59]
	v_mfma_f32_16x16x32_bf16 v[44:47], v[132:135], v[214:217], v[44:47]
	v_mfma_f32_16x16x32_bf16 v[40:43], v[140:143], v[214:217], v[40:43]
	v_mfma_f32_16x16x32_bf16 v[28:31], v[132:135], v[222:225], v[28:31]
	v_mfma_f32_16x16x32_bf16 v[24:27], v[140:143], v[222:225], v[24:27]
	v_mfma_f32_16x16x32_bf16 v[12:15], v[132:135], v[234:237], v[12:15]
	v_mfma_f32_16x16x32_bf16 v[8:11], v[140:143], v[234:237], v[8:11]
	s_setprio 0
	s_setprio 1
	v_mfma_f32_16x16x32_bf16 v[52:55], v[144:147], v[202:205], v[52:55]
	v_mfma_f32_16x16x32_bf16 v[48:51], v[184:187], v[202:205], v[48:51]
	v_mfma_f32_16x16x32_bf16 v[36:39], v[144:147], v[210:213], v[36:39]
	v_mfma_f32_16x16x32_bf16 v[32:35], v[184:187], v[210:213], v[32:35]
	v_mfma_f32_16x16x32_bf16 v[20:23], v[144:147], v[218:221], v[20:23]
	v_mfma_f32_16x16x32_bf16 v[16:19], v[184:187], v[218:221], v[16:19]
	v_mfma_f32_16x16x32_bf16 v[4:7], v[144:147], v[230:233], v[4:7]
	v_mfma_f32_16x16x32_bf16 v[0:3], v[184:187], v[230:233], v[0:3]
	v_mfma_f32_16x16x32_bf16 v[52:55], v[148:151], v[206:209], v[52:55]
	v_mfma_f32_16x16x32_bf16 v[48:51], v[188:191], v[206:209], v[48:51]
	v_mfma_f32_16x16x32_bf16 v[36:39], v[148:151], v[214:217], v[36:39]
	v_mfma_f32_16x16x32_bf16 v[32:35], v[188:191], v[214:217], v[32:35]
	v_mfma_f32_16x16x32_bf16 v[20:23], v[148:151], v[222:225], v[20:23]
	v_mfma_f32_16x16x32_bf16 v[16:19], v[188:191], v[222:225], v[16:19]
	v_mfma_f32_16x16x32_bf16 v[4:7], v[148:151], v[234:237], v[4:7]
	v_mfma_f32_16x16x32_bf16 v[0:3], v[188:191], v[234:237], v[0:3]
	s_setprio 0
	s_barrier
	s_add_i32 s29, 0, 0x18000
	s_add_i32 s38, 0, 0x1c000
	v_add_u32_e32 v140, s29, v169
	v_add_u32_e32 v164, s38, v169
	ds_read_b128 v[128:131], v140
	ds_read_b128 v[132:135], v140 offset:1024
	ds_read_b128 v[136:139], v140 offset:2048
	ds_read_b128 v[140:143], v140 offset:3072
	ds_read_b128 v[144:147], v164
	ds_read_b128 v[148:151], v164 offset:1024
	ds_read_b128 v[184:187], v164 offset:2048
	ds_read_b128 v[188:191], v164 offset:3072
	s_add_u32 s8, s8, 0x40000
	s_addc_u32 s9, s9, 0
	s_mov_b32 m0, s76
	v_lshl_add_u64 v[244:245], s[8:9], 0, v[156:157]
	ds_read_b128 v[202:205], v194 offset:32768
	ds_read_b128 v[206:209], v194 offset:33792
	ds_read_b128 v[210:213], v194 offset:34816
	ds_read_b128 v[214:217], v194 offset:35840
	ds_read_b128 v[218:221], v194 offset:36864
	ds_read_b128 v[222:225], v194 offset:37888
	ds_read_b128 v[230:233], v194 offset:38912
	ds_read_b128 v[234:237], v194 offset:39936
	global_load_lds_dwordx4 v[244:245], off
	v_lshl_add_u64 v[244:245], s[8:9], 0, v[160:161]
	s_mov_b32 m0, s77
	s_nop 0
	global_load_lds_dwordx4 v[244:245], off
	s_waitcnt vmcnt(8)
	s_waitcnt lgkmcnt(0)
	s_barrier
	s_setprio 1
	s_waitcnt lgkmcnt(0)
	v_mfma_f32_16x16x32_bf16 v[124:127], v[128:131], v[202:205], v[124:127]
	v_mfma_f32_16x16x32_bf16 v[120:123], v[136:139], v[202:205], v[120:123]
	v_mfma_f32_16x16x32_bf16 v[108:111], v[128:131], v[210:213], v[108:111]
	v_mfma_f32_16x16x32_bf16 v[104:107], v[136:139], v[210:213], v[104:107]
	v_mfma_f32_16x16x32_bf16 v[92:95], v[128:131], v[218:221], v[92:95]
	v_mfma_f32_16x16x32_bf16 v[88:91], v[136:139], v[218:221], v[88:91]
	v_mfma_f32_16x16x32_bf16 v[76:79], v[128:131], v[230:233], v[76:79]
	v_mfma_f32_16x16x32_bf16 v[72:75], v[136:139], v[230:233], v[72:75]
	v_mfma_f32_16x16x32_bf16 v[124:127], v[132:135], v[206:209], v[124:127]
	v_mfma_f32_16x16x32_bf16 v[120:123], v[140:143], v[206:209], v[120:123]
	v_mfma_f32_16x16x32_bf16 v[108:111], v[132:135], v[214:217], v[108:111]
	v_mfma_f32_16x16x32_bf16 v[104:107], v[140:143], v[214:217], v[104:107]
	v_mfma_f32_16x16x32_bf16 v[92:95], v[132:135], v[222:225], v[92:95]
	v_mfma_f32_16x16x32_bf16 v[88:91], v[140:143], v[222:225], v[88:91]
	v_mfma_f32_16x16x32_bf16 v[76:79], v[132:135], v[234:237], v[76:79]
	v_mfma_f32_16x16x32_bf16 v[72:75], v[140:143], v[234:237], v[72:75]
	s_setprio 0
	s_setprio 1
	v_mfma_f32_16x16x32_bf16 v[116:119], v[144:147], v[202:205], v[116:119]
	v_mfma_f32_16x16x32_bf16 v[112:115], v[184:187], v[202:205], v[112:115]
	v_mfma_f32_16x16x32_bf16 v[100:103], v[144:147], v[210:213], v[100:103]
	v_mfma_f32_16x16x32_bf16 v[96:99], v[184:187], v[210:213], v[96:99]
	v_mfma_f32_16x16x32_bf16 v[84:87], v[144:147], v[218:221], v[84:87]
	v_mfma_f32_16x16x32_bf16 v[80:83], v[184:187], v[218:221], v[80:83]
	v_mfma_f32_16x16x32_bf16 v[68:71], v[144:147], v[230:233], v[68:71]
	v_mfma_f32_16x16x32_bf16 v[64:67], v[184:187], v[230:233], v[64:67]
	v_mfma_f32_16x16x32_bf16 v[116:119], v[148:151], v[206:209], v[116:119]
	v_mfma_f32_16x16x32_bf16 v[112:115], v[188:191], v[206:209], v[112:115]
	v_mfma_f32_16x16x32_bf16 v[100:103], v[148:151], v[214:217], v[100:103]
	v_mfma_f32_16x16x32_bf16 v[96:99], v[188:191], v[214:217], v[96:99]
	v_mfma_f32_16x16x32_bf16 v[84:87], v[148:151], v[222:225], v[84:87]
	v_mfma_f32_16x16x32_bf16 v[80:83], v[188:191], v[222:225], v[80:83]
	v_mfma_f32_16x16x32_bf16 v[68:71], v[148:151], v[234:237], v[68:71]
	v_mfma_f32_16x16x32_bf16 v[64:67], v[188:191], v[234:237], v[64:67]
	s_setprio 0
	s_barrier
; #define PG8_STAGE(bufoff, gbase, voff) do { _Pragma("unroll") for (int _i = 0; _i < 2; ++_i) \
;         __builtin_amdgcn_global_load_lds((const unsigned*)((const char*)(gbase) + (voff)[_i]), (PG8_LAS unsigned*)(lds + (bufoff) + ldsw + _i * 8192), 16, 0, 0); } while (0)
; #define PG8_LDA(dst, b, h) do { _Pragma("unroll") for (int m = 0; m < 4; ++m) _Pragma("unroll") for (int k = 0; k < 2; ++k) dst[m][k] = *(const PG8_LAS bf16x8*)(lds + PG8_SA(b, h) + aoff + m * 2048 + k * 1024); } while (0)
; #define PG8_MMA(ai, bj, At, Bt) do { __builtin_amdgcn_s_setprio(1); _Pragma("unroll") for (int m = 0; m < 4; ++m) _Pragma("unroll") for (int n = 0; n < 2; ++n) _Pragma("unroll") for (int k = 0; k < 2; ++k) \
;         acc[ai][bj][m][n] = __builtin_amdgcn_mfma_f32_16x16x32_bf16(Bt[n][k], At[m][k], acc[ai][bj][m][n], 0, 0, 0); __builtin_amdgcn_s_setprio(0); } while (0)
; #define PG8_WAIT_V(n) asm volatile("s_waitcnt vmcnt(" #n ")" ::: "memory")
; #define PG8_WAIT_L(n) asm volatile("s_waitcnt lgkmcnt(" #n ")" ::: "memory")
; #define PG8_BAR __builtin_amdgcn_s_barrier()
; #define PG8_SCHED __builtin_amdgcn_sched_barrier(0)
; template <class Epi, class Sched, bool ALIGN_EPI = false, bool SP2 = false>
; __device__ __forceinline__ void gemm_phase(PG8_LAS unsigned char* lds, const Gemm g, const Sched& S, const Epi& E) {
;     ...
;             PG8_LDA(At, 1, 1); PG8_STAGE(PG8_SB(1, 0), b3, voffB); PG8_STAGE(PG8_SB(1, 1), b3 + hstep, voffB); PG8_STAGE(PG8_SA(1, 0), a3, voffA);
;             PG8_WAIT_V(8); PG8_WAIT_L(0); PG8_BAR; PG8_MMA(1, 0, At, B0); PG8_MMA(1, 1, At, B1); PG8_BAR; PG8_SCHED;
	s_add_i32 s8, s29, s74
	v_lshl_add_u64 v[192:193], v[192:193], 0, s[22:23]
	s_mov_b32 m0, s8
	ds_read_b128 v[202:205], v194 offset:49152
	ds_read_b128 v[206:209], v194 offset:50176
	ds_read_b128 v[210:213], v194 offset:51200
	ds_read_b128 v[214:217], v194 offset:52224
	ds_read_b128 v[218:221], v194 offset:53248
	ds_read_b128 v[222:225], v194 offset:54272
	ds_read_b128 v[230:233], v194 offset:55296
	ds_read_b128 v[234:237], v194 offset:56320
	global_load_lds_dwordx4 v[192:193], off
	s_add_i32 m0, s8, 0x2000
	s_add_u32 s6, s6, 0x40080
	v_lshl_add_u64 v[192:193], v[238:239], 0, s[22:23]
	s_addc_u32 s7, s7, 0
	s_add_i32 s8, s38, s74
	global_load_lds_dwordx4 v[192:193], off
	v_lshl_add_u64 v[192:193], s[6:7], 0, v[158:159]
	s_mov_b32 m0, s8
	s_nop 0
	global_load_lds_dwordx4 v[192:193], off
	v_lshl_add_u64 v[192:193], s[6:7], 0, v[162:163]
	s_add_i32 m0, s8, 0x2000
	s_nop 0
	global_load_lds_dwordx4 v[192:193], off
	v_lshl_add_u64 v[192:193], v[240:241], 0, s[22:23]
	s_mov_b32 m0, s95
	s_nop 0
	global_load_lds_dwordx4 v[192:193], off
	v_lshl_add_u64 v[192:193], v[242:243], 0, s[22:23]
	s_mov_b32 m0, s96
	s_nop 0
	global_load_lds_dwordx4 v[192:193], off
	s_waitcnt vmcnt(8)
	s_waitcnt lgkmcnt(0)
	s_barrier
	s_setprio 1
	s_waitcnt lgkmcnt(0)
	v_mfma_f32_16x16x32_bf16 v[60:63], v[128:131], v[202:205], v[60:63]
	v_mfma_f32_16x16x32_bf16 v[56:59], v[136:139], v[202:205], v[56:59]
	v_mfma_f32_16x16x32_bf16 v[44:47], v[128:131], v[210:213], v[44:47]
	v_mfma_f32_16x16x32_bf16 v[40:43], v[136:139], v[210:213], v[40:43]
	v_mfma_f32_16x16x32_bf16 v[28:31], v[128:131], v[218:221], v[28:31]
	v_mfma_f32_16x16x32_bf16 v[24:27], v[136:139], v[218:221], v[24:27]
	v_mfma_f32_16x16x32_bf16 v[12:15], v[128:131], v[230:233], v[12:15]
	v_mfma_f32_16x16x32_bf16 v[8:11], v[136:139], v[230:233], v[8:11]
	v_mfma_f32_16x16x32_bf16 v[60:63], v[132:135], v[206:209], v[60:63]
	v_mfma_f32_16x16x32_bf16 v[56:59], v[140:143], v[206:209], v[56:59]
	v_mfma_f32_16x16x32_bf16 v[44:47], v[132:135], v[214:217], v[44:47]
	v_mfma_f32_16x16x32_bf16 v[40:43], v[140:143], v[214:217], v[40:43]
	v_mfma_f32_16x16x32_bf16 v[28:31], v[132:135], v[222:225], v[28:31]
	v_mfma_f32_16x16x32_bf16 v[24:27], v[140:143], v[222:225], v[24:27]
	v_mfma_f32_16x16x32_bf16 v[12:15], v[132:135], v[234:237], v[12:15]
	v_mfma_f32_16x16x32_bf16 v[8:11], v[140:143], v[234:237], v[8:11]
	s_setprio 0
	s_setprio 1
	v_mfma_f32_16x16x32_bf16 v[52:55], v[144:147], v[202:205], v[52:55]
	v_mfma_f32_16x16x32_bf16 v[48:51], v[184:187], v[202:205], v[48:51]
	v_mfma_f32_16x16x32_bf16 v[36:39], v[144:147], v[210:213], v[36:39]
	v_mfma_f32_16x16x32_bf16 v[32:35], v[184:187], v[210:213], v[32:35]
	v_mfma_f32_16x16x32_bf16 v[20:23], v[144:147], v[218:221], v[20:23]
	v_mfma_f32_16x16x32_bf16 v[16:19], v[184:187], v[218:221], v[16:19]
	v_mfma_f32_16x16x32_bf16 v[4:7], v[144:147], v[230:233], v[4:7]
	v_mfma_f32_16x16x32_bf16 v[0:3], v[184:187], v[230:233], v[0:3]
	v_mfma_f32_16x16x32_bf16 v[52:55], v[148:151], v[206:209], v[52:55]
	v_mfma_f32_16x16x32_bf16 v[48:51], v[188:191], v[206:209], v[48:51]
	v_mfma_f32_16x16x32_bf16 v[36:39], v[148:151], v[214:217], v[36:39]
	v_mfma_f32_16x16x32_bf16 v[32:35], v[188:191], v[214:217], v[32:35]
	v_mfma_f32_16x16x32_bf16 v[20:23], v[148:151], v[222:225], v[20:23]
	v_mfma_f32_16x16x32_bf16 v[16:19], v[188:191], v[222:225], v[16:19]
	v_mfma_f32_16x16x32_bf16 v[4:7], v[148:151], v[234:237], v[4:7]
	v_mfma_f32_16x16x32_bf16 v[0:3], v[188:191], v[234:237], v[0:3]
	s_setprio 0
	s_barrier
	s_mov_b32 s99, 0
	s_add_i32 s27, s27, 2
	s_add_u32 s4, s4, 0x100
	s_addc_u32 s5, s5, 0
	s_add_u32 s24, s24, 0x100
	s_addc_u32 s25, s25, 0
	s_cmp_gt_u32 s27, 13
	s_cbranch_scc0 .LBB0_121
	s_and_b64 vcc, exec, s[70:71]
	s_cbranch_vccz .LBB0_124
	s_barrier

; #define PG8_STAGE(bufoff, gbase, voff) do { _Pragma("unroll") for (int _i = 0; _i < 2; ++_i) \
;         __builtin_amdgcn_global_load_lds((const unsigned*)((const char*)(gbase) + (voff)[_i]), (PG8_LAS unsigned*)(lds + (bufoff) + ldsw + _i * 8192), 16, 0, 0); } while (0)
; #define PG8_WAIT_V(n) asm volatile("s_waitcnt vmcnt(" #n ")" ::: "memory")
; #define PG8_BAR __builtin_amdgcn_s_barrier()
; template <class Epi, class Sched, bool ALIGN_EPI = false, bool SP2 = false>
; __device__ __forceinline__ void gemm_phase(PG8_LAS unsigned char* lds, const Gemm g, const Sched& S, const Epi& E) {
;     ...
;     const int tid = tid_, wid = __builtin_amdgcn_readfirstlane(tid >> 6), lane = tid & 63, wr = wid >> 2, wc = wid & 3, fr = lane & 15, fq = lane >> 4;
;     const int K = g.K, nt = K / BK;
;     unsigned voffA[2], voffB[2];
; #pragma unroll
;     for (int i = 0; i < 2; ++i) { int R, C; stage_rc(tid * 16 + i * 8192, R, C); const int Rb = Epi::PERM ? ((R & ~31) + perm32(R & 31)) : R;
;         voffA[i] = (unsigned)(R * K + C) * 2u; voffB[i] = (unsigned)(Rb * K + C) * 2u; }
;     const size_t kstep = (size_t)(BK * 2);
;     const size_t hstep = (size_t)HALF * K * 2;
;     const size_t tstep = 2 * hstep;
;     const unsigned ldsw = (unsigned)wid * 1024u;
;     const int aoff = lds_byte(wr * 64 + fr, fq * 8), boff = lds_byte(wc * 32 + fr, fq * 8);
;     ...
;         PG8_STAGE(PG8_SB(0, 0), cB, voffB); PG8_STAGE(PG8_SB(0, 1), cB + hstep, voffB); PG8_STAGE(PG8_SA(0, 0), cA, voffA); PG8_STAGE(PG8_SA(0, 1), cA + hstep, voffA);
;         if (wr == 1) PG8_BAR;
;         PG8_WAIT_V(2); PG8_BAR;
;         PG8_STAGE(PG8_SB(1, 0), cB + kstep, voffB); PG8_STAGE(PG8_SA(1, 0), cA + kstep, voffA); PG8_STAGE(PG8_SB(1, 1), cB + hstep + kstep, voffB);
;         PG8_WAIT_V(6); PG8_BAR;
.LBB0_1278:
	s_add_u32 s10, s86, 0x3d200000
	s_addc_u32 s11, s87, 0
	s_lshl_b32 s12, s12, 5
	s_and_b32 s18, s12, 0x60
	s_mov_b64 s[12:13], 0x80
	s_add_i32 m0, s35, 0x18000
	v_lshl_add_u64 v[6:7], v[6:7], 0, s[12:13]
	s_lshl_b32 s15, s14, 13
	s_lshl_b32 s19, s18, 7
	s_waitcnt vmcnt(2)
	s_barrier
	global_load_lds_dwordx4 v[6:7], off
	v_lshl_add_u64 v[4:5], v[4:5], 0, s[12:13]
	s_add_i32 m0, s35, 0x1a000
	s_add_i32 s64, s35, 0x8000
	s_add_i32 s65, s35, 0xa000
	global_load_lds_dwordx4 v[4:5], off
	v_lshl_add_u64 v[0:1], v[0:1], 0, s[12:13]
	s_mov_b32 m0, s64
	s_add_u32 s16, s38, 0x20080
	global_load_lds_dwordx4 v[0:1], off
	v_lshl_add_u64 v[0:1], v[2:3], 0, s[12:13]
	s_mov_b32 m0, s65
	s_addc_u32 s17, s39, 0
	global_load_lds_dwordx4 v[0:1], off
	s_add_i32 m0, s35, 0x1c000
	v_lshl_add_u64 v[0:1], s[16:17], 0, v[132:133]
	global_load_lds_dwordx4 v[0:1], off
	v_lshl_add_u64 v[0:1], s[16:17], 0, v[128:129]
	s_add_i32 m0, s35, 0x1e000
	s_cmpk_lt_u32 s1, 0x100
	global_load_lds_dwordx4 v[0:1], off
	v_lshrrev_b32_e32 v1, 1, v9
	v_and_b32_e32 v1, 24, v1
	v_and_b32_e32 v0, 15, v9
	v_lshlrev_b32_e32 v2, 1, v1
	v_lshl_or_b32 v150, s14, 6, v0
	v_lshl_or_b32 v0, v0, 6, v2
	v_lshlrev_b32_e32 v2, 2, v9
	v_and_b32_e32 v2, 32, v2
	v_bitop3_b32 v3, v0, s15, v2 bitop3:0xde
	v_bitop3_b32 v151, v0, s19, v2 bitop3:0xde
	v_lshlrev_b32_e32 v0, 13, v13
	v_and_b32_e32 v0, 0xffffc000, v0
	v_or_b32_e32 v152, s18, v1
	v_lshl_add_u32 v0, v12, 10, v0
	v_and_b32_e32 v1, 1, v13
	v_lshl_or_b32 v0, v1, 6, v0
	v_lshl_add_u32 v136, v14, 1, v0
	v_lshlrev_b32_e32 v0, 13, v8
	v_and_b32_e32 v0, 0xffffc000, v0
	s_waitcnt vmcnt(6)
	v_lshl_add_u32 v0, v10, 10, v0
	v_and_b32_e32 v1, 1, v8
	s_cselect_b64 s[14:15], -1, 0
	v_lshl_or_b32 v0, v1, 6, v0
	s_add_i32 s67, 0, 0x10000
	s_add_i32 s68, 0, 0x14000
	s_sext_i32_i8 s69, s0
	s_ashr_i32 s66, s3, 31
	v_mov_b32_e32 v137, v133
	v_lshl_add_u32 v138, v11, 1, v0
	v_mov_b32_e32 v139, v133
	v_mov_b64_e32 v[140:141], 0x410
	v_mov_b64_e32 v[142:143], 0x40f
	v_add_u32_e32 v153, s67, v151
	v_add_u32_e32 v154, s68, v151
	v_add_u32_e32 v155, 0, v3
	s_mov_b64 s[16:17], 0x40000
	s_mov_b64 s[18:19], 0x48000
	s_mov_b64 s[20:21], 0x50000
	s_mov_b64 s[22:23], 0x58000
	s_barrier
	s_mov_b32 s99, 0
	s_branch .LBB0_1281

; #define PG8_BAR __builtin_amdgcn_s_barrier()
; template <class Epi, class Sched, bool ALIGN_EPI = false, bool SP2 = false>
; __device__ __forceinline__ void gemm_phase(PG8_LAS unsigned char* lds, const Gemm g, const Sched& S, const Epi& E) {
;     ...
;         if (!has_next) break;
; #pragma unroll
;         for (int a = 0; a < 2; ++a)
; #pragma unroll
;             for (int b = 0; b < 2; ++b)
; #pragma unroll
;                 for (int m = 0; m < 4; ++m)
; #pragma unroll
;                     for (int n = 0; n < 2; ++n) acc[a][b][m][n] = (f32x4){0.f, 0.f, 0.f, 0.f};
;         cur = nxt; cA = nA; cB = nB; ++ui;
;         if constexpr (ALIGN_EPI) { if (wr == 1) PG8_BAR; }
.LBB0_1280:
	s_mov_b32 s99, 1
	s_andn2_b64 vcc, exec, s[0:1]
	s_mov_b32 s69, s24
	s_mov_b32 s34, s26
	s_mov_b64 s[38:39], s[30:31]
	s_mov_b64 s[36:37], s[28:29]
	s_cbranch_vccz .LBB0_1290

; #define PG8_STAGE(bufoff, gbase, voff) do { _Pragma("unroll") for (int _i = 0; _i < 2; ++_i) \
;         __builtin_amdgcn_global_load_lds((const unsigned*)((const char*)(gbase) + (voff)[_i]), (PG8_LAS unsigned*)(lds + (bufoff) + ldsw + _i * 8192), 16, 0, 0); } while (0)
; #define PG8_LDA(dst, b, h) do { _Pragma("unroll") for (int m = 0; m < 4; ++m) _Pragma("unroll") for (int k = 0; k < 2; ++k) dst[m][k] = *(const PG8_LAS bf16x8*)(lds + PG8_SA(b, h) + aoff + m * 2048 + k * 1024); } while (0)
; #define PG8_LDB(dst, b, h) do { _Pragma("unroll") for (int n = 0; n < 2; ++n) _Pragma("unroll") for (int k = 0; k < 2; ++k) dst[n][k] = *(const PG8_LAS bf16x8*)(lds + PG8_SB(b, h) + boff + n * 2048 + k * 1024); } while (0)
; #define PG8_MMA(ai, bj, At, Bt) do { __builtin_amdgcn_s_setprio(1); _Pragma("unroll") for (int m = 0; m < 4; ++m) _Pragma("unroll") for (int n = 0; n < 2; ++n) _Pragma("unroll") for (int k = 0; k < 2; ++k) \
;         acc[ai][bj][m][n] = __builtin_amdgcn_mfma_f32_16x16x32_bf16(Bt[n][k], At[m][k], acc[ai][bj][m][n], 0, 0, 0); __builtin_amdgcn_s_setprio(0); } while (0)
; #define PG8_WAIT_V(n) asm volatile("s_waitcnt vmcnt(" #n ")" ::: "memory")
; #define PG8_WAIT_L(n) asm volatile("s_waitcnt lgkmcnt(" #n ")" ::: "memory")
; #define PG8_BAR __builtin_amdgcn_s_barrier()
; template <class Epi, class Sched, bool ALIGN_EPI = false, bool SP2 = false>
; __device__ __forceinline__ void gemm_phase(PG8_LAS unsigned char* lds, const Gemm g, const Sched& S, const Epi& E) {
;     ...
;         const bool has_next = S.next(ui + 1, nxt);
;         const char* nA = has_next ? (const char*)g.A + (size_t)nxt.pm * tstep : cA; const char* nB = has_next ? (const char*)g.Bt + (size_t)nxt.pn * tstep : cB;
;         for (int t = 0; t < nt; t += 2) {
;             const bool last = (t == nt - 2);
;             const char* a1 = cA + (size_t)(t + 1) * kstep;
;             const char* a2 = last ? nA : cA + (size_t)(t + 2) * kstep; const char* b2 = last ? nB : cB + (size_t)(t + 2) * kstep;
;             const char* a3 = a2 + kstep; const char* b3 = b2 + kstep;
;             if (last && has_next) S.a_ready(nxt);
;             if constexpr (SP2) {
;             PG8_LDB(B0, 0, 0); PG8_LDB(B1, 0, 1); PG8_SCHED; PG8_LDA(At, 0, 0); PG8_STAGE(PG8_SA(1, 1), a1 + hstep, voffA);
;             PG8_WAIT_V(8); PG8_WAIT_L(0); PG8_BAR; PG8_MMA(0, 0, At, B0); PG8_MMA(0, 1, At, B1); PG8_BAR; PG8_SCHED;
.LBB0_1284:
	ds_read_b128 v[144:147], v153
	ds_read_b128 v[156:159], v153 offset:1024
	ds_read_b128 v[160:163], v153 offset:2048
	ds_read_b128 v[164:167], v153 offset:3072
	ds_read_b128 v[168:171], v154
	ds_read_b128 v[172:175], v154 offset:1024
	ds_read_b128 v[176:179], v154 offset:2048
	ds_read_b128 v[180:183], v154 offset:3072
	s_add_u32 s38, s36, 0xfffe0080
	s_addc_u32 s39, s37, -1
	s_cmp_eq_u32 s74, 4
	s_cselect_b32 s41, s27, s39
	s_cselect_b32 s40, s70, s38
	s_cselect_b32 s39, s25, s73
	s_cselect_b32 s38, s71, s72
	v_lshl_add_u64 v[148:149], s[36:37], 0, v[136:137]
	s_add_i32 m0, s35, 0xc000
	ds_read_b128 v[184:187], v155
	ds_read_b128 v[188:191], v155 offset:1024
	ds_read_b128 v[192:195], v155 offset:2048
	ds_read_b128 v[196:199], v155 offset:3072
	ds_read_b128 v[200:203], v155 offset:4096
	ds_read_b128 v[204:207], v155 offset:5120
	ds_read_b128 v[208:211], v155 offset:6144
	ds_read_b128 v[212:215], v155 offset:7168
	global_load_lds_dwordx4 v[148:149], off
	v_lshl_add_u64 v[148:149], s[36:37], 0, v[138:139]
	s_add_i32 m0, s35, 0xe000
	s_nop 0
	global_load_lds_dwordx4 v[148:149], off
	s_cmp_eq_u32 s99, 1
	s_cbranch_scc1 .Lrw_P3a_0
	s_waitcnt vmcnt(8)
	s_branch .Lrj_P3a_0

; #define PG8_STAGE(bufoff, gbase, voff) do { _Pragma("unroll") for (int _i = 0; _i < 2; ++_i) \
;         __builtin_amdgcn_global_load_lds((const unsigned*)((const char*)(gbase) + (voff)[_i]), (PG8_LAS unsigned*)(lds + (bufoff) + ldsw + _i * 8192), 16, 0, 0); } while (0)
; #define PG8_LDA(dst, b, h) do { _Pragma("unroll") for (int m = 0; m < 4; ++m) _Pragma("unroll") for (int k = 0; k < 2; ++k) dst[m][k] = *(const PG8_LAS bf16x8*)(lds + PG8_SA(b, h) + aoff + m * 2048 + k * 1024); } while (0)
; #define PG8_MMA(ai, bj, At, Bt) do { __builtin_amdgcn_s_setprio(1); _Pragma("unroll") for (int m = 0; m < 4; ++m) _Pragma("unroll") for (int n = 0; n < 2; ++n) _Pragma("unroll") for (int k = 0; k < 2; ++k) \
;         acc[ai][bj][m][n] = __builtin_amdgcn_mfma_f32_16x16x32_bf16(Bt[n][k], At[m][k], acc[ai][bj][m][n], 0, 0, 0); __builtin_amdgcn_s_setprio(0); } while (0)
; #define PG8_WAIT_V(n) asm volatile("s_waitcnt vmcnt(" #n ")" ::: "memory")
; #define PG8_WAIT_L(n) asm volatile("s_waitcnt lgkmcnt(" #n ")" ::: "memory")
; #define PG8_BAR __builtin_amdgcn_s_barrier()
; #define PG8_SCHED __builtin_amdgcn_sched_barrier(0)
; template <class Epi, class Sched, bool ALIGN_EPI = false, bool SP2 = false>
; __device__ __forceinline__ void gemm_phase(PG8_LAS unsigned char* lds, const Gemm g, const Sched& S, const Epi& E) {
;     ...
;             PG8_WAIT_V(8); PG8_WAIT_L(0); PG8_BAR; PG8_MMA(0, 0, At, B0); PG8_MMA(0, 1, At, B1); PG8_BAR; PG8_SCHED;
;             PG8_LDA(At, 0, 1); PG8_STAGE(PG8_SB(0, 0), b2, voffB); PG8_STAGE(PG8_SB(0, 1), b2 + hstep, voffB); PG8_STAGE(PG8_SA(0, 0), a2, voffA);
;             PG8_WAIT_V(8); PG8_WAIT_L(0); PG8_BAR; PG8_MMA(1, 0, At, B0); PG8_MMA(1, 1, At, B1); PG8_BAR; PG8_SCHED;
.Lrj_P3a_0:
	s_waitcnt lgkmcnt(0)
	s_barrier
	s_setprio 1
	s_waitcnt lgkmcnt(0)
	v_mfma_f32_16x16x32_bf16 v[124:127], v[144:147], v[184:187], v[124:127]
	v_mfma_f32_16x16x32_bf16 v[120:123], v[160:163], v[184:187], v[120:123]
	v_mfma_f32_16x16x32_bf16 v[112:115], v[144:147], v[192:195], v[112:115]
	v_mfma_f32_16x16x32_bf16 v[104:107], v[160:163], v[192:195], v[104:107]
	v_mfma_f32_16x16x32_bf16 v[96:99], v[144:147], v[200:203], v[96:99]
	v_mfma_f32_16x16x32_bf16 v[88:91], v[160:163], v[200:203], v[88:91]
	v_mfma_f32_16x16x32_bf16 v[80:83], v[144:147], v[208:211], v[80:83]
	v_mfma_f32_16x16x32_bf16 v[72:75], v[160:163], v[208:211], v[72:75]
	v_mfma_f32_16x16x32_bf16 v[124:127], v[156:159], v[188:191], v[124:127]
	v_mfma_f32_16x16x32_bf16 v[120:123], v[164:167], v[188:191], v[120:123]
	v_mfma_f32_16x16x32_bf16 v[112:115], v[156:159], v[196:199], v[112:115]
	v_mfma_f32_16x16x32_bf16 v[104:107], v[164:167], v[196:199], v[104:107]
	v_mfma_f32_16x16x32_bf16 v[96:99], v[156:159], v[204:207], v[96:99]
	v_mfma_f32_16x16x32_bf16 v[88:91], v[164:167], v[204:207], v[88:91]
	v_mfma_f32_16x16x32_bf16 v[80:83], v[156:159], v[212:215], v[80:83]
	v_mfma_f32_16x16x32_bf16 v[72:75], v[164:167], v[212:215], v[72:75]
	s_setprio 0
	s_setprio 1
	v_mfma_f32_16x16x32_bf16 v[116:119], v[168:171], v[184:187], v[116:119]
	v_mfma_f32_16x16x32_bf16 v[108:111], v[176:179], v[184:187], v[108:111]
	v_mfma_f32_16x16x32_bf16 v[100:103], v[168:171], v[192:195], v[100:103]
	v_mfma_f32_16x16x32_bf16 v[92:95], v[176:179], v[192:195], v[92:95]
	v_mfma_f32_16x16x32_bf16 v[84:87], v[168:171], v[200:203], v[84:87]
	v_mfma_f32_16x16x32_bf16 v[76:79], v[176:179], v[200:203], v[76:79]
	v_mfma_f32_16x16x32_bf16 v[68:71], v[168:171], v[208:211], v[68:71]
	v_mfma_f32_16x16x32_bf16 v[64:67], v[176:179], v[208:211], v[64:67]
	v_mfma_f32_16x16x32_bf16 v[116:119], v[172:175], v[188:191], v[116:119]
	v_mfma_f32_16x16x32_bf16 v[108:111], v[180:183], v[188:191], v[108:111]
	v_mfma_f32_16x16x32_bf16 v[100:103], v[172:175], v[196:199], v[100:103]
	v_mfma_f32_16x16x32_bf16 v[92:95], v[180:183], v[196:199], v[92:95]
	v_mfma_f32_16x16x32_bf16 v[84:87], v[172:175], v[204:207], v[84:87]
	v_mfma_f32_16x16x32_bf16 v[76:79], v[180:183], v[204:207], v[76:79]
	v_mfma_f32_16x16x32_bf16 v[68:71], v[172:175], v[212:215], v[68:71]
	v_mfma_f32_16x16x32_bf16 v[64:67], v[180:183], v[212:215], v[64:67]
	s_setprio 0
	s_barrier
	s_add_i32 s75, s67, s43
	v_lshl_add_u64 v[148:149], s[38:39], 0, v[132:133]
	s_mov_b32 m0, s75
	ds_read_b128 v[184:187], v155 offset:16384
	ds_read_b128 v[188:191], v155 offset:17408
	ds_read_b128 v[192:195], v155 offset:18432
	ds_read_b128 v[196:199], v155 offset:19456
	ds_read_b128 v[200:203], v155 offset:20480
	ds_read_b128 v[204:207], v155 offset:21504
	ds_read_b128 v[208:211], v155 offset:22528
	ds_read_b128 v[212:215], v155 offset:23552
	global_load_lds_dwordx4 v[148:149], off
	s_add_i32 m0, s75, 0x2000
	s_add_u32 s76, s38, 0x20000
	v_lshl_add_u64 v[216:217], s[38:39], 0, v[128:129]
	s_addc_u32 s77, s39, 0
	s_add_i32 s75, s68, s43
	global_load_lds_dwordx4 v[216:217], off
	v_lshl_add_u64 v[218:219], s[76:77], 0, v[132:133]
	s_mov_b32 m0, s75
	v_lshl_add_u64 v[220:221], s[40:41], 0, v[130:131]
	global_load_lds_dwordx4 v[218:219], off
	v_lshl_add_u64 v[218:219], s[76:77], 0, v[128:129]
	s_add_i32 m0, s75, 0x2000
	s_nop 0
	global_load_lds_dwordx4 v[218:219], off
	v_lshl_add_u64 v[218:219], s[40:41], 0, v[134:135]
	s_mov_b32 m0, s35
	s_nop 0
	global_load_lds_dwordx4 v[218:219], off
	s_mov_b32 m0, s52
	s_nop 0
	global_load_lds_dwordx4 v[220:221], off
	s_cmp_eq_u32 s99, 1
	s_cbranch_scc1 .Lrw_P3a_1
	s_waitcnt vmcnt(8)
	s_branch .Lrj_P3a_1

; #define PG8_STAGE(bufoff, gbase, voff) do { _Pragma("unroll") for (int _i = 0; _i < 2; ++_i) \
;         __builtin_amdgcn_global_load_lds((const unsigned*)((const char*)(gbase) + (voff)[_i]), (PG8_LAS unsigned*)(lds + (bufoff) + ldsw + _i * 8192), 16, 0, 0); } while (0)
; #define PG8_LDA(dst, b, h) do { _Pragma("unroll") for (int m = 0; m < 4; ++m) _Pragma("unroll") for (int k = 0; k < 2; ++k) dst[m][k] = *(const PG8_LAS bf16x8*)(lds + PG8_SA(b, h) + aoff + m * 2048 + k * 1024); } while (0)
; #define PG8_LDB(dst, b, h) do { _Pragma("unroll") for (int n = 0; n < 2; ++n) _Pragma("unroll") for (int k = 0; k < 2; ++k) dst[n][k] = *(const PG8_LAS bf16x8*)(lds + PG8_SB(b, h) + boff + n * 2048 + k * 1024); } while (0)
; #define PG8_MMA(ai, bj, At, Bt) do { __builtin_amdgcn_s_setprio(1); _Pragma("unroll") for (int m = 0; m < 4; ++m) _Pragma("unroll") for (int n = 0; n < 2; ++n) _Pragma("unroll") for (int k = 0; k < 2; ++k) \
;         acc[ai][bj][m][n] = __builtin_amdgcn_mfma_f32_16x16x32_bf16(Bt[n][k], At[m][k], acc[ai][bj][m][n], 0, 0, 0); __builtin_amdgcn_s_setprio(0); } while (0)
; #define PG8_WAIT_V(n) asm volatile("s_waitcnt vmcnt(" #n ")" ::: "memory")
; #define PG8_WAIT_L(n) asm volatile("s_waitcnt lgkmcnt(" #n ")" ::: "memory")
; #define PG8_BAR __builtin_amdgcn_s_barrier()
; #define PG8_SCHED __builtin_amdgcn_sched_barrier(0)
; template <class Epi, class Sched, bool ALIGN_EPI = false, bool SP2 = false>
; __device__ __forceinline__ void gemm_phase(PG8_LAS unsigned char* lds, const Gemm g, const Sched& S, const Epi& E) {
;     ...
;             PG8_WAIT_V(8); PG8_WAIT_L(0); PG8_BAR; PG8_MMA(1, 0, At, B0); PG8_MMA(1, 1, At, B1); PG8_BAR; PG8_SCHED;
;             PG8_LDB(B0, 1, 0); PG8_LDB(B1, 1, 1); PG8_SCHED; PG8_LDA(At, 1, 0); PG8_STAGE(PG8_SA(0, 1), a2 + hstep, voffA);
;             PG8_WAIT_V(8); PG8_WAIT_L(0); PG8_BAR; PG8_MMA(0, 0, At, B0); PG8_MMA(0, 1, At, B1); PG8_BAR; PG8_SCHED;
.Lrj_P3a_1:
	s_waitcnt lgkmcnt(0)
	s_barrier
	s_setprio 1
	s_waitcnt lgkmcnt(0)
	v_mfma_f32_16x16x32_bf16 v[60:63], v[144:147], v[184:187], v[60:63]
	v_mfma_f32_16x16x32_bf16 v[56:59], v[160:163], v[184:187], v[56:59]
	v_mfma_f32_16x16x32_bf16 v[48:51], v[144:147], v[192:195], v[48:51]
	v_mfma_f32_16x16x32_bf16 v[40:43], v[160:163], v[192:195], v[40:43]
	v_mfma_f32_16x16x32_bf16 v[32:35], v[144:147], v[200:203], v[32:35]
	v_mfma_f32_16x16x32_bf16 v[24:27], v[160:163], v[200:203], v[24:27]
	v_mfma_f32_16x16x32_bf16 v[16:19], v[144:147], v[208:211], v[16:19]
	v_mfma_f32_16x16x32_bf16 v[8:11], v[160:163], v[208:211], v[8:11]
	v_mfma_f32_16x16x32_bf16 v[60:63], v[156:159], v[188:191], v[60:63]
	v_mfma_f32_16x16x32_bf16 v[56:59], v[164:167], v[188:191], v[56:59]
	v_mfma_f32_16x16x32_bf16 v[48:51], v[156:159], v[196:199], v[48:51]
	v_mfma_f32_16x16x32_bf16 v[40:43], v[164:167], v[196:199], v[40:43]
	v_mfma_f32_16x16x32_bf16 v[32:35], v[156:159], v[204:207], v[32:35]
	v_mfma_f32_16x16x32_bf16 v[24:27], v[164:167], v[204:207], v[24:27]
	v_mfma_f32_16x16x32_bf16 v[16:19], v[156:159], v[212:215], v[16:19]
	v_mfma_f32_16x16x32_bf16 v[8:11], v[164:167], v[212:215], v[8:11]
	s_setprio 0
	s_setprio 1
	v_mfma_f32_16x16x32_bf16 v[52:55], v[168:171], v[184:187], v[52:55]
	v_mfma_f32_16x16x32_bf16 v[44:47], v[176:179], v[184:187], v[44:47]
	v_mfma_f32_16x16x32_bf16 v[36:39], v[168:171], v[192:195], v[36:39]
	v_mfma_f32_16x16x32_bf16 v[28:31], v[176:179], v[192:195], v[28:31]
	v_mfma_f32_16x16x32_bf16 v[20:23], v[168:171], v[200:203], v[20:23]
	v_mfma_f32_16x16x32_bf16 v[12:15], v[176:179], v[200:203], v[12:15]
	v_mfma_f32_16x16x32_bf16 v[4:7], v[168:171], v[208:211], v[4:7]
	v_mfma_f32_16x16x32_bf16 v[0:3], v[176:179], v[208:211], v[0:3]
	v_mfma_f32_16x16x32_bf16 v[52:55], v[172:175], v[188:191], v[52:55]
	v_mfma_f32_16x16x32_bf16 v[44:47], v[180:183], v[188:191], v[44:47]
	v_mfma_f32_16x16x32_bf16 v[36:39], v[172:175], v[196:199], v[36:39]
	v_mfma_f32_16x16x32_bf16 v[28:31], v[180:183], v[196:199], v[28:31]
	v_mfma_f32_16x16x32_bf16 v[20:23], v[172:175], v[204:207], v[20:23]
	v_mfma_f32_16x16x32_bf16 v[12:15], v[180:183], v[204:207], v[12:15]
	v_mfma_f32_16x16x32_bf16 v[4:7], v[172:175], v[212:215], v[4:7]
	v_mfma_f32_16x16x32_bf16 v[0:3], v[180:183], v[212:215], v[0:3]
	s_setprio 0
	s_barrier
	s_add_i32 s75, 0, 0x18000
	s_add_i32 s76, 0, 0x1c000
	v_add_u32_e32 v164, s75, v151
	v_add_u32_e32 v180, s76, v151
	ds_read_b128 v[144:147], v164
	ds_read_b128 v[156:159], v164 offset:1024
	ds_read_b128 v[160:163], v164 offset:2048
	ds_read_b128 v[164:167], v164 offset:3072
	ds_read_b128 v[168:171], v180
	ds_read_b128 v[172:175], v180 offset:1024
	ds_read_b128 v[176:179], v180 offset:2048
	ds_read_b128 v[180:183], v180 offset:3072
	s_add_u32 s40, s40, 0x20000
	s_addc_u32 s41, s41, 0
	s_mov_b32 m0, s53
	v_lshl_add_u64 v[222:223], s[40:41], 0, v[134:135]
	ds_read_b128 v[184:187], v155 offset:32768
	ds_read_b128 v[188:191], v155 offset:33792
	ds_read_b128 v[192:195], v155 offset:34816
	ds_read_b128 v[196:199], v155 offset:35840
	ds_read_b128 v[200:203], v155 offset:36864
	ds_read_b128 v[204:207], v155 offset:37888
	ds_read_b128 v[208:211], v155 offset:38912
	ds_read_b128 v[212:215], v155 offset:39936
	global_load_lds_dwordx4 v[222:223], off
	v_lshl_add_u64 v[222:223], s[40:41], 0, v[130:131]
	s_mov_b32 m0, s60
	s_nop 0
	global_load_lds_dwordx4 v[222:223], off
	s_waitcnt vmcnt(8)
	s_waitcnt lgkmcnt(0)
	s_barrier
	s_setprio 1
	s_waitcnt lgkmcnt(0)
	v_mfma_f32_16x16x32_bf16 v[124:127], v[144:147], v[184:187], v[124:127]
	v_mfma_f32_16x16x32_bf16 v[120:123], v[160:163], v[184:187], v[120:123]
	v_mfma_f32_16x16x32_bf16 v[112:115], v[144:147], v[192:195], v[112:115]
	v_mfma_f32_16x16x32_bf16 v[104:107], v[160:163], v[192:195], v[104:107]
	v_mfma_f32_16x16x32_bf16 v[96:99], v[144:147], v[200:203], v[96:99]
	v_mfma_f32_16x16x32_bf16 v[88:91], v[160:163], v[200:203], v[88:91]
	v_mfma_f32_16x16x32_bf16 v[80:83], v[144:147], v[208:211], v[80:83]
	v_mfma_f32_16x16x32_bf16 v[72:75], v[160:163], v[208:211], v[72:75]
	v_mfma_f32_16x16x32_bf16 v[124:127], v[156:159], v[188:191], v[124:127]
	v_mfma_f32_16x16x32_bf16 v[120:123], v[164:167], v[188:191], v[120:123]
	v_mfma_f32_16x16x32_bf16 v[112:115], v[156:159], v[196:199], v[112:115]
	v_mfma_f32_16x16x32_bf16 v[104:107], v[164:167], v[196:199], v[104:107]
	v_mfma_f32_16x16x32_bf16 v[96:99], v[156:159], v[204:207], v[96:99]
	v_mfma_f32_16x16x32_bf16 v[88:91], v[164:167], v[204:207], v[88:91]
	v_mfma_f32_16x16x32_bf16 v[80:83], v[156:159], v[212:215], v[80:83]
	v_mfma_f32_16x16x32_bf16 v[72:75], v[164:167], v[212:215], v[72:75]
	s_setprio 0
	s_setprio 1
	v_mfma_f32_16x16x32_bf16 v[116:119], v[168:171], v[184:187], v[116:119]
	v_mfma_f32_16x16x32_bf16 v[108:111], v[176:179], v[184:187], v[108:111]
	v_mfma_f32_16x16x32_bf16 v[100:103], v[168:171], v[192:195], v[100:103]
	v_mfma_f32_16x16x32_bf16 v[92:95], v[176:179], v[192:195], v[92:95]
	v_mfma_f32_16x16x32_bf16 v[84:87], v[168:171], v[200:203], v[84:87]
	v_mfma_f32_16x16x32_bf16 v[76:79], v[176:179], v[200:203], v[76:79]
	v_mfma_f32_16x16x32_bf16 v[68:71], v[168:171], v[208:211], v[68:71]
	v_mfma_f32_16x16x32_bf16 v[64:67], v[176:179], v[208:211], v[64:67]
	v_mfma_f32_16x16x32_bf16 v[116:119], v[172:175], v[188:191], v[116:119]
	v_mfma_f32_16x16x32_bf16 v[108:111], v[180:183], v[188:191], v[108:111]
	v_mfma_f32_16x16x32_bf16 v[100:103], v[172:175], v[196:199], v[100:103]
	v_mfma_f32_16x16x32_bf16 v[92:95], v[180:183], v[196:199], v[92:95]
	v_mfma_f32_16x16x32_bf16 v[84:87], v[172:175], v[204:207], v[84:87]
	v_mfma_f32_16x16x32_bf16 v[76:79], v[180:183], v[204:207], v[76:79]
	v_mfma_f32_16x16x32_bf16 v[68:71], v[172:175], v[212:215], v[68:71]
	v_mfma_f32_16x16x32_bf16 v[64:67], v[180:183], v[212:215], v[64:67]
	s_setprio 0
	s_barrier
; #define PG8_STAGE(bufoff, gbase, voff) do { _Pragma("unroll") for (int _i = 0; _i < 2; ++_i) \
;         __builtin_amdgcn_global_load_lds((const unsigned*)((const char*)(gbase) + (voff)[_i]), (PG8_LAS unsigned*)(lds + (bufoff) + ldsw + _i * 8192), 16, 0, 0); } while (0)
; #define PG8_LDA(dst, b, h) do { _Pragma("unroll") for (int m = 0; m < 4; ++m) _Pragma("unroll") for (int k = 0; k < 2; ++k) dst[m][k] = *(const PG8_LAS bf16x8*)(lds + PG8_SA(b, h) + aoff + m * 2048 + k * 1024); } while (0)
; #define PG8_MMA(ai, bj, At, Bt) do { __builtin_amdgcn_s_setprio(1); _Pragma("unroll") for (int m = 0; m < 4; ++m) _Pragma("unroll") for (int n = 0; n < 2; ++n) _Pragma("unroll") for (int k = 0; k < 2; ++k) \
;         acc[ai][bj][m][n] = __builtin_amdgcn_mfma_f32_16x16x32_bf16(Bt[n][k], At[m][k], acc[ai][bj][m][n], 0, 0, 0); __builtin_amdgcn_s_setprio(0); } while (0)
; #define PG8_WAIT_V(n) asm volatile("s_waitcnt vmcnt(" #n ")" ::: "memory")
; #define PG8_WAIT_L(n) asm volatile("s_waitcnt lgkmcnt(" #n ")" ::: "memory")
; #define PG8_BAR __builtin_amdgcn_s_barrier()
; #define PG8_SCHED __builtin_amdgcn_sched_barrier(0)
; template <class Epi, class Sched, bool ALIGN_EPI = false, bool SP2 = false>
; __device__ __forceinline__ void gemm_phase(PG8_LAS unsigned char* lds, const Gemm g, const Sched& S, const Epi& E) {
;     ...
;             PG8_LDA(At, 1, 1); PG8_STAGE(PG8_SB(1, 0), b3, voffB); PG8_STAGE(PG8_SB(1, 1), b3 + hstep, voffB); PG8_STAGE(PG8_SA(1, 0), a3, voffA);
;             PG8_WAIT_V(8); PG8_WAIT_L(0); PG8_BAR; PG8_MMA(1, 0, At, B0); PG8_MMA(1, 1, At, B1); PG8_BAR; PG8_SCHED;
	s_add_i32 s40, s75, s43
	v_lshl_add_u64 v[148:149], v[148:149], 0, s[12:13]
	s_mov_b32 m0, s40
	ds_read_b128 v[184:187], v155 offset:49152
	ds_read_b128 v[188:191], v155 offset:50176
	ds_read_b128 v[192:195], v155 offset:51200
	ds_read_b128 v[196:199], v155 offset:52224
	ds_read_b128 v[200:203], v155 offset:53248
	ds_read_b128 v[204:207], v155 offset:54272
	ds_read_b128 v[208:211], v155 offset:55296
	ds_read_b128 v[212:215], v155 offset:56320
	global_load_lds_dwordx4 v[148:149], off
	s_add_i32 m0, s40, 0x2000
	s_add_u32 s38, s38, 0x20080
	v_lshl_add_u64 v[148:149], v[216:217], 0, s[12:13]
	s_addc_u32 s39, s39, 0
	s_add_i32 s40, s76, s43
	global_load_lds_dwordx4 v[148:149], off
	v_lshl_add_u64 v[148:149], s[38:39], 0, v[132:133]
	s_mov_b32 m0, s40
	s_nop 0
	global_load_lds_dwordx4 v[148:149], off
	v_lshl_add_u64 v[148:149], s[38:39], 0, v[128:129]
	s_add_i32 m0, s40, 0x2000
	s_nop 0
	global_load_lds_dwordx4 v[148:149], off
	v_lshl_add_u64 v[148:149], v[218:219], 0, s[12:13]
	s_mov_b32 m0, s64
	s_nop 0
	global_load_lds_dwordx4 v[148:149], off
	v_lshl_add_u64 v[148:149], v[220:221], 0, s[12:13]
	s_mov_b32 m0, s65
	s_nop 0
	global_load_lds_dwordx4 v[148:149], off
	s_waitcnt vmcnt(8)
	s_waitcnt lgkmcnt(0)
	s_barrier
	s_setprio 1
	s_waitcnt lgkmcnt(0)
	v_mfma_f32_16x16x32_bf16 v[60:63], v[144:147], v[184:187], v[60:63]
	v_mfma_f32_16x16x32_bf16 v[56:59], v[160:163], v[184:187], v[56:59]
	v_mfma_f32_16x16x32_bf16 v[48:51], v[144:147], v[192:195], v[48:51]
	v_mfma_f32_16x16x32_bf16 v[40:43], v[160:163], v[192:195], v[40:43]
	v_mfma_f32_16x16x32_bf16 v[32:35], v[144:147], v[200:203], v[32:35]
	v_mfma_f32_16x16x32_bf16 v[24:27], v[160:163], v[200:203], v[24:27]
	v_mfma_f32_16x16x32_bf16 v[16:19], v[144:147], v[208:211], v[16:19]
	v_mfma_f32_16x16x32_bf16 v[8:11], v[160:163], v[208:211], v[8:11]
	v_mfma_f32_16x16x32_bf16 v[60:63], v[156:159], v[188:191], v[60:63]
	v_mfma_f32_16x16x32_bf16 v[56:59], v[164:167], v[188:191], v[56:59]
	v_mfma_f32_16x16x32_bf16 v[48:51], v[156:159], v[196:199], v[48:51]
	v_mfma_f32_16x16x32_bf16 v[40:43], v[164:167], v[196:199], v[40:43]
	v_mfma_f32_16x16x32_bf16 v[32:35], v[156:159], v[204:207], v[32:35]
	v_mfma_f32_16x16x32_bf16 v[24:27], v[164:167], v[204:207], v[24:27]
	v_mfma_f32_16x16x32_bf16 v[16:19], v[156:159], v[212:215], v[16:19]
	v_mfma_f32_16x16x32_bf16 v[8:11], v[164:167], v[212:215], v[8:11]
	s_setprio 0
	s_setprio 1
	v_mfma_f32_16x16x32_bf16 v[52:55], v[168:171], v[184:187], v[52:55]
	v_mfma_f32_16x16x32_bf16 v[44:47], v[176:179], v[184:187], v[44:47]
	v_mfma_f32_16x16x32_bf16 v[36:39], v[168:171], v[192:195], v[36:39]
	v_mfma_f32_16x16x32_bf16 v[28:31], v[176:179], v[192:195], v[28:31]
	v_mfma_f32_16x16x32_bf16 v[20:23], v[168:171], v[200:203], v[20:23]
	v_mfma_f32_16x16x32_bf16 v[12:15], v[176:179], v[200:203], v[12:15]
	v_mfma_f32_16x16x32_bf16 v[4:7], v[168:171], v[208:211], v[4:7]
	v_mfma_f32_16x16x32_bf16 v[0:3], v[176:179], v[208:211], v[0:3]
	v_mfma_f32_16x16x32_bf16 v[52:55], v[172:175], v[188:191], v[52:55]
	v_mfma_f32_16x16x32_bf16 v[44:47], v[180:183], v[188:191], v[44:47]
	v_mfma_f32_16x16x32_bf16 v[36:39], v[172:175], v[196:199], v[36:39]
	v_mfma_f32_16x16x32_bf16 v[28:31], v[180:183], v[196:199], v[28:31]
	v_mfma_f32_16x16x32_bf16 v[20:23], v[172:175], v[204:207], v[20:23]
	v_mfma_f32_16x16x32_bf16 v[12:15], v[180:183], v[204:207], v[12:15]
	v_mfma_f32_16x16x32_bf16 v[4:7], v[172:175], v[212:215], v[4:7]
	v_mfma_f32_16x16x32_bf16 v[0:3], v[180:183], v[212:215], v[0:3]
	s_setprio 0
	s_barrier
	s_mov_b32 s99, 0
	s_add_i32 s74, s74, 2
	s_add_u32 s36, s36, 0x100
	s_addc_u32 s37, s37, 0
	s_add_u32 s72, s72, 0x100
	s_addc_u32 s73, s73, 0
	s_cmp_gt_u32 s74, 5
	s_cbranch_scc0 .LBB0_1284
	s_and_b64 vcc, exec, s[14:15]
	s_cbranch_vccz .LBB0_1287
	s_barrier

; #define PG8_STAGE(bufoff, gbase, voff) do { _Pragma("unroll") for (int _i = 0; _i < 2; ++_i) \
;         __builtin_amdgcn_global_load_lds((const unsigned*)((const char*)(gbase) + (voff)[_i]), (PG8_LAS unsigned*)(lds + (bufoff) + ldsw + _i * 8192), 16, 0, 0); } while (0)
; #define PG8_WAIT_V(n) asm volatile("s_waitcnt vmcnt(" #n ")" ::: "memory")
; #define PG8_BAR __builtin_amdgcn_s_barrier()
; template <class Epi, class Sched, bool ALIGN_EPI = false, bool SP2 = false>
; __device__ __forceinline__ void gemm_phase(PG8_LAS unsigned char* lds, const Gemm g, const Sched& S, const Epi& E) {
;     ...
;     const int tid = tid_, wid = __builtin_amdgcn_readfirstlane(tid >> 6), lane = tid & 63, wr = wid >> 2, wc = wid & 3, fr = lane & 15, fq = lane >> 4;
;     const int K = g.K, nt = K / BK;
;     unsigned voffA[2], voffB[2];
; #pragma unroll
;     for (int i = 0; i < 2; ++i) { int R, C; stage_rc(tid * 16 + i * 8192, R, C); const int Rb = Epi::PERM ? ((R & ~31) + perm32(R & 31)) : R;
;         voffA[i] = (unsigned)(R * K + C) * 2u; voffB[i] = (unsigned)(Rb * K + C) * 2u; }
;     const size_t kstep = (size_t)(BK * 2);
;     const size_t hstep = (size_t)HALF * K * 2;
;     const size_t tstep = 2 * hstep;
;     const unsigned ldsw = (unsigned)wid * 1024u;
;     const int aoff = lds_byte(wr * 64 + fr, fq * 8), boff = lds_byte(wc * 32 + fr, fq * 8);
;     ...
;         PG8_STAGE(PG8_SB(0, 0), cB, voffB); PG8_STAGE(PG8_SB(0, 1), cB + hstep, voffB); PG8_STAGE(PG8_SA(0, 0), cA, voffA); PG8_STAGE(PG8_SA(0, 1), cA + hstep, voffA);
;         if (wr == 1) PG8_BAR;
;         PG8_WAIT_V(2); PG8_BAR;
;         PG8_STAGE(PG8_SB(1, 0), cB + kstep, voffB); PG8_STAGE(PG8_SA(1, 0), cA + kstep, voffA); PG8_STAGE(PG8_SB(1, 1), cB + hstep + kstep, voffB);
;         PG8_WAIT_V(6); PG8_BAR;
.LBB0_1349:
	s_add_u32 s12, s86, 0x45400000
	s_addc_u32 s13, s87, 0
	s_lshl_b32 s14, s14, 5
	s_and_b32 s18, s14, 0x60
	s_mov_b64 s[14:15], 0x80
	s_add_i32 m0, s43, 0x18000
	v_lshl_add_u64 v[6:7], v[6:7], 0, s[14:15]
	s_lshl_b32 s17, s16, 13
	s_lshl_b32 s22, s18, 7
	s_waitcnt vmcnt(2)
	s_barrier
	global_load_lds_dwordx4 v[6:7], off
	v_lshl_add_u64 v[4:5], v[4:5], 0, s[14:15]
	s_add_i32 m0, s43, 0x1a000
	s_add_i32 s70, s43, 0x8000
	s_add_i32 s71, s43, 0xa000
	global_load_lds_dwordx4 v[4:5], off
	v_lshl_add_u64 v[0:1], v[0:1], 0, s[14:15]
	s_mov_b32 m0, s70
	s_add_u32 s20, s62, 0x10080
	global_load_lds_dwordx4 v[0:1], off
	v_lshl_add_u64 v[0:1], v[2:3], 0, s[14:15]
	s_mov_b32 m0, s71
	s_addc_u32 s21, s63, 0
	global_load_lds_dwordx4 v[0:1], off
	s_add_i32 m0, s43, 0x1c000
	v_lshl_add_u64 v[0:1], s[20:21], 0, v[132:133]
	global_load_lds_dwordx4 v[0:1], off
	v_lshl_add_u64 v[0:1], s[20:21], 0, v[128:129]
	s_add_i32 m0, s43, 0x1e000
	s_cmpk_lt_u32 s5, 0x100
	global_load_lds_dwordx4 v[0:1], off
	v_lshrrev_b32_e32 v1, 1, v8
	v_and_b32_e32 v1, 24, v1
	v_and_b32_e32 v0, 15, v8
	v_lshlrev_b32_e32 v2, 1, v1
	v_lshl_or_b32 v146, s16, 6, v0
	v_lshl_or_b32 v0, v0, 6, v2
	v_lshlrev_b32_e32 v2, 2, v8
	v_and_b32_e32 v2, 32, v2
	v_bitop3_b32 v3, v0, s17, v2 bitop3:0xde
	s_cselect_b64 s[16:17], -1, 0
	s_ashr_i32 s72, s3, 31
	v_or_b32_e32 v148, s18, v1
	s_add_u32 s18, s2, s3
	v_bitop3_b32 v147, v0, s22, v2 bitop3:0xde
	s_waitcnt vmcnt(6)
	s_addc_u32 s19, s19, s72
	s_add_i32 s75, 0, 0x10000
	s_add_i32 s77, 0, 0x14000
	v_add_u32_e32 v149, s75, v147
	v_add_u32_e32 v150, s77, v147
	s_add_i32 s75, s75, s47
	s_add_i32 s77, s77, s47
	s_add_i32 s81, 0, 0x18000
	s_sext_i32_i8 s82, s4
	v_mov_b64_e32 v[136:137], 0x410
	v_mov_b64_e32 v[138:139], 0x40f
	v_add_u32_e32 v151, 0, v3
	s_add_i32 s73, s43, 0xc000
	s_add_i32 s74, s43, 0xe000
	s_mov_b64 s[20:21], 0x100
	s_mov_b64 s[22:23], 0x180
	s_mov_b64 s[24:25], 0x40000
	s_mov_b64 s[26:27], 0x48000
	s_mov_b64 s[28:29], 0x50000
	s_mov_b64 s[30:31], 0x58000
	s_add_i32 s76, s75, 0x2000
	s_add_i32 s80, s77, 0x2000
	v_add_u32_e32 v152, s81, v147
	s_barrier
	s_mov_b32 s99, 0
	s_branch .LBB0_1352

; #define PG8_BAR __builtin_amdgcn_s_barrier()
; template <class Epi, class Sched, bool ALIGN_EPI = false, bool SP2 = false>
; __device__ __forceinline__ void gemm_phase(PG8_LAS unsigned char* lds, const Gemm g, const Sched& S, const Epi& E) {
;     ...
;         if (!has_next) break;
; #pragma unroll
;         for (int a = 0; a < 2; ++a)
; #pragma unroll
;             for (int b = 0; b < 2; ++b)
; #pragma unroll
;                 for (int m = 0; m < 4; ++m)
; #pragma unroll
;                     for (int n = 0; n < 2; ++n) acc[a][b][m][n] = (f32x4){0.f, 0.f, 0.f, 0.f};
;         cur = nxt; cA = nA; cB = nB; ++ui;
;         if constexpr (ALIGN_EPI) { if (wr == 1) PG8_BAR; }
.LBB0_1351:
	s_mov_b32 s99, 1
	s_and_b64 vcc, exec, s[4:5]
	s_mov_b32 s82, s34
	s_mov_b32 s42, s36
	s_mov_b64 s[62:63], s[40:41]
	s_mov_b64 s[52:53], s[38:39]
	s_cbranch_vccnz .LBB0_1359

; #define PG8_STAGE(bufoff, gbase, voff) do { _Pragma("unroll") for (int _i = 0; _i < 2; ++_i) \
;         __builtin_amdgcn_global_load_lds((const unsigned*)((const char*)(gbase) + (voff)[_i]), (PG8_LAS unsigned*)(lds + (bufoff) + ldsw + _i * 8192), 16, 0, 0); } while (0)
; #define PG8_LDA(dst, b, h) do { _Pragma("unroll") for (int m = 0; m < 4; ++m) _Pragma("unroll") for (int k = 0; k < 2; ++k) dst[m][k] = *(const PG8_LAS bf16x8*)(lds + PG8_SA(b, h) + aoff + m * 2048 + k * 1024); } while (0)
; #define PG8_LDB(dst, b, h) do { _Pragma("unroll") for (int n = 0; n < 2; ++n) _Pragma("unroll") for (int k = 0; k < 2; ++k) dst[n][k] = *(const PG8_LAS bf16x8*)(lds + PG8_SB(b, h) + boff + n * 2048 + k * 1024); } while (0)
; #define PG8_MMA(ai, bj, At, Bt) do { __builtin_amdgcn_s_setprio(1); _Pragma("unroll") for (int m = 0; m < 4; ++m) _Pragma("unroll") for (int n = 0; n < 2; ++n) _Pragma("unroll") for (int k = 0; k < 2; ++k) \
;         acc[ai][bj][m][n] = __builtin_amdgcn_mfma_f32_16x16x32_bf16(Bt[n][k], At[m][k], acc[ai][bj][m][n], 0, 0, 0); __builtin_amdgcn_s_setprio(0); } while (0)
; #define PG8_WAIT_V(n) asm volatile("s_waitcnt vmcnt(" #n ")" ::: "memory")
; #define PG8_WAIT_L(n) asm volatile("s_waitcnt lgkmcnt(" #n ")" ::: "memory")
; #define PG8_BAR __builtin_amdgcn_s_barrier()
; template <class Epi, class Sched, bool ALIGN_EPI = false, bool SP2 = false>
; __device__ __forceinline__ void gemm_phase(PG8_LAS unsigned char* lds, const Gemm g, const Sched& S, const Epi& E) {
;     ...
;         const bool has_next = S.next(ui + 1, nxt);
;         const char* nA = has_next ? (const char*)g.A + (size_t)nxt.pm * tstep : cA; const char* nB = has_next ? (const char*)g.Bt + (size_t)nxt.pn * tstep : cB;
;         for (int t = 0; t < nt; t += 2) {
;             const bool last = (t == nt - 2);
;             const char* a1 = cA + (size_t)(t + 1) * kstep;
;             const char* a2 = last ? nA : cA + (size_t)(t + 2) * kstep; const char* b2 = last ? nB : cB + (size_t)(t + 2) * kstep;
;             const char* a3 = a2 + kstep; const char* b3 = b2 + kstep;
;             if (last && has_next) S.a_ready(nxt);
;             if constexpr (SP2) {
;             PG8_LDB(B0, 0, 0); PG8_LDB(B1, 0, 1); PG8_SCHED; PG8_LDA(At, 0, 0); PG8_STAGE(PG8_SA(1, 1), a1 + hstep, voffA);
;             PG8_WAIT_V(8); PG8_WAIT_L(0); PG8_BAR; PG8_MMA(0, 0, At, B0); PG8_MMA(0, 1, At, B1); PG8_BAR; PG8_SCHED;
.LBB0_1354:
	ds_read_b128 v[0:3], v149
	ds_read_b128 v[4:7], v149 offset:1024
	ds_read_b128 v[8:11], v149 offset:2048
	ds_read_b128 v[12:15], v149 offset:3072
	ds_read_b128 v[16:19], v150
	ds_read_b128 v[20:23], v150 offset:1024
	ds_read_b128 v[24:27], v150 offset:2048
	ds_read_b128 v[28:31], v150 offset:3072
	s_ashr_i32 s37, s36, 31
	s_lshl_b64 s[38:39], s[36:37], 17
	s_add_u32 s38, s6, s38
	s_addc_u32 s39, s7, s39
	s_and_b64 s[40:41], s[4:5], exec
	s_cselect_b32 s67, s39, s53
	s_cselect_b32 s66, s38, s52
	s_ashr_i32 s35, s34, 31
	s_lshl_b64 s[40:41], s[34:35], 17
	s_add_u32 s40, s33, s40
	s_addc_u32 s41, s46, s41
	s_and_b64 s[64:65], s[4:5], exec
	s_cselect_b32 s65, s41, s63
	s_cselect_b32 s64, s40, s62
	s_add_u32 s88, s52, 0x10080
	s_addc_u32 s89, s53, 0
	s_mov_b32 m0, s73
	v_lshl_add_u64 v[64:65], s[88:89], 0, v[134:135]
	ds_read_b128 v[32:35], v151
	ds_read_b128 v[36:39], v151 offset:1024
	ds_read_b128 v[40:43], v151 offset:2048
	ds_read_b128 v[44:47], v151 offset:3072
	ds_read_b128 v[48:51], v151 offset:4096
	ds_read_b128 v[52:55], v151 offset:5120
	ds_read_b128 v[56:59], v151 offset:6144
	ds_read_b128 v[60:63], v151 offset:7168
	global_load_lds_dwordx4 v[64:65], off
	v_lshl_add_u64 v[64:65], s[88:89], 0, v[130:131]
	s_mov_b32 m0, s74
	s_nop 0
	global_load_lds_dwordx4 v[64:65], off
	s_cmp_eq_u32 s99, 1
	s_cbranch_scc1 .Lrw_P3b_0
	s_waitcnt vmcnt(8)
	s_branch .Lrj_P3b_0

; #define PG8_STAGE(bufoff, gbase, voff) do { _Pragma("unroll") for (int _i = 0; _i < 2; ++_i) \
;         __builtin_amdgcn_global_load_lds((const unsigned*)((const char*)(gbase) + (voff)[_i]), (PG8_LAS unsigned*)(lds + (bufoff) + ldsw + _i * 8192), 16, 0, 0); } while (0)
; #define PG8_LDA(dst, b, h) do { _Pragma("unroll") for (int m = 0; m < 4; ++m) _Pragma("unroll") for (int k = 0; k < 2; ++k) dst[m][k] = *(const PG8_LAS bf16x8*)(lds + PG8_SA(b, h) + aoff + m * 2048 + k * 1024); } while (0)
; #define PG8_MMA(ai, bj, At, Bt) do { __builtin_amdgcn_s_setprio(1); _Pragma("unroll") for (int m = 0; m < 4; ++m) _Pragma("unroll") for (int n = 0; n < 2; ++n) _Pragma("unroll") for (int k = 0; k < 2; ++k) \
;         acc[ai][bj][m][n] = __builtin_amdgcn_mfma_f32_16x16x32_bf16(Bt[n][k], At[m][k], acc[ai][bj][m][n], 0, 0, 0); __builtin_amdgcn_s_setprio(0); } while (0)
; #define PG8_WAIT_V(n) asm volatile("s_waitcnt vmcnt(" #n ")" ::: "memory")
; #define PG8_WAIT_L(n) asm volatile("s_waitcnt lgkmcnt(" #n ")" ::: "memory")
; #define PG8_BAR __builtin_amdgcn_s_barrier()
; #define PG8_SCHED __builtin_amdgcn_sched_barrier(0)
; template <class Epi, class Sched, bool ALIGN_EPI = false, bool SP2 = false>
; __device__ __forceinline__ void gemm_phase(PG8_LAS unsigned char* lds, const Gemm g, const Sched& S, const Epi& E) {
;     ...
;             PG8_WAIT_V(8); PG8_WAIT_L(0); PG8_BAR; PG8_MMA(0, 0, At, B0); PG8_MMA(0, 1, At, B1); PG8_BAR; PG8_SCHED;
;             PG8_LDA(At, 0, 1); PG8_STAGE(PG8_SB(0, 0), b2, voffB); PG8_STAGE(PG8_SB(0, 1), b2 + hstep, voffB); PG8_STAGE(PG8_SA(0, 0), a2, voffA);
;             PG8_WAIT_V(8); PG8_WAIT_L(0); PG8_BAR; PG8_MMA(1, 0, At, B0); PG8_MMA(1, 1, At, B1); PG8_BAR; PG8_SCHED;
.Lrj_P3b_0:
	s_waitcnt lgkmcnt(0)
	s_barrier
	s_setprio 1
	s_waitcnt lgkmcnt(0)
	v_mfma_f32_16x16x32_bf16 v[64:67], v[0:3], v[32:35], 0
	v_mfma_f32_16x16x32_bf16 v[68:71], v[8:11], v[32:35], 0
	v_mfma_f32_16x16x32_bf16 v[72:75], v[0:3], v[40:43], 0
	v_mfma_f32_16x16x32_bf16 v[76:79], v[8:11], v[40:43], 0
	v_mfma_f32_16x16x32_bf16 v[80:83], v[0:3], v[48:51], 0
	v_mfma_f32_16x16x32_bf16 v[84:87], v[8:11], v[48:51], 0
	v_mfma_f32_16x16x32_bf16 v[88:91], v[0:3], v[56:59], 0
	v_mfma_f32_16x16x32_bf16 v[92:95], v[8:11], v[56:59], 0
	v_mfma_f32_16x16x32_bf16 v[64:67], v[4:7], v[36:39], v[64:67]
	v_mfma_f32_16x16x32_bf16 v[68:71], v[12:15], v[36:39], v[68:71]
	v_mfma_f32_16x16x32_bf16 v[72:75], v[4:7], v[44:47], v[72:75]
	v_mfma_f32_16x16x32_bf16 v[76:79], v[12:15], v[44:47], v[76:79]
	v_mfma_f32_16x16x32_bf16 v[80:83], v[4:7], v[52:55], v[80:83]
	v_mfma_f32_16x16x32_bf16 v[84:87], v[12:15], v[52:55], v[84:87]
	v_mfma_f32_16x16x32_bf16 v[88:91], v[4:7], v[60:63], v[88:91]
	v_mfma_f32_16x16x32_bf16 v[92:95], v[12:15], v[60:63], v[92:95]
	s_setprio 0
	s_setprio 1
	v_mfma_f32_16x16x32_bf16 v[96:99], v[16:19], v[32:35], 0
	v_mfma_f32_16x16x32_bf16 v[32:35], v[24:27], v[32:35], 0
	v_mfma_f32_16x16x32_bf16 v[96:99], v[20:23], v[36:39], v[96:99]
	v_mfma_f32_16x16x32_bf16 v[32:35], v[28:31], v[36:39], v[32:35]
	v_mfma_f32_16x16x32_bf16 v[36:39], v[16:19], v[40:43], 0
	v_mfma_f32_16x16x32_bf16 v[40:43], v[24:27], v[40:43], 0
	v_mfma_f32_16x16x32_bf16 v[36:39], v[20:23], v[44:47], v[36:39]
	v_mfma_f32_16x16x32_bf16 v[40:43], v[28:31], v[44:47], v[40:43]
	v_mfma_f32_16x16x32_bf16 v[44:47], v[16:19], v[48:51], 0
	v_mfma_f32_16x16x32_bf16 v[48:51], v[24:27], v[48:51], 0
	v_mfma_f32_16x16x32_bf16 v[44:47], v[20:23], v[52:55], v[44:47]
	v_mfma_f32_16x16x32_bf16 v[48:51], v[28:31], v[52:55], v[48:51]
	v_mfma_f32_16x16x32_bf16 v[52:55], v[16:19], v[56:59], 0
	v_mfma_f32_16x16x32_bf16 v[56:59], v[24:27], v[56:59], 0
	v_mfma_f32_16x16x32_bf16 v[52:55], v[20:23], v[60:63], v[52:55]
	v_mfma_f32_16x16x32_bf16 v[56:59], v[28:31], v[60:63], v[56:59]
	s_setprio 0
	s_barrier
	v_lshl_add_u64 v[144:145], s[62:63], 0, v[132:133]
	s_mov_b32 m0, s75
	v_lshl_add_u64 v[140:141], v[144:145], 0, s[20:21]
	v_lshl_add_u64 v[214:215], s[62:63], 0, v[128:129]
	s_add_u32 s88, s62, 0x10100
	ds_read_b128 v[60:63], v151 offset:16384
	ds_read_b128 v[100:103], v151 offset:17408
	ds_read_b128 v[104:107], v151 offset:18432
	ds_read_b128 v[108:111], v151 offset:19456
	ds_read_b128 v[112:115], v151 offset:20480
	ds_read_b128 v[116:119], v151 offset:21504
	ds_read_b128 v[120:123], v151 offset:22528
	ds_read_b128 v[124:127], v151 offset:23552
	global_load_lds_dwordx4 v[140:141], off
	v_lshl_add_u64 v[140:141], v[214:215], 0, s[20:21]
	s_mov_b32 m0, s76
	s_addc_u32 s89, s63, 0
	global_load_lds_dwordx4 v[140:141], off
	v_lshl_add_u64 v[140:141], s[88:89], 0, v[132:133]
	s_mov_b32 m0, s77
	v_lshl_add_u64 v[216:217], s[52:53], 0, v[134:135]
	global_load_lds_dwordx4 v[140:141], off
	v_lshl_add_u64 v[140:141], s[88:89], 0, v[128:129]
	s_mov_b32 m0, s80
	v_lshl_add_u64 v[218:219], s[52:53], 0, v[130:131]
	global_load_lds_dwordx4 v[140:141], off
	v_lshl_add_u64 v[140:141], v[216:217], 0, s[20:21]
	s_mov_b32 m0, s43
	s_nop 0
	global_load_lds_dwordx4 v[140:141], off
	v_lshl_add_u64 v[140:141], v[218:219], 0, s[20:21]
	s_mov_b32 m0, s61
	s_nop 0
	global_load_lds_dwordx4 v[140:141], off
	s_cmp_eq_u32 s99, 1
	s_cbranch_scc1 .Lrw_P3b_1
	s_waitcnt vmcnt(8)
	s_branch .Lrj_P3b_1

; #define PG8_STAGE(bufoff, gbase, voff) do { _Pragma("unroll") for (int _i = 0; _i < 2; ++_i) \
;         __builtin_amdgcn_global_load_lds((const unsigned*)((const char*)(gbase) + (voff)[_i]), (PG8_LAS unsigned*)(lds + (bufoff) + ldsw + _i * 8192), 16, 0, 0); } while (0)
; #define PG8_LDA(dst, b, h) do { _Pragma("unroll") for (int m = 0; m < 4; ++m) _Pragma("unroll") for (int k = 0; k < 2; ++k) dst[m][k] = *(const PG8_LAS bf16x8*)(lds + PG8_SA(b, h) + aoff + m * 2048 + k * 1024); } while (0)
; #define PG8_LDB(dst, b, h) do { _Pragma("unroll") for (int n = 0; n < 2; ++n) _Pragma("unroll") for (int k = 0; k < 2; ++k) dst[n][k] = *(const PG8_LAS bf16x8*)(lds + PG8_SB(b, h) + boff + n * 2048 + k * 1024); } while (0)
; #define PG8_MMA(ai, bj, At, Bt) do { __builtin_amdgcn_s_setprio(1); _Pragma("unroll") for (int m = 0; m < 4; ++m) _Pragma("unroll") for (int n = 0; n < 2; ++n) _Pragma("unroll") for (int k = 0; k < 2; ++k) \
;         acc[ai][bj][m][n] = __builtin_amdgcn_mfma_f32_16x16x32_bf16(Bt[n][k], At[m][k], acc[ai][bj][m][n], 0, 0, 0); __builtin_amdgcn_s_setprio(0); } while (0)
; #define PG8_WAIT_V(n) asm volatile("s_waitcnt vmcnt(" #n ")" ::: "memory")
; #define PG8_WAIT_L(n) asm volatile("s_waitcnt lgkmcnt(" #n ")" ::: "memory")
; #define PG8_BAR __builtin_amdgcn_s_barrier()
; #define PG8_SCHED __builtin_amdgcn_sched_barrier(0)
; template <class Epi, class Sched, bool ALIGN_EPI = false, bool SP2 = false>
; __device__ __forceinline__ void gemm_phase(PG8_LAS unsigned char* lds, const Gemm g, const Sched& S, const Epi& E) {
;     ...
;             PG8_WAIT_V(8); PG8_WAIT_L(0); PG8_BAR; PG8_MMA(1, 0, At, B0); PG8_MMA(1, 1, At, B1); PG8_BAR; PG8_SCHED;
;             PG8_LDB(B0, 1, 0); PG8_LDB(B1, 1, 1); PG8_SCHED; PG8_LDA(At, 1, 0); PG8_STAGE(PG8_SA(0, 1), a2 + hstep, voffA);
;             PG8_WAIT_V(8); PG8_WAIT_L(0); PG8_BAR; PG8_MMA(0, 0, At, B0); PG8_MMA(0, 1, At, B1); PG8_BAR; PG8_SCHED;
.Lrj_P3b_1:
	s_mov_b32 s99, 0
	s_waitcnt lgkmcnt(0)
	s_barrier
	s_setprio 1
	s_waitcnt lgkmcnt(0)
	v_mfma_f32_16x16x32_bf16 v[140:143], v[0:3], v[60:63], 0
	v_mfma_f32_16x16x32_bf16 v[158:161], v[0:3], v[104:107], 0
	v_mfma_f32_16x16x32_bf16 v[166:169], v[0:3], v[112:115], 0
	v_mfma_f32_16x16x32_bf16 v[0:3], v[0:3], v[120:123], 0
	v_mfma_f32_16x16x32_bf16 v[140:143], v[4:7], v[100:103], v[140:143]
	v_mfma_f32_16x16x32_bf16 v[158:161], v[4:7], v[108:111], v[158:161]
	v_mfma_f32_16x16x32_bf16 v[166:169], v[4:7], v[116:119], v[166:169]
	v_mfma_f32_16x16x32_bf16 v[0:3], v[4:7], v[124:127], v[0:3]
	v_mfma_f32_16x16x32_bf16 v[4:7], v[8:11], v[120:123], 0
	v_mfma_f32_16x16x32_bf16 v[154:157], v[8:11], v[60:63], 0
	v_mfma_f32_16x16x32_bf16 v[162:165], v[8:11], v[104:107], 0
	v_mfma_f32_16x16x32_bf16 v[170:173], v[8:11], v[112:115], 0
	v_mfma_f32_16x16x32_bf16 v[4:7], v[12:15], v[124:127], v[4:7]
	v_mfma_f32_16x16x32_bf16 v[154:157], v[12:15], v[100:103], v[154:157]
	v_mfma_f32_16x16x32_bf16 v[162:165], v[12:15], v[108:111], v[162:165]
	v_mfma_f32_16x16x32_bf16 v[170:173], v[12:15], v[116:119], v[170:173]
	s_setprio 0
	s_setprio 1
	v_mfma_f32_16x16x32_bf16 v[8:11], v[16:19], v[60:63], 0
	v_mfma_f32_16x16x32_bf16 v[12:15], v[24:27], v[60:63], 0
	v_mfma_f32_16x16x32_bf16 v[8:11], v[20:23], v[100:103], v[8:11]
	v_mfma_f32_16x16x32_bf16 v[12:15], v[28:31], v[100:103], v[12:15]
	v_mfma_f32_16x16x32_bf16 v[60:63], v[16:19], v[104:107], 0
	v_mfma_f32_16x16x32_bf16 v[100:103], v[24:27], v[104:107], 0
	v_mfma_f32_16x16x32_bf16 v[104:107], v[16:19], v[112:115], 0
	v_mfma_f32_16x16x32_bf16 v[16:19], v[16:19], v[120:123], 0
	v_mfma_f32_16x16x32_bf16 v[60:63], v[20:23], v[108:111], v[60:63]
	v_mfma_f32_16x16x32_bf16 v[100:103], v[28:31], v[108:111], v[100:103]
	v_mfma_f32_16x16x32_bf16 v[104:107], v[20:23], v[116:119], v[104:107]
	v_mfma_f32_16x16x32_bf16 v[108:111], v[24:27], v[112:115], 0
	v_mfma_f32_16x16x32_bf16 v[16:19], v[20:23], v[124:127], v[16:19]
	v_mfma_f32_16x16x32_bf16 v[20:23], v[24:27], v[120:123], 0
	v_mfma_f32_16x16x32_bf16 v[108:111], v[28:31], v[116:119], v[108:111]
	v_mfma_f32_16x16x32_bf16 v[20:23], v[28:31], v[124:127], v[20:23]
	s_setprio 0
	s_barrier
	s_add_i32 s37, 0, 0x1c000
	v_add_u32_e32 v153, s37, v147
	ds_read_b128 v[24:27], v152
	ds_read_b128 v[28:31], v152 offset:1024
	ds_read_b128 v[112:115], v152 offset:2048
	ds_read_b128 v[116:119], v152 offset:3072
	ds_read_b128 v[120:123], v153
	ds_read_b128 v[124:127], v153 offset:1024
	ds_read_b128 v[174:177], v153 offset:2048
	ds_read_b128 v[178:181], v153 offset:3072
	s_add_u32 s88, s52, 0x10100
	s_addc_u32 s89, s53, 0
	s_mov_b32 m0, s68
	v_lshl_add_u64 v[220:221], s[88:89], 0, v[134:135]
	ds_read_b128 v[182:185], v151 offset:32768
	ds_read_b128 v[186:189], v151 offset:33792
	ds_read_b128 v[190:193], v151 offset:34816
	ds_read_b128 v[194:197], v151 offset:35840
	ds_read_b128 v[198:201], v151 offset:36864
	ds_read_b128 v[202:205], v151 offset:37888
	ds_read_b128 v[206:209], v151 offset:38912
	ds_read_b128 v[210:213], v151 offset:39936
	global_load_lds_dwordx4 v[220:221], off
	v_lshl_add_u64 v[220:221], s[88:89], 0, v[130:131]
	s_mov_b32 m0, s69
	s_nop 0
	global_load_lds_dwordx4 v[220:221], off
	s_waitcnt vmcnt(8)
	s_waitcnt lgkmcnt(0)
	s_barrier
	s_setprio 1
	s_waitcnt lgkmcnt(0)
	v_mfma_f32_16x16x32_bf16 v[64:67], v[24:27], v[182:185], v[64:67]
	v_mfma_f32_16x16x32_bf16 v[68:71], v[112:115], v[182:185], v[68:71]
	v_mfma_f32_16x16x32_bf16 v[72:75], v[24:27], v[190:193], v[72:75]
	v_mfma_f32_16x16x32_bf16 v[76:79], v[112:115], v[190:193], v[76:79]
	v_mfma_f32_16x16x32_bf16 v[80:83], v[24:27], v[198:201], v[80:83]
	v_mfma_f32_16x16x32_bf16 v[84:87], v[112:115], v[198:201], v[84:87]
	v_mfma_f32_16x16x32_bf16 v[88:91], v[24:27], v[206:209], v[88:91]
	v_mfma_f32_16x16x32_bf16 v[92:95], v[112:115], v[206:209], v[92:95]
	v_mfma_f32_16x16x32_bf16 v[64:67], v[28:31], v[186:189], v[64:67]
	v_mfma_f32_16x16x32_bf16 v[68:71], v[116:119], v[186:189], v[68:71]
	v_mfma_f32_16x16x32_bf16 v[72:75], v[28:31], v[194:197], v[72:75]
	v_mfma_f32_16x16x32_bf16 v[76:79], v[116:119], v[194:197], v[76:79]
	v_mfma_f32_16x16x32_bf16 v[80:83], v[28:31], v[202:205], v[80:83]
	v_mfma_f32_16x16x32_bf16 v[84:87], v[116:119], v[202:205], v[84:87]
	v_mfma_f32_16x16x32_bf16 v[88:91], v[28:31], v[210:213], v[88:91]
	v_mfma_f32_16x16x32_bf16 v[92:95], v[116:119], v[210:213], v[92:95]
	s_setprio 0
	s_setprio 1
	v_mfma_f32_16x16x32_bf16 v[96:99], v[120:123], v[182:185], v[96:99]
	v_mfma_f32_16x16x32_bf16 v[32:35], v[174:177], v[182:185], v[32:35]
	v_mfma_f32_16x16x32_bf16 v[36:39], v[120:123], v[190:193], v[36:39]
	v_mfma_f32_16x16x32_bf16 v[40:43], v[174:177], v[190:193], v[40:43]
	v_mfma_f32_16x16x32_bf16 v[44:47], v[120:123], v[198:201], v[44:47]
	v_mfma_f32_16x16x32_bf16 v[48:51], v[174:177], v[198:201], v[48:51]
	v_mfma_f32_16x16x32_bf16 v[52:55], v[120:123], v[206:209], v[52:55]
	v_mfma_f32_16x16x32_bf16 v[56:59], v[174:177], v[206:209], v[56:59]
	v_mfma_f32_16x16x32_bf16 v[96:99], v[124:127], v[186:189], v[96:99]
	v_mfma_f32_16x16x32_bf16 v[32:35], v[178:181], v[186:189], v[32:35]
	v_mfma_f32_16x16x32_bf16 v[36:39], v[124:127], v[194:197], v[36:39]
	v_mfma_f32_16x16x32_bf16 v[40:43], v[178:181], v[194:197], v[40:43]
	v_mfma_f32_16x16x32_bf16 v[44:47], v[124:127], v[202:205], v[44:47]
	v_mfma_f32_16x16x32_bf16 v[48:51], v[178:181], v[202:205], v[48:51]
	v_mfma_f32_16x16x32_bf16 v[52:55], v[124:127], v[210:213], v[52:55]
	v_mfma_f32_16x16x32_bf16 v[56:59], v[178:181], v[210:213], v[56:59]
	s_setprio 0
	s_barrier
; #define PG8_STAGE(bufoff, gbase, voff) do { _Pragma("unroll") for (int _i = 0; _i < 2; ++_i) \
;         __builtin_amdgcn_global_load_lds((const unsigned*)((const char*)(gbase) + (voff)[_i]), (PG8_LAS unsigned*)(lds + (bufoff) + ldsw + _i * 8192), 16, 0, 0); } while (0)
; #define PG8_LDA(dst, b, h) do { _Pragma("unroll") for (int m = 0; m < 4; ++m) _Pragma("unroll") for (int k = 0; k < 2; ++k) dst[m][k] = *(const PG8_LAS bf16x8*)(lds + PG8_SA(b, h) + aoff + m * 2048 + k * 1024); } while (0)
; #define PG8_LDB(dst, b, h) do { _Pragma("unroll") for (int n = 0; n < 2; ++n) _Pragma("unroll") for (int k = 0; k < 2; ++k) dst[n][k] = *(const PG8_LAS bf16x8*)(lds + PG8_SB(b, h) + boff + n * 2048 + k * 1024); } while (0)
; #define PG8_MMA(ai, bj, At, Bt) do { __builtin_amdgcn_s_setprio(1); _Pragma("unroll") for (int m = 0; m < 4; ++m) _Pragma("unroll") for (int n = 0; n < 2; ++n) _Pragma("unroll") for (int k = 0; k < 2; ++k) \
;         acc[ai][bj][m][n] = __builtin_amdgcn_mfma_f32_16x16x32_bf16(Bt[n][k], At[m][k], acc[ai][bj][m][n], 0, 0, 0); __builtin_amdgcn_s_setprio(0); } while (0)
; #define PG8_WAIT_V(n) asm volatile("s_waitcnt vmcnt(" #n ")" ::: "memory")
; #define PG8_WAIT_L(n) asm volatile("s_waitcnt lgkmcnt(" #n ")" ::: "memory")
; #define PG8_BAR __builtin_amdgcn_s_barrier()
; #define PG8_SCHED __builtin_amdgcn_sched_barrier(0)
; template <class Epi, class Sched, bool ALIGN_EPI = false, bool SP2 = false>
; __device__ __forceinline__ void gemm_phase(PG8_LAS unsigned char* lds, const Gemm g, const Sched& S, const Epi& E) {
;     ...
;             PG8_LDB(B0, 0, 0); PG8_LDB(B1, 0, 1); PG8_SCHED; PG8_LDA(At, 0, 0); PG8_STAGE(PG8_SA(1, 1), a1 + hstep, voffA);
;             PG8_WAIT_V(8); PG8_WAIT_L(0); PG8_BAR; PG8_MMA(0, 0, At, B0); PG8_MMA(0, 1, At, B1); PG8_BAR; PG8_SCHED;
;     ...
;             PG8_LDA(At, 1, 1); PG8_STAGE(PG8_SB(1, 0), b3, voffB); PG8_STAGE(PG8_SB(1, 1), b3 + hstep, voffB); PG8_STAGE(PG8_SA(1, 0), a3, voffA);
;             PG8_WAIT_V(8); PG8_WAIT_L(0); PG8_BAR; PG8_MMA(1, 0, At, B0); PG8_MMA(1, 1, At, B1); PG8_BAR; PG8_SCHED;
	s_add_i32 s83, s81, s47
	s_add_i32 s35, s83, 0x2000
	v_lshl_add_u64 v[144:145], v[144:145], 0, s[22:23]
	s_mov_b32 m0, s83
	s_add_u32 s62, s62, 0x10180
	ds_read_b128 v[182:185], v151 offset:49152
	ds_read_b128 v[186:189], v151 offset:50176
	ds_read_b128 v[190:193], v151 offset:51200
	ds_read_b128 v[194:197], v151 offset:52224
	ds_read_b128 v[198:201], v151 offset:53248
	ds_read_b128 v[202:205], v151 offset:54272
	ds_read_b128 v[206:209], v151 offset:55296
	ds_read_b128 v[210:213], v151 offset:56320
	global_load_lds_dwordx4 v[144:145], off
	v_lshl_add_u64 v[144:145], v[214:215], 0, s[22:23]
	s_mov_b32 m0, s35
	s_addc_u32 s63, s63, 0
	s_add_i32 s37, s37, s47
	global_load_lds_dwordx4 v[144:145], off
	v_lshl_add_u64 v[144:145], s[62:63], 0, v[132:133]
	s_mov_b32 m0, s37
	s_nop 0
	global_load_lds_dwordx4 v[144:145], off
	v_lshl_add_u64 v[144:145], s[62:63], 0, v[128:129]
	s_add_i32 s62, s37, 0x2000
	s_mov_b32 m0, s62
	s_nop 0
	global_load_lds_dwordx4 v[144:145], off
	v_lshl_add_u64 v[144:145], v[216:217], 0, s[22:23]
	s_mov_b32 m0, s70
	s_nop 0
	global_load_lds_dwordx4 v[144:145], off
	v_lshl_add_u64 v[144:145], v[218:219], 0, s[22:23]
	s_mov_b32 m0, s71
	s_nop 0
	global_load_lds_dwordx4 v[144:145], off
	s_waitcnt vmcnt(8)
	s_waitcnt lgkmcnt(0)
	s_barrier
	s_setprio 1
	s_waitcnt lgkmcnt(0)
	v_mfma_f32_16x16x32_bf16 v[0:3], v[24:27], v[206:209], v[0:3]
	v_mfma_f32_16x16x32_bf16 v[4:7], v[112:115], v[206:209], v[4:7]
	v_mfma_f32_16x16x32_bf16 v[140:143], v[24:27], v[182:185], v[140:143]
	v_mfma_f32_16x16x32_bf16 v[154:157], v[112:115], v[182:185], v[154:157]
	v_mfma_f32_16x16x32_bf16 v[158:161], v[24:27], v[190:193], v[158:161]
	v_mfma_f32_16x16x32_bf16 v[162:165], v[112:115], v[190:193], v[162:165]
	v_mfma_f32_16x16x32_bf16 v[166:169], v[24:27], v[198:201], v[166:169]
	v_mfma_f32_16x16x32_bf16 v[170:173], v[112:115], v[198:201], v[170:173]
	v_mfma_f32_16x16x32_bf16 v[0:3], v[28:31], v[210:213], v[0:3]
	v_mfma_f32_16x16x32_bf16 v[4:7], v[116:119], v[210:213], v[4:7]
	v_mfma_f32_16x16x32_bf16 v[140:143], v[28:31], v[186:189], v[140:143]
	v_mfma_f32_16x16x32_bf16 v[154:157], v[116:119], v[186:189], v[154:157]
	v_mfma_f32_16x16x32_bf16 v[158:161], v[28:31], v[194:197], v[158:161]
	v_mfma_f32_16x16x32_bf16 v[162:165], v[116:119], v[194:197], v[162:165]
	v_mfma_f32_16x16x32_bf16 v[166:169], v[28:31], v[202:205], v[166:169]
	v_mfma_f32_16x16x32_bf16 v[170:173], v[116:119], v[202:205], v[170:173]
	s_setprio 0
	s_setprio 1
	v_mfma_f32_16x16x32_bf16 v[8:11], v[120:123], v[182:185], v[8:11]
	v_mfma_f32_16x16x32_bf16 v[12:15], v[174:177], v[182:185], v[12:15]
	v_mfma_f32_16x16x32_bf16 v[24:27], v[120:123], v[190:193], v[60:63]
	v_mfma_f32_16x16x32_bf16 v[28:31], v[174:177], v[190:193], v[100:103]
	v_mfma_f32_16x16x32_bf16 v[60:63], v[120:123], v[198:201], v[104:107]
	v_mfma_f32_16x16x32_bf16 v[100:103], v[174:177], v[198:201], v[108:111]
	v_mfma_f32_16x16x32_bf16 v[16:19], v[120:123], v[206:209], v[16:19]
	v_mfma_f32_16x16x32_bf16 v[20:23], v[174:177], v[206:209], v[20:23]
	v_mfma_f32_16x16x32_bf16 v[8:11], v[124:127], v[186:189], v[8:11]
	v_mfma_f32_16x16x32_bf16 v[12:15], v[178:181], v[186:189], v[12:15]
	v_mfma_f32_16x16x32_bf16 v[24:27], v[124:127], v[194:197], v[24:27]
	v_mfma_f32_16x16x32_bf16 v[28:31], v[178:181], v[194:197], v[28:31]
	v_mfma_f32_16x16x32_bf16 v[60:63], v[124:127], v[202:205], v[60:63]
	v_mfma_f32_16x16x32_bf16 v[100:103], v[178:181], v[202:205], v[100:103]
	v_mfma_f32_16x16x32_bf16 v[16:19], v[124:127], v[210:213], v[16:19]
	v_mfma_f32_16x16x32_bf16 v[20:23], v[178:181], v[210:213], v[20:23]
	s_setprio 0
	s_barrier
	ds_read_b128 v[104:107], v149
	ds_read_b128 v[108:111], v149 offset:1024
	ds_read_b128 v[112:115], v149 offset:2048
	ds_read_b128 v[116:119], v149 offset:3072
	ds_read_b128 v[120:123], v150
	ds_read_b128 v[124:127], v150 offset:1024
	ds_read_b128 v[174:177], v150 offset:2048
	ds_read_b128 v[178:181], v150 offset:3072
	s_add_u32 s52, s52, 0x10180
	s_addc_u32 s53, s53, 0
	s_mov_b32 m0, s73
	v_lshl_add_u64 v[144:145], s[52:53], 0, v[134:135]
	ds_read_b128 v[182:185], v151
	ds_read_b128 v[186:189], v151 offset:1024
	ds_read_b128 v[190:193], v151 offset:2048
	ds_read_b128 v[194:197], v151 offset:3072
	ds_read_b128 v[198:201], v151 offset:4096
	ds_read_b128 v[202:205], v151 offset:5120
	ds_read_b128 v[206:209], v151 offset:6144
	ds_read_b128 v[210:213], v151 offset:7168
	global_load_lds_dwordx4 v[144:145], off
	v_lshl_add_u64 v[144:145], s[52:53], 0, v[130:131]
	s_mov_b32 m0, s74
	s_nop 0
	global_load_lds_dwordx4 v[144:145], off
	s_waitcnt vmcnt(8)
	s_waitcnt lgkmcnt(0)
	s_barrier
; #define PG8_STAGE(bufoff, gbase, voff) do { _Pragma("unroll") for (int _i = 0; _i < 2; ++_i) \
;         __builtin_amdgcn_global_load_lds((const unsigned*)((const char*)(gbase) + (voff)[_i]), (PG8_LAS unsigned*)(lds + (bufoff) + ldsw + _i * 8192), 16, 0, 0); } while (0)
; #define PG8_LDA(dst, b, h) do { _Pragma("unroll") for (int m = 0; m < 4; ++m) _Pragma("unroll") for (int k = 0; k < 2; ++k) dst[m][k] = *(const PG8_LAS bf16x8*)(lds + PG8_SA(b, h) + aoff + m * 2048 + k * 1024); } while (0)
; #define PG8_LDB(dst, b, h) do { _Pragma("unroll") for (int n = 0; n < 2; ++n) _Pragma("unroll") for (int k = 0; k < 2; ++k) dst[n][k] = *(const PG8_LAS bf16x8*)(lds + PG8_SB(b, h) + boff + n * 2048 + k * 1024); } while (0)
; #define PG8_MMA(ai, bj, At, Bt) do { __builtin_amdgcn_s_setprio(1); _Pragma("unroll") for (int m = 0; m < 4; ++m) _Pragma("unroll") for (int n = 0; n < 2; ++n) _Pragma("unroll") for (int k = 0; k < 2; ++k) \
;         acc[ai][bj][m][n] = __builtin_amdgcn_mfma_f32_16x16x32_bf16(Bt[n][k], At[m][k], acc[ai][bj][m][n], 0, 0, 0); __builtin_amdgcn_s_setprio(0); } while (0)
; #define PG8_WAIT_V(n) asm volatile("s_waitcnt vmcnt(" #n ")" ::: "memory")
; #define PG8_WAIT_L(n) asm volatile("s_waitcnt lgkmcnt(" #n ")" ::: "memory")
; #define PG8_BAR __builtin_amdgcn_s_barrier()
; #define PG8_SCHED __builtin_amdgcn_sched_barrier(0)
; template <class Epi, class Sched, bool ALIGN_EPI = false, bool SP2 = false>
; __device__ __forceinline__ void gemm_phase(PG8_LAS unsigned char* lds, const Gemm g, const Sched& S, const Epi& E) {
;     ...
;             PG8_WAIT_V(8); PG8_WAIT_L(0); PG8_BAR; PG8_MMA(0, 0, At, B0); PG8_MMA(0, 1, At, B1); PG8_BAR; PG8_SCHED;
;             PG8_LDA(At, 0, 1); PG8_STAGE(PG8_SB(0, 0), b2, voffB); PG8_STAGE(PG8_SB(0, 1), b2 + hstep, voffB); PG8_STAGE(PG8_SA(0, 0), a2, voffA);
;             PG8_WAIT_V(8); PG8_WAIT_L(0); PG8_BAR; PG8_MMA(1, 0, At, B0); PG8_MMA(1, 1, At, B1); PG8_BAR; PG8_SCHED;
;             PG8_LDB(B0, 1, 0); PG8_LDB(B1, 1, 1); PG8_SCHED; PG8_LDA(At, 1, 0); PG8_STAGE(PG8_SA(0, 1), a2 + hstep, voffA);
;             PG8_WAIT_V(8); PG8_WAIT_L(0); PG8_BAR; PG8_MMA(0, 0, At, B0); PG8_MMA(0, 1, At, B1); PG8_BAR; PG8_SCHED;
	s_setprio 1
	s_waitcnt lgkmcnt(0)
	v_mfma_f32_16x16x32_bf16 v[64:67], v[104:107], v[182:185], v[64:67]
	v_mfma_f32_16x16x32_bf16 v[68:71], v[112:115], v[182:185], v[68:71]
	v_mfma_f32_16x16x32_bf16 v[72:75], v[104:107], v[190:193], v[72:75]
	v_mfma_f32_16x16x32_bf16 v[76:79], v[112:115], v[190:193], v[76:79]
	v_mfma_f32_16x16x32_bf16 v[80:83], v[104:107], v[198:201], v[80:83]
	v_mfma_f32_16x16x32_bf16 v[84:87], v[112:115], v[198:201], v[84:87]
	v_mfma_f32_16x16x32_bf16 v[88:91], v[104:107], v[206:209], v[88:91]
	v_mfma_f32_16x16x32_bf16 v[64:67], v[108:111], v[186:189], v[64:67]
	v_mfma_f32_16x16x32_bf16 v[68:71], v[116:119], v[186:189], v[68:71]
	v_mfma_f32_16x16x32_bf16 v[72:75], v[108:111], v[194:197], v[72:75]
	v_mfma_f32_16x16x32_bf16 v[76:79], v[116:119], v[194:197], v[76:79]
	v_mfma_f32_16x16x32_bf16 v[80:83], v[108:111], v[202:205], v[80:83]
	v_mfma_f32_16x16x32_bf16 v[84:87], v[116:119], v[202:205], v[84:87]
	v_mfma_f32_16x16x32_bf16 v[214:217], v[108:111], v[210:213], v[88:91]
	v_mfma_f32_16x16x32_bf16 v[88:91], v[112:115], v[206:209], v[92:95]
	v_mfma_f32_16x16x32_bf16 v[218:221], v[116:119], v[210:213], v[88:91]
	s_setprio 0
	s_setprio 1
	v_mfma_f32_16x16x32_bf16 v[88:91], v[120:123], v[182:185], v[96:99]
	v_mfma_f32_16x16x32_bf16 v[32:35], v[174:177], v[182:185], v[32:35]
	v_mfma_f32_16x16x32_bf16 v[36:39], v[120:123], v[190:193], v[36:39]
	v_mfma_f32_16x16x32_bf16 v[40:43], v[174:177], v[190:193], v[40:43]
	v_mfma_f32_16x16x32_bf16 v[44:47], v[120:123], v[198:201], v[44:47]
	v_mfma_f32_16x16x32_bf16 v[48:51], v[174:177], v[198:201], v[48:51]
	v_mfma_f32_16x16x32_bf16 v[52:55], v[120:123], v[206:209], v[52:55]
	v_mfma_f32_16x16x32_bf16 v[56:59], v[174:177], v[206:209], v[56:59]
	v_mfma_f32_16x16x32_bf16 v[96:99], v[124:127], v[186:189], v[88:91]
	v_mfma_f32_16x16x32_bf16 v[32:35], v[178:181], v[186:189], v[32:35]
	v_mfma_f32_16x16x32_bf16 v[36:39], v[124:127], v[194:197], v[36:39]
	v_mfma_f32_16x16x32_bf16 v[40:43], v[178:181], v[194:197], v[40:43]
	v_mfma_f32_16x16x32_bf16 v[44:47], v[124:127], v[202:205], v[44:47]
	v_mfma_f32_16x16x32_bf16 v[48:51], v[178:181], v[202:205], v[48:51]
	v_mfma_f32_16x16x32_bf16 v[52:55], v[124:127], v[210:213], v[52:55]
	v_mfma_f32_16x16x32_bf16 v[56:59], v[178:181], v[210:213], v[56:59]
	s_setprio 0
	s_barrier
	s_mov_b32 m0, s75
	v_lshl_add_u64 v[144:145], s[64:65], 0, v[132:133]
	s_add_u32 s52, s64, 0x10000
	ds_read_b128 v[88:91], v151 offset:16384
	ds_read_b128 v[92:95], v151 offset:17408
	ds_read_b128 v[182:185], v151 offset:18432
	ds_read_b128 v[186:189], v151 offset:19456
	ds_read_b128 v[190:193], v151 offset:20480
	ds_read_b128 v[194:197], v151 offset:21504
	ds_read_b128 v[198:201], v151 offset:22528
	ds_read_b128 v[202:205], v151 offset:23552
	global_load_lds_dwordx4 v[144:145], off
	v_lshl_add_u64 v[248:249], s[64:65], 0, v[128:129]
	s_mov_b32 m0, s76
	s_addc_u32 s53, s65, 0
	global_load_lds_dwordx4 v[248:249], off
	v_lshl_add_u64 v[206:207], s[52:53], 0, v[132:133]
	s_mov_b32 m0, s77
	v_lshl_add_u64 v[250:251], s[66:67], 0, v[134:135]
	global_load_lds_dwordx4 v[206:207], off
	v_lshl_add_u64 v[206:207], s[52:53], 0, v[128:129]
	s_mov_b32 m0, s80
	v_lshl_add_u64 v[252:253], s[66:67], 0, v[130:131]
	global_load_lds_dwordx4 v[206:207], off
	s_mov_b32 m0, s43
	s_nop 0
	global_load_lds_dwordx4 v[250:251], off
	s_mov_b32 m0, s61
	s_nop 0
	global_load_lds_dwordx4 v[252:253], off
	s_waitcnt vmcnt(8)
	s_waitcnt lgkmcnt(0)
	s_barrier
	s_setprio 1
	s_waitcnt lgkmcnt(0)
	v_mfma_f32_16x16x32_bf16 v[0:3], v[104:107], v[198:201], v[0:3]
	v_mfma_f32_16x16x32_bf16 v[4:7], v[112:115], v[198:201], v[4:7]
	v_mfma_f32_16x16x32_bf16 v[140:143], v[104:107], v[88:91], v[140:143]
	v_mfma_f32_16x16x32_bf16 v[154:157], v[112:115], v[88:91], v[154:157]
	v_mfma_f32_16x16x32_bf16 v[158:161], v[104:107], v[182:185], v[158:161]
	v_mfma_f32_16x16x32_bf16 v[162:165], v[112:115], v[182:185], v[162:165]
	v_mfma_f32_16x16x32_bf16 v[166:169], v[104:107], v[190:193], v[166:169]
	v_mfma_f32_16x16x32_bf16 v[170:173], v[112:115], v[190:193], v[170:173]
	v_mfma_f32_16x16x32_bf16 v[0:3], v[108:111], v[202:205], v[0:3]
	v_mfma_f32_16x16x32_bf16 v[4:7], v[116:119], v[202:205], v[4:7]
	v_mfma_f32_16x16x32_bf16 v[140:143], v[108:111], v[92:95], v[140:143]
	v_mfma_f32_16x16x32_bf16 v[154:157], v[116:119], v[92:95], v[154:157]
	v_mfma_f32_16x16x32_bf16 v[158:161], v[108:111], v[186:189], v[158:161]
	v_mfma_f32_16x16x32_bf16 v[162:165], v[116:119], v[186:189], v[162:165]
	v_mfma_f32_16x16x32_bf16 v[166:169], v[108:111], v[194:197], v[166:169]
	v_mfma_f32_16x16x32_bf16 v[170:173], v[116:119], v[194:197], v[170:173]
	s_setprio 0
	s_setprio 1
	v_mfma_f32_16x16x32_bf16 v[8:11], v[120:123], v[88:91], v[8:11]
	v_mfma_f32_16x16x32_bf16 v[206:209], v[124:127], v[92:95], v[8:11]
	v_mfma_f32_16x16x32_bf16 v[8:11], v[174:177], v[88:91], v[12:15]
	v_mfma_f32_16x16x32_bf16 v[210:213], v[178:181], v[92:95], v[8:11]
	v_mfma_f32_16x16x32_bf16 v[8:11], v[120:123], v[182:185], v[24:27]
	v_mfma_f32_16x16x32_bf16 v[222:225], v[124:127], v[186:189], v[8:11]
	v_mfma_f32_16x16x32_bf16 v[8:11], v[174:177], v[182:185], v[28:31]
	v_mfma_f32_16x16x32_bf16 v[182:185], v[178:181], v[186:189], v[8:11]
	v_mfma_f32_16x16x32_bf16 v[8:11], v[120:123], v[190:193], v[60:63]
	v_mfma_f32_16x16x32_bf16 v[186:189], v[124:127], v[194:197], v[8:11]
	v_mfma_f32_16x16x32_bf16 v[8:11], v[174:177], v[190:193], v[100:103]
	v_mfma_f32_16x16x32_bf16 v[190:193], v[178:181], v[194:197], v[8:11]
	v_mfma_f32_16x16x32_bf16 v[8:11], v[120:123], v[198:201], v[16:19]
	v_mfma_f32_16x16x32_bf16 v[194:197], v[124:127], v[202:205], v[8:11]
	v_mfma_f32_16x16x32_bf16 v[8:11], v[174:177], v[198:201], v[20:23]
	v_mfma_f32_16x16x32_bf16 v[174:177], v[178:181], v[202:205], v[8:11]
	s_setprio 0
	s_barrier
; #define PG8_STAGE(bufoff, gbase, voff) do { _Pragma("unroll") for (int _i = 0; _i < 2; ++_i) \
;         __builtin_amdgcn_global_load_lds((const unsigned*)((const char*)(gbase) + (voff)[_i]), (PG8_LAS unsigned*)(lds + (bufoff) + ldsw + _i * 8192), 16, 0, 0); } while (0)
; #define PG8_LDA(dst, b, h) do { _Pragma("unroll") for (int m = 0; m < 4; ++m) _Pragma("unroll") for (int k = 0; k < 2; ++k) dst[m][k] = *(const PG8_LAS bf16x8*)(lds + PG8_SA(b, h) + aoff + m * 2048 + k * 1024); } while (0)
; #define PG8_LDB(dst, b, h) do { _Pragma("unroll") for (int n = 0; n < 2; ++n) _Pragma("unroll") for (int k = 0; k < 2; ++k) dst[n][k] = *(const PG8_LAS bf16x8*)(lds + PG8_SB(b, h) + boff + n * 2048 + k * 1024); } while (0)
; #define PG8_MMA(ai, bj, At, Bt) do { __builtin_amdgcn_s_setprio(1); _Pragma("unroll") for (int m = 0; m < 4; ++m) _Pragma("unroll") for (int n = 0; n < 2; ++n) _Pragma("unroll") for (int k = 0; k < 2; ++k) \
;         acc[ai][bj][m][n] = __builtin_amdgcn_mfma_f32_16x16x32_bf16(Bt[n][k], At[m][k], acc[ai][bj][m][n], 0, 0, 0); __builtin_amdgcn_s_setprio(0); } while (0)
; #define PG8_WAIT_V(n) asm volatile("s_waitcnt vmcnt(" #n ")" ::: "memory")
; #define PG8_WAIT_L(n) asm volatile("s_waitcnt lgkmcnt(" #n ")" ::: "memory")
; #define PG8_BAR __builtin_amdgcn_s_barrier()
; #define PG8_SCHED __builtin_amdgcn_sched_barrier(0)
; template <class Epi, class Sched, bool ALIGN_EPI = false, bool SP2 = false>
; __device__ __forceinline__ void gemm_phase(PG8_LAS unsigned char* lds, const Gemm g, const Sched& S, const Epi& E) {
;     ...
;             PG8_LDB(B0, 1, 0); PG8_LDB(B1, 1, 1); PG8_SCHED; PG8_LDA(At, 1, 0); PG8_STAGE(PG8_SA(0, 1), a2 + hstep, voffA);
;             PG8_WAIT_V(8); PG8_WAIT_L(0); PG8_BAR; PG8_MMA(0, 0, At, B0); PG8_MMA(0, 1, At, B1); PG8_BAR; PG8_SCHED;
;             PG8_LDA(At, 1, 1); PG8_STAGE(PG8_SB(1, 0), b3, voffB); PG8_STAGE(PG8_SB(1, 1), b3 + hstep, voffB); PG8_STAGE(PG8_SA(1, 0), a3, voffA);
;             PG8_WAIT_V(8); PG8_WAIT_L(0); PG8_BAR; PG8_MMA(1, 0, At, B0); PG8_MMA(1, 1, At, B1); PG8_BAR; PG8_SCHED;
;     ...
;         if constexpr (ALIGN_EPI) { if (wr == 0) PG8_BAR; }
	s_nop 4
	ds_read_b128 v[8:11], v152
	ds_read_b128 v[12:15], v152 offset:1024
	ds_read_b128 v[16:19], v152 offset:2048
	ds_read_b128 v[20:23], v152 offset:3072
	ds_read_b128 v[178:181], v153
	ds_read_b128 v[198:201], v153 offset:1024
	ds_read_b128 v[202:205], v153 offset:2048
	ds_read_b128 v[228:231], v153 offset:3072
	s_add_u32 s52, s66, 0x10000
	s_addc_u32 s53, s67, 0
	s_mov_b32 m0, s68
	v_lshl_add_u64 v[88:89], s[52:53], 0, v[134:135]
	ds_read_b128 v[24:27], v151 offset:32768
	ds_read_b128 v[28:31], v151 offset:33792
	ds_read_b128 v[60:63], v151 offset:34816
	ds_read_b128 v[100:103], v151 offset:35840
	ds_read_b128 v[232:235], v151 offset:36864
	ds_read_b128 v[236:239], v151 offset:37888
	ds_read_b128 v[240:243], v151 offset:38912
	ds_read_b128 v[244:247], v151 offset:39936
	global_load_lds_dwordx4 v[88:89], off
	v_lshl_add_u64 v[88:89], s[52:53], 0, v[130:131]
	s_mov_b32 m0, s69
	s_nop 0
	global_load_lds_dwordx4 v[88:89], off
	s_waitcnt vmcnt(8)
	s_waitcnt lgkmcnt(0)
	s_barrier
	s_setprio 1
	s_waitcnt lgkmcnt(0)
	v_mfma_f32_16x16x32_bf16 v[64:67], v[8:11], v[24:27], v[64:67]
	v_mfma_f32_16x16x32_bf16 v[124:127], v[12:15], v[28:31], v[64:67]
	v_mfma_f32_16x16x32_bf16 v[64:67], v[16:19], v[24:27], v[68:71]
	v_mfma_f32_16x16x32_bf16 v[120:123], v[20:23], v[28:31], v[64:67]
	v_mfma_f32_16x16x32_bf16 v[64:67], v[8:11], v[60:63], v[72:75]
	v_mfma_f32_16x16x32_bf16 v[108:111], v[12:15], v[100:103], v[64:67]
	v_mfma_f32_16x16x32_bf16 v[64:67], v[16:19], v[60:63], v[76:79]
	v_mfma_f32_16x16x32_bf16 v[104:107], v[20:23], v[100:103], v[64:67]
	v_mfma_f32_16x16x32_bf16 v[64:67], v[8:11], v[232:235], v[80:83]
	v_mfma_f32_16x16x32_bf16 v[92:95], v[12:15], v[236:239], v[64:67]
	v_mfma_f32_16x16x32_bf16 v[64:67], v[16:19], v[232:235], v[84:87]
	v_mfma_f32_16x16x32_bf16 v[88:91], v[20:23], v[236:239], v[64:67]
	v_mfma_f32_16x16x32_bf16 v[64:67], v[8:11], v[240:243], v[214:217]
	v_mfma_f32_16x16x32_bf16 v[76:79], v[12:15], v[244:247], v[64:67]
	v_mfma_f32_16x16x32_bf16 v[64:67], v[16:19], v[240:243], v[218:221]
	v_mfma_f32_16x16x32_bf16 v[72:75], v[20:23], v[244:247], v[64:67]
	s_setprio 0
	s_setprio 1
	v_mfma_f32_16x16x32_bf16 v[64:67], v[178:181], v[24:27], v[96:99]
	v_mfma_f32_16x16x32_bf16 v[24:27], v[202:205], v[24:27], v[32:35]
	v_mfma_f32_16x16x32_bf16 v[116:119], v[228:231], v[28:31], v[24:27]
	v_mfma_f32_16x16x32_bf16 v[24:27], v[178:181], v[60:63], v[36:39]
	v_mfma_f32_16x16x32_bf16 v[96:99], v[198:201], v[100:103], v[24:27]
	v_mfma_f32_16x16x32_bf16 v[24:27], v[202:205], v[60:63], v[40:43]
	v_mfma_f32_16x16x32_bf16 v[100:103], v[228:231], v[100:103], v[24:27]
	v_mfma_f32_16x16x32_bf16 v[24:27], v[178:181], v[232:235], v[44:47]
	v_mfma_f32_16x16x32_bf16 v[80:83], v[198:201], v[236:239], v[24:27]
	v_mfma_f32_16x16x32_bf16 v[24:27], v[202:205], v[232:235], v[48:51]
	v_mfma_f32_16x16x32_bf16 v[84:87], v[228:231], v[236:239], v[24:27]
	v_mfma_f32_16x16x32_bf16 v[24:27], v[178:181], v[240:243], v[52:55]
	v_mfma_f32_16x16x32_bf16 v[112:115], v[198:201], v[28:31], v[64:67]
	v_mfma_f32_16x16x32_bf16 v[64:67], v[198:201], v[244:247], v[24:27]
	v_mfma_f32_16x16x32_bf16 v[24:27], v[202:205], v[240:243], v[56:59]
	v_mfma_f32_16x16x32_bf16 v[68:71], v[228:231], v[244:247], v[24:27]
	s_setprio 0
	s_barrier
	s_mov_b32 m0, s83
	s_nop 3
	v_lshl_add_u64 v[24:25], v[144:145], 0, s[14:15]
	s_add_u32 s52, s64, 0x10080
	ds_read_b128 v[32:35], v151 offset:49152
	ds_read_b128 v[36:39], v151 offset:50176
	ds_read_b128 v[214:217], v151 offset:51200
	ds_read_b128 v[218:221], v151 offset:52224
	ds_read_b128 v[232:235], v151 offset:53248
	ds_read_b128 v[236:239], v151 offset:54272
	ds_read_b128 v[240:243], v151 offset:55296
	ds_read_b128 v[244:247], v151 offset:56320
	global_load_lds_dwordx4 v[24:25], off
	v_lshl_add_u64 v[24:25], v[248:249], 0, s[14:15]
	s_mov_b32 m0, s35
	s_addc_u32 s53, s65, 0
	global_load_lds_dwordx4 v[24:25], off
	v_lshl_add_u64 v[24:25], s[52:53], 0, v[132:133]
	s_mov_b32 m0, s37
	s_nop 0
	global_load_lds_dwordx4 v[24:25], off
	v_lshl_add_u64 v[24:25], s[52:53], 0, v[128:129]
	s_mov_b32 m0, s62
	s_nop 0
	global_load_lds_dwordx4 v[24:25], off
	v_lshl_add_u64 v[24:25], v[250:251], 0, s[14:15]
	s_mov_b32 m0, s70
	s_nop 0
	global_load_lds_dwordx4 v[24:25], off
	v_lshl_add_u64 v[24:25], v[252:253], 0, s[14:15]
	s_mov_b32 m0, s71
	s_nop 0
	global_load_lds_dwordx4 v[24:25], off
	s_waitcnt vmcnt(8)
	s_waitcnt lgkmcnt(0)
	s_barrier
	s_setprio 1
	s_waitcnt lgkmcnt(0)
	v_mfma_f32_16x16x32_bf16 v[24:27], v[8:11], v[32:35], v[140:143]
	v_mfma_f32_16x16x32_bf16 v[60:63], v[12:15], v[36:39], v[24:27]
	v_mfma_f32_16x16x32_bf16 v[24:27], v[16:19], v[32:35], v[154:157]
	v_mfma_f32_16x16x32_bf16 v[56:59], v[20:23], v[36:39], v[24:27]
	v_mfma_f32_16x16x32_bf16 v[24:27], v[8:11], v[214:217], v[158:161]
	v_mfma_f32_16x16x32_bf16 v[44:47], v[12:15], v[218:221], v[24:27]
	v_mfma_f32_16x16x32_bf16 v[24:27], v[16:19], v[214:217], v[162:165]
	v_mfma_f32_16x16x32_bf16 v[40:43], v[20:23], v[218:221], v[24:27]
	v_mfma_f32_16x16x32_bf16 v[24:27], v[8:11], v[232:235], v[166:169]
	v_mfma_f32_16x16x32_bf16 v[0:3], v[8:11], v[240:243], v[0:3]
	v_mfma_f32_16x16x32_bf16 v[28:31], v[12:15], v[236:239], v[24:27]
	v_mfma_f32_16x16x32_bf16 v[24:27], v[16:19], v[232:235], v[170:173]
	v_mfma_f32_16x16x32_bf16 v[12:15], v[12:15], v[244:247], v[0:3]
	v_mfma_f32_16x16x32_bf16 v[0:3], v[16:19], v[240:243], v[4:7]
	v_mfma_f32_16x16x32_bf16 v[24:27], v[20:23], v[236:239], v[24:27]
	v_mfma_f32_16x16x32_bf16 v[8:11], v[20:23], v[244:247], v[0:3]
	s_setprio 0
	s_setprio 1
	v_mfma_f32_16x16x32_bf16 v[0:3], v[178:181], v[32:35], v[206:209]
	v_mfma_f32_16x16x32_bf16 v[48:51], v[198:201], v[36:39], v[0:3]
	v_mfma_f32_16x16x32_bf16 v[0:3], v[202:205], v[32:35], v[210:213]
	v_mfma_f32_16x16x32_bf16 v[52:55], v[228:231], v[36:39], v[0:3]
	v_mfma_f32_16x16x32_bf16 v[0:3], v[178:181], v[214:217], v[222:225]
	v_mfma_f32_16x16x32_bf16 v[32:35], v[198:201], v[218:221], v[0:3]
	v_mfma_f32_16x16x32_bf16 v[0:3], v[202:205], v[214:217], v[182:185]
	v_mfma_f32_16x16x32_bf16 v[36:39], v[228:231], v[218:221], v[0:3]
	v_mfma_f32_16x16x32_bf16 v[0:3], v[178:181], v[232:235], v[186:189]
	v_mfma_f32_16x16x32_bf16 v[16:19], v[198:201], v[236:239], v[0:3]
	v_mfma_f32_16x16x32_bf16 v[0:3], v[202:205], v[232:235], v[190:193]
	v_mfma_f32_16x16x32_bf16 v[20:23], v[228:231], v[236:239], v[0:3]
	v_mfma_f32_16x16x32_bf16 v[0:3], v[178:181], v[240:243], v[194:197]
	v_mfma_f32_16x16x32_bf16 v[4:7], v[198:201], v[244:247], v[0:3]
	v_mfma_f32_16x16x32_bf16 v[0:3], v[202:205], v[240:243], v[174:177]
	v_mfma_f32_16x16x32_bf16 v[0:3], v[228:231], v[244:247], v[0:3]
	s_setprio 0
	s_barrier
	s_andn2_b64 vcc, exec, s[16:17]
	s_cbranch_vccnz .LBB0_1356
	s_barrier

; #define PG8_STAGE(bufoff, gbase, voff) do { _Pragma("unroll") for (int _i = 0; _i < 2; ++_i) \
;         __builtin_amdgcn_global_load_lds((const unsigned*)((const char*)(gbase) + (voff)[_i]), (PG8_LAS unsigned*)(lds + (bufoff) + ldsw + _i * 8192), 16, 0, 0); } while (0)
; #define PG8_WAIT_V(n) asm volatile("s_waitcnt vmcnt(" #n ")" ::: "memory")
; #define PG8_BAR __builtin_amdgcn_s_barrier()
; template <class Epi, class Sched, bool ALIGN_EPI = false, bool SP2 = false>
; __device__ __forceinline__ void gemm_phase(PG8_LAS unsigned char* lds, const Gemm g, const Sched& S, const Epi& E) {
;     ...
;     const int tid = tid_, wid = __builtin_amdgcn_readfirstlane(tid >> 6), lane = tid & 63, wr = wid >> 2, wc = wid & 3, fr = lane & 15, fq = lane >> 4;
;     const int K = g.K, nt = K / BK;
;     unsigned voffA[2], voffB[2];
; #pragma unroll
;     for (int i = 0; i < 2; ++i) { int R, C; stage_rc(tid * 16 + i * 8192, R, C); const int Rb = Epi::PERM ? ((R & ~31) + perm32(R & 31)) : R;
;         voffA[i] = (unsigned)(R * K + C) * 2u; voffB[i] = (unsigned)(Rb * K + C) * 2u; }
;     const size_t kstep = (size_t)(BK * 2);
;     const size_t hstep = (size_t)HALF * K * 2;
;     const size_t tstep = 2 * hstep;
;     const unsigned ldsw = (unsigned)wid * 1024u;
;     const int aoff = lds_byte(wr * 64 + fr, fq * 8), boff = lds_byte(wc * 32 + fr, fq * 8);
;     ...
;         PG8_STAGE(PG8_SB(0, 0), cB, voffB); PG8_STAGE(PG8_SB(0, 1), cB + hstep, voffB); PG8_STAGE(PG8_SA(0, 0), cA, voffA); PG8_STAGE(PG8_SA(0, 1), cA + hstep, voffA);
;         if (wr == 1) PG8_BAR;
;         PG8_WAIT_V(2); PG8_BAR;
;         PG8_STAGE(PG8_SB(1, 0), cB + kstep, voffB); PG8_STAGE(PG8_SA(1, 0), cA + kstep, voffA); PG8_STAGE(PG8_SB(1, 1), cB + hstep + kstep, voffB);
;         PG8_WAIT_V(6); PG8_BAR;
.LBB0_1417:
	s_mov_b64 s[18:19], 0x80
	s_and_b32 s52, s5, 3
	s_add_i32 m0, s42, 0x18000
	v_lshl_add_u64 v[6:7], v[6:7], 0, s[18:19]
	s_lshl_b32 s5, s6, 13
	s_lshl_b32 s7, s52, 12
	s_waitcnt vmcnt(2)
	s_barrier
	global_load_lds_dwordx4 v[6:7], off
	v_lshl_add_u64 v[4:5], v[4:5], 0, s[18:19]
	s_add_i32 m0, s42, 0x1a000
	s_add_i32 s53, s42, 0x8000
	s_add_i32 s60, s42, 0xa000
	global_load_lds_dwordx4 v[4:5], off
	v_lshl_add_u64 v[0:1], v[0:1], 0, s[18:19]
	s_mov_b32 m0, s53
	s_add_u32 s20, s36, 0x40080
	global_load_lds_dwordx4 v[0:1], off
	v_lshl_add_u64 v[0:1], v[2:3], 0, s[18:19]
	s_mov_b32 m0, s60
	s_addc_u32 s21, s37, 0
	global_load_lds_dwordx4 v[0:1], off
	s_add_i32 m0, s42, 0x1c000
	v_lshl_add_u64 v[0:1], s[20:21], 0, v[146:147]
	global_load_lds_dwordx4 v[0:1], off
	v_lshl_add_u64 v[0:1], s[20:21], 0, v[150:151]
	s_add_i32 m0, s42, 0x1e000
	s_cmpk_lt_u32 s4, 0x100
	global_load_lds_dwordx4 v[0:1], off
	v_bfe_u32 v1, v8, 4, 2
	v_and_b32_e32 v0, 15, v8
	v_lshlrev_b32_e32 v3, 4, v1
	v_lshl_or_b32 v170, s6, 6, v0
	v_lshl_or_b32 v0, v0, 6, v3
	v_lshlrev_b32_e32 v3, 2, v8
	v_and_b32_e32 v3, 32, v3
	v_bitop3_b32 v4, v0, s5, v3 bitop3:0xde
	v_bitop3_b32 v171, v0, s7, v3 bitop3:0xde
	v_lshlrev_b32_e32 v0, 14, v9
	v_and_b32_e32 v0, 0xffff8000, v0
	v_lshlrev_b32_e32 v2, 3, v1
	v_cmp_eq_u32_e64 s[4:5], 0, v1
	v_lshl_add_u32 v0, v10, 11, v0
	v_and_b32_e32 v1, 1, v9
	v_lshl_or_b32 v0, v1, 6, v0
	v_lshl_add_u32 v154, v11, 1, v0
	v_lshlrev_b32_e32 v0, 14, v12
	v_and_b32_e32 v0, 0xffff8000, v0
	s_waitcnt vmcnt(6)
	v_lshl_add_u32 v0, v13, 11, v0
	v_and_b32_e32 v1, 1, v12
	s_cselect_b64 s[20:21], -1, 0
	v_lshl_or_b32 v0, v1, 6, v0
	s_add_i32 s64, 0, 0x10000
	s_add_i32 s65, 0, 0x14000
	v_lshl_or_b32 v172, s52, 5, v2
	s_ashr_i32 s61, s3, 31
	s_ashr_i32 s62, s2, 31
	v_mov_b32_e32 v155, v153
	v_lshl_add_u32 v156, v14, 1, v0
	v_mov_b32_e32 v157, v153
	v_mov_b64_e32 v[158:159], 0x410
	v_mov_b64_e32 v[160:161], 0x40f
	s_movk_i32 s63, 0x83
	v_add_u32_e32 v173, s64, v171
	v_add_u32_e32 v174, s65, v171
	v_add_u32_e32 v175, 0, v4
	s_mov_b32 s66, 0xffff
	v_mbcnt_hi_u32_b32 v176, -1, v227
	s_mov_b32 s67, 0xff7f
	s_mov_b32 s68, 0xff6f
	s_mov_b32 s69, 0xff5f
	s_mov_b32 s70, 0xff4f
	s_mov_b32 s71, 0
	s_barrier
	s_mov_b32 s99, 0
	s_branch .LBB0_1420

; #define PG8_BAR __builtin_amdgcn_s_barrier()
; template <class Epi, class Sched, bool ALIGN_EPI = false, bool SP2 = false>
; __device__ __forceinline__ void gemm_phase(PG8_LAS unsigned char* lds, const Gemm g, const Sched& S, const Epi& E) {
;     ...
;         if (!has_next) break;
; #pragma unroll
;         for (int a = 0; a < 2; ++a)
; #pragma unroll
;             for (int b = 0; b < 2; ++b)
; #pragma unroll
;                 for (int m = 0; m < 4; ++m)
; #pragma unroll
;                     for (int n = 0; n < 2; ++n) acc[a][b][m][n] = (f32x4){0.f, 0.f, 0.f, 0.f};
;         cur = nxt; cA = nA; cB = nB; ++ui;
;         if constexpr (ALIGN_EPI) { if (wr == 1) PG8_BAR; }
.LBB0_1419:
	s_mov_b32 s99, 1
	s_andn2_b64 vcc, exec, s[6:7]
	s_mov_b32 s14, s22
	s_mov_b32 s30, s24
	s_mov_b64 s[36:37], s[28:29]
	s_mov_b64 s[34:35], s[26:27]
	s_cbranch_vccz .LBB0_1477

; #define PG8_STAGE(bufoff, gbase, voff) do { _Pragma("unroll") for (int _i = 0; _i < 2; ++_i) \
;         __builtin_amdgcn_global_load_lds((const unsigned*)((const char*)(gbase) + (voff)[_i]), (PG8_LAS unsigned*)(lds + (bufoff) + ldsw + _i * 8192), 16, 0, 0); } while (0)
; #define PG8_LDA(dst, b, h) do { _Pragma("unroll") for (int m = 0; m < 4; ++m) _Pragma("unroll") for (int k = 0; k < 2; ++k) dst[m][k] = *(const PG8_LAS bf16x8*)(lds + PG8_SA(b, h) + aoff + m * 2048 + k * 1024); } while (0)
; #define PG8_LDB(dst, b, h) do { _Pragma("unroll") for (int n = 0; n < 2; ++n) _Pragma("unroll") for (int k = 0; k < 2; ++k) dst[n][k] = *(const PG8_LAS bf16x8*)(lds + PG8_SB(b, h) + boff + n * 2048 + k * 1024); } while (0)
; #define PG8_MMA(ai, bj, At, Bt) do { __builtin_amdgcn_s_setprio(1); _Pragma("unroll") for (int m = 0; m < 4; ++m) _Pragma("unroll") for (int n = 0; n < 2; ++n) _Pragma("unroll") for (int k = 0; k < 2; ++k) \
;         acc[ai][bj][m][n] = __builtin_amdgcn_mfma_f32_16x16x32_bf16(Bt[n][k], At[m][k], acc[ai][bj][m][n], 0, 0, 0); __builtin_amdgcn_s_setprio(0); } while (0)
; #define PG8_WAIT_V(n) asm volatile("s_waitcnt vmcnt(" #n ")" ::: "memory")
; #define PG8_WAIT_L(n) asm volatile("s_waitcnt lgkmcnt(" #n ")" ::: "memory")
; #define PG8_BAR __builtin_amdgcn_s_barrier()
; template <class Epi, class Sched, bool ALIGN_EPI = false, bool SP2 = false>
; __device__ __forceinline__ void gemm_phase(PG8_LAS unsigned char* lds, const Gemm g, const Sched& S, const Epi& E) {
;     ...
;         const bool has_next = S.next(ui + 1, nxt);
;         const char* nA = has_next ? (const char*)g.A + (size_t)nxt.pm * tstep : cA; const char* nB = has_next ? (const char*)g.Bt + (size_t)nxt.pn * tstep : cB;
;         for (int t = 0; t < nt; t += 2) {
;             const bool last = (t == nt - 2);
;             const char* a1 = cA + (size_t)(t + 1) * kstep;
;             const char* a2 = last ? nA : cA + (size_t)(t + 2) * kstep; const char* b2 = last ? nB : cB + (size_t)(t + 2) * kstep;
;             const char* a3 = a2 + kstep; const char* b3 = b2 + kstep;
;             if (last && has_next) S.a_ready(nxt);
;             if constexpr (SP2) {
;             PG8_LDB(B0, 0, 0); PG8_LDB(B1, 0, 1); PG8_SCHED; PG8_LDA(At, 0, 0); PG8_STAGE(PG8_SA(1, 1), a1 + hstep, voffA);
;             PG8_WAIT_V(8); PG8_WAIT_L(0); PG8_BAR; PG8_MMA(0, 0, At, B0); PG8_MMA(0, 1, At, B1); PG8_BAR; PG8_SCHED;
.LBB0_1423:
	ds_read_b128 v[56:59], v173
	ds_read_b128 v[60:63], v173 offset:1024
	ds_read_b128 v[72:75], v173 offset:2048
	ds_read_b128 v[76:79], v173 offset:3072
	ds_read_b128 v[162:165], v174
	ds_read_b128 v[166:169], v174 offset:1024
	ds_read_b128 v[178:181], v174 offset:2048
	ds_read_b128 v[182:185], v174 offset:3072
	s_add_u32 s36, s34, 0xfffc0080
	s_addc_u32 s37, s35, -1
	s_cmp_eq_u32 s75, 12
	s_cselect_b32 s39, s25, s37
	s_cselect_b32 s38, s31, s36
	s_cselect_b32 s37, s23, s74
	s_cselect_b32 s36, s72, s73
	v_lshl_add_u64 v[218:219], s[34:35], 0, v[154:155]
	s_add_i32 m0, s42, 0xc000
	ds_read_b128 v[186:189], v175
	ds_read_b128 v[190:193], v175 offset:1024
	ds_read_b128 v[194:197], v175 offset:2048
	ds_read_b128 v[198:201], v175 offset:3072
	ds_read_b128 v[202:205], v175 offset:4096
	ds_read_b128 v[206:209], v175 offset:5120
	ds_read_b128 v[210:213], v175 offset:6144
	ds_read_b128 v[214:217], v175 offset:7168
	global_load_lds_dwordx4 v[218:219], off
	v_lshl_add_u64 v[218:219], s[34:35], 0, v[156:157]
	s_add_i32 m0, s42, 0xe000
	s_nop 0
	global_load_lds_dwordx4 v[218:219], off
	s_cmp_eq_u32 s99, 1
	s_cbranch_scc1 .Lrw_P4_0
	s_waitcnt vmcnt(8)
	s_branch .Lrj_P4_0

; #define PG8_STAGE(bufoff, gbase, voff) do { _Pragma("unroll") for (int _i = 0; _i < 2; ++_i) \
;         __builtin_amdgcn_global_load_lds((const unsigned*)((const char*)(gbase) + (voff)[_i]), (PG8_LAS unsigned*)(lds + (bufoff) + ldsw + _i * 8192), 16, 0, 0); } while (0)
; #define PG8_LDA(dst, b, h) do { _Pragma("unroll") for (int m = 0; m < 4; ++m) _Pragma("unroll") for (int k = 0; k < 2; ++k) dst[m][k] = *(const PG8_LAS bf16x8*)(lds + PG8_SA(b, h) + aoff + m * 2048 + k * 1024); } while (0)
; #define PG8_MMA(ai, bj, At, Bt) do { __builtin_amdgcn_s_setprio(1); _Pragma("unroll") for (int m = 0; m < 4; ++m) _Pragma("unroll") for (int n = 0; n < 2; ++n) _Pragma("unroll") for (int k = 0; k < 2; ++k) \
;         acc[ai][bj][m][n] = __builtin_amdgcn_mfma_f32_16x16x32_bf16(Bt[n][k], At[m][k], acc[ai][bj][m][n], 0, 0, 0); __builtin_amdgcn_s_setprio(0); } while (0)
; #define PG8_WAIT_V(n) asm volatile("s_waitcnt vmcnt(" #n ")" ::: "memory")
; #define PG8_WAIT_L(n) asm volatile("s_waitcnt lgkmcnt(" #n ")" ::: "memory")
; #define PG8_BAR __builtin_amdgcn_s_barrier()
; #define PG8_SCHED __builtin_amdgcn_sched_barrier(0)
; template <class Epi, class Sched, bool ALIGN_EPI = false, bool SP2 = false>
; __device__ __forceinline__ void gemm_phase(PG8_LAS unsigned char* lds, const Gemm g, const Sched& S, const Epi& E) {
;     ...
;             PG8_WAIT_V(8); PG8_WAIT_L(0); PG8_BAR; PG8_MMA(0, 0, At, B0); PG8_MMA(0, 1, At, B1); PG8_BAR; PG8_SCHED;
;             PG8_LDA(At, 0, 1); PG8_STAGE(PG8_SB(0, 0), b2, voffB); PG8_STAGE(PG8_SB(0, 1), b2 + hstep, voffB); PG8_STAGE(PG8_SA(0, 0), a2, voffA);
;             PG8_WAIT_V(8); PG8_WAIT_L(0); PG8_BAR; PG8_MMA(1, 0, At, B0); PG8_MMA(1, 1, At, B1); PG8_BAR; PG8_SCHED;
.Lrj_P4_0:
	s_waitcnt lgkmcnt(0)
	s_barrier
	s_setprio 1
	s_waitcnt lgkmcnt(0)
	v_mfma_f32_16x16x32_bf16 v[140:143], v[56:59], v[186:189], v[140:143]
	v_mfma_f32_16x16x32_bf16 v[136:139], v[72:75], v[186:189], v[136:139]
	v_mfma_f32_16x16x32_bf16 v[124:127], v[56:59], v[194:197], v[124:127]
	v_mfma_f32_16x16x32_bf16 v[120:123], v[72:75], v[194:197], v[120:123]
	v_mfma_f32_16x16x32_bf16 v[108:111], v[56:59], v[202:205], v[108:111]
	v_mfma_f32_16x16x32_bf16 v[104:107], v[72:75], v[202:205], v[104:107]
	v_mfma_f32_16x16x32_bf16 v[92:95], v[56:59], v[210:213], v[92:95]
	v_mfma_f32_16x16x32_bf16 v[88:91], v[72:75], v[210:213], v[88:91]
	v_mfma_f32_16x16x32_bf16 v[140:143], v[60:63], v[190:193], v[140:143]
	v_mfma_f32_16x16x32_bf16 v[136:139], v[76:79], v[190:193], v[136:139]
	v_mfma_f32_16x16x32_bf16 v[124:127], v[60:63], v[198:201], v[124:127]
	v_mfma_f32_16x16x32_bf16 v[120:123], v[76:79], v[198:201], v[120:123]
	v_mfma_f32_16x16x32_bf16 v[108:111], v[60:63], v[206:209], v[108:111]
	v_mfma_f32_16x16x32_bf16 v[104:107], v[76:79], v[206:209], v[104:107]
	v_mfma_f32_16x16x32_bf16 v[92:95], v[60:63], v[214:217], v[92:95]
	v_mfma_f32_16x16x32_bf16 v[88:91], v[76:79], v[214:217], v[88:91]
	s_setprio 0
	s_setprio 1
	v_mfma_f32_16x16x32_bf16 v[132:135], v[162:165], v[186:189], v[132:135]
	v_mfma_f32_16x16x32_bf16 v[128:131], v[178:181], v[186:189], v[128:131]
	v_mfma_f32_16x16x32_bf16 v[116:119], v[162:165], v[194:197], v[116:119]
	v_mfma_f32_16x16x32_bf16 v[112:115], v[178:181], v[194:197], v[112:115]
	v_mfma_f32_16x16x32_bf16 v[100:103], v[162:165], v[202:205], v[100:103]
	v_mfma_f32_16x16x32_bf16 v[96:99], v[178:181], v[202:205], v[96:99]
	v_mfma_f32_16x16x32_bf16 v[84:87], v[162:165], v[210:213], v[84:87]
	v_mfma_f32_16x16x32_bf16 v[80:83], v[178:181], v[210:213], v[80:83]
	v_mfma_f32_16x16x32_bf16 v[132:135], v[166:169], v[190:193], v[132:135]
	v_mfma_f32_16x16x32_bf16 v[128:131], v[182:185], v[190:193], v[128:131]
	v_mfma_f32_16x16x32_bf16 v[116:119], v[166:169], v[198:201], v[116:119]
	v_mfma_f32_16x16x32_bf16 v[112:115], v[182:185], v[198:201], v[112:115]
	v_mfma_f32_16x16x32_bf16 v[100:103], v[166:169], v[206:209], v[100:103]
	v_mfma_f32_16x16x32_bf16 v[96:99], v[182:185], v[206:209], v[96:99]
	v_mfma_f32_16x16x32_bf16 v[84:87], v[166:169], v[214:217], v[84:87]
	v_mfma_f32_16x16x32_bf16 v[80:83], v[182:185], v[214:217], v[80:83]
	s_setprio 0
	s_barrier
	s_add_i32 s76, s64, s41
	v_lshl_add_u64 v[218:219], s[36:37], 0, v[146:147]
	s_mov_b32 m0, s76
	ds_read_b128 v[186:189], v175 offset:16384
	ds_read_b128 v[190:193], v175 offset:17408
	ds_read_b128 v[194:197], v175 offset:18432
	ds_read_b128 v[198:201], v175 offset:19456
	ds_read_b128 v[202:205], v175 offset:20480
	ds_read_b128 v[206:209], v175 offset:21504
	ds_read_b128 v[210:213], v175 offset:22528
	ds_read_b128 v[214:217], v175 offset:23552
	global_load_lds_dwordx4 v[218:219], off
	s_add_i32 m0, s76, 0x2000
	s_add_u32 s76, s36, 0x40000
	v_lshl_add_u64 v[220:221], s[36:37], 0, v[150:151]
	s_addc_u32 s77, s37, 0
	s_add_i32 s80, s65, s41
	global_load_lds_dwordx4 v[220:221], off
	v_lshl_add_u64 v[222:223], s[76:77], 0, v[146:147]
	s_mov_b32 m0, s80
	v_lshl_add_u64 v[224:225], s[38:39], 0, v[148:149]
	global_load_lds_dwordx4 v[222:223], off
	v_lshl_add_u64 v[222:223], s[76:77], 0, v[150:151]
	s_add_i32 m0, s80, 0x2000
	s_nop 0
	global_load_lds_dwordx4 v[222:223], off
	v_lshl_add_u64 v[222:223], s[38:39], 0, v[144:145]
	s_mov_b32 m0, s42
	s_nop 0
	global_load_lds_dwordx4 v[222:223], off
	s_mov_b32 m0, s43
	s_nop 0
	global_load_lds_dwordx4 v[224:225], off
	s_cmp_eq_u32 s99, 1
	s_cbranch_scc1 .Lrw_P4_1
	s_waitcnt vmcnt(8)
	s_branch .Lrj_P4_1

; #define PG8_STAGE(bufoff, gbase, voff) do { _Pragma("unroll") for (int _i = 0; _i < 2; ++_i) \
;         __builtin_amdgcn_global_load_lds((const unsigned*)((const char*)(gbase) + (voff)[_i]), (PG8_LAS unsigned*)(lds + (bufoff) + ldsw + _i * 8192), 16, 0, 0); } while (0)
; #define PG8_LDA(dst, b, h) do { _Pragma("unroll") for (int m = 0; m < 4; ++m) _Pragma("unroll") for (int k = 0; k < 2; ++k) dst[m][k] = *(const PG8_LAS bf16x8*)(lds + PG8_SA(b, h) + aoff + m * 2048 + k * 1024); } while (0)
; #define PG8_LDB(dst, b, h) do { _Pragma("unroll") for (int n = 0; n < 2; ++n) _Pragma("unroll") for (int k = 0; k < 2; ++k) dst[n][k] = *(const PG8_LAS bf16x8*)(lds + PG8_SB(b, h) + boff + n * 2048 + k * 1024); } while (0)
; #define PG8_MMA(ai, bj, At, Bt) do { __builtin_amdgcn_s_setprio(1); _Pragma("unroll") for (int m = 0; m < 4; ++m) _Pragma("unroll") for (int n = 0; n < 2; ++n) _Pragma("unroll") for (int k = 0; k < 2; ++k) \
;         acc[ai][bj][m][n] = __builtin_amdgcn_mfma_f32_16x16x32_bf16(Bt[n][k], At[m][k], acc[ai][bj][m][n], 0, 0, 0); __builtin_amdgcn_s_setprio(0); } while (0)
; #define PG8_WAIT_V(n) asm volatile("s_waitcnt vmcnt(" #n ")" ::: "memory")
; #define PG8_WAIT_L(n) asm volatile("s_waitcnt lgkmcnt(" #n ")" ::: "memory")
; #define PG8_BAR __builtin_amdgcn_s_barrier()
; #define PG8_SCHED __builtin_amdgcn_sched_barrier(0)
; template <class Epi, class Sched, bool ALIGN_EPI = false, bool SP2 = false>
; __device__ __forceinline__ void gemm_phase(PG8_LAS unsigned char* lds, const Gemm g, const Sched& S, const Epi& E) {
;     ...
;             PG8_WAIT_V(8); PG8_WAIT_L(0); PG8_BAR; PG8_MMA(1, 0, At, B0); PG8_MMA(1, 1, At, B1); PG8_BAR; PG8_SCHED;
;             PG8_LDB(B0, 1, 0); PG8_LDB(B1, 1, 1); PG8_SCHED; PG8_LDA(At, 1, 0); PG8_STAGE(PG8_SA(0, 1), a2 + hstep, voffA);
;             PG8_WAIT_V(8); PG8_WAIT_L(0); PG8_BAR; PG8_MMA(0, 0, At, B0); PG8_MMA(0, 1, At, B1); PG8_BAR; PG8_SCHED;
.Lrj_P4_1:
	s_waitcnt lgkmcnt(0)
	s_barrier
	s_setprio 1
	s_waitcnt lgkmcnt(0)
	v_mfma_f32_16x16x32_bf16 v[68:71], v[56:59], v[186:189], v[68:71]
	v_mfma_f32_16x16x32_bf16 v[64:67], v[72:75], v[186:189], v[64:67]
	v_mfma_f32_16x16x32_bf16 v[44:47], v[56:59], v[194:197], v[44:47]
	v_mfma_f32_16x16x32_bf16 v[40:43], v[72:75], v[194:197], v[40:43]
	v_mfma_f32_16x16x32_bf16 v[28:31], v[56:59], v[202:205], v[28:31]
	v_mfma_f32_16x16x32_bf16 v[24:27], v[72:75], v[202:205], v[24:27]
	v_mfma_f32_16x16x32_bf16 v[12:15], v[56:59], v[210:213], v[12:15]
	v_mfma_f32_16x16x32_bf16 v[8:11], v[72:75], v[210:213], v[8:11]
	v_mfma_f32_16x16x32_bf16 v[68:71], v[60:63], v[190:193], v[68:71]
	v_mfma_f32_16x16x32_bf16 v[64:67], v[76:79], v[190:193], v[64:67]
	v_mfma_f32_16x16x32_bf16 v[44:47], v[60:63], v[198:201], v[44:47]
	v_mfma_f32_16x16x32_bf16 v[40:43], v[76:79], v[198:201], v[40:43]
	v_mfma_f32_16x16x32_bf16 v[28:31], v[60:63], v[206:209], v[28:31]
	v_mfma_f32_16x16x32_bf16 v[24:27], v[76:79], v[206:209], v[24:27]
	v_mfma_f32_16x16x32_bf16 v[12:15], v[60:63], v[214:217], v[12:15]
	v_mfma_f32_16x16x32_bf16 v[8:11], v[76:79], v[214:217], v[8:11]
	s_setprio 0
	s_setprio 1
	v_mfma_f32_16x16x32_bf16 v[52:55], v[162:165], v[186:189], v[52:55]
	v_mfma_f32_16x16x32_bf16 v[48:51], v[178:181], v[186:189], v[48:51]
	v_mfma_f32_16x16x32_bf16 v[36:39], v[162:165], v[194:197], v[36:39]
	v_mfma_f32_16x16x32_bf16 v[32:35], v[178:181], v[194:197], v[32:35]
	v_mfma_f32_16x16x32_bf16 v[20:23], v[162:165], v[202:205], v[20:23]
	v_mfma_f32_16x16x32_bf16 v[16:19], v[178:181], v[202:205], v[16:19]
	v_mfma_f32_16x16x32_bf16 v[4:7], v[162:165], v[210:213], v[4:7]
	v_mfma_f32_16x16x32_bf16 v[0:3], v[178:181], v[210:213], v[0:3]
	v_mfma_f32_16x16x32_bf16 v[52:55], v[166:169], v[190:193], v[52:55]
	v_mfma_f32_16x16x32_bf16 v[48:51], v[182:185], v[190:193], v[48:51]
	v_mfma_f32_16x16x32_bf16 v[36:39], v[166:169], v[198:201], v[36:39]
	v_mfma_f32_16x16x32_bf16 v[32:35], v[182:185], v[198:201], v[32:35]
	v_mfma_f32_16x16x32_bf16 v[20:23], v[166:169], v[206:209], v[20:23]
	v_mfma_f32_16x16x32_bf16 v[16:19], v[182:185], v[206:209], v[16:19]
	v_mfma_f32_16x16x32_bf16 v[4:7], v[166:169], v[214:217], v[4:7]
	v_mfma_f32_16x16x32_bf16 v[0:3], v[182:185], v[214:217], v[0:3]
	s_setprio 0
	s_barrier
	s_add_i32 s76, 0, 0x18000
	s_add_i32 s77, 0, 0x1c000
	v_add_u32_e32 v76, s76, v171
	v_add_u32_e32 v152, s77, v171
	ds_read_b128 v[56:59], v76
	ds_read_b128 v[60:63], v76 offset:1024
	ds_read_b128 v[72:75], v76 offset:2048
	ds_read_b128 v[76:79], v76 offset:3072
	ds_read_b128 v[162:165], v152
	ds_read_b128 v[166:169], v152 offset:1024
	ds_read_b128 v[178:181], v152 offset:2048
	ds_read_b128 v[182:185], v152 offset:3072
	s_add_u32 s38, s38, 0x40000
	s_addc_u32 s39, s39, 0
	s_mov_b32 m0, s46
	v_lshl_add_u64 v[228:229], s[38:39], 0, v[144:145]
	ds_read_b128 v[186:189], v175 offset:32768
	ds_read_b128 v[190:193], v175 offset:33792
	ds_read_b128 v[194:197], v175 offset:34816
	ds_read_b128 v[198:201], v175 offset:35840
	ds_read_b128 v[202:205], v175 offset:36864
	ds_read_b128 v[206:209], v175 offset:37888
	ds_read_b128 v[210:213], v175 offset:38912
	ds_read_b128 v[214:217], v175 offset:39936
	global_load_lds_dwordx4 v[228:229], off
	v_lshl_add_u64 v[228:229], s[38:39], 0, v[148:149]
	s_mov_b32 m0, s47
	s_nop 0
	global_load_lds_dwordx4 v[228:229], off
	s_waitcnt vmcnt(8)
	s_waitcnt lgkmcnt(0)
	s_barrier
	s_setprio 1
	s_waitcnt lgkmcnt(0)
	v_mfma_f32_16x16x32_bf16 v[140:143], v[56:59], v[186:189], v[140:143]
	v_mfma_f32_16x16x32_bf16 v[136:139], v[72:75], v[186:189], v[136:139]
	v_mfma_f32_16x16x32_bf16 v[124:127], v[56:59], v[194:197], v[124:127]
	v_mfma_f32_16x16x32_bf16 v[120:123], v[72:75], v[194:197], v[120:123]
	v_mfma_f32_16x16x32_bf16 v[108:111], v[56:59], v[202:205], v[108:111]
	v_mfma_f32_16x16x32_bf16 v[104:107], v[72:75], v[202:205], v[104:107]
	v_mfma_f32_16x16x32_bf16 v[92:95], v[56:59], v[210:213], v[92:95]
	v_mfma_f32_16x16x32_bf16 v[88:91], v[72:75], v[210:213], v[88:91]
	v_mfma_f32_16x16x32_bf16 v[140:143], v[60:63], v[190:193], v[140:143]
	v_mfma_f32_16x16x32_bf16 v[136:139], v[76:79], v[190:193], v[136:139]
	v_mfma_f32_16x16x32_bf16 v[124:127], v[60:63], v[198:201], v[124:127]
	v_mfma_f32_16x16x32_bf16 v[120:123], v[76:79], v[198:201], v[120:123]
	v_mfma_f32_16x16x32_bf16 v[108:111], v[60:63], v[206:209], v[108:111]
	v_mfma_f32_16x16x32_bf16 v[104:107], v[76:79], v[206:209], v[104:107]
	v_mfma_f32_16x16x32_bf16 v[92:95], v[60:63], v[214:217], v[92:95]
	v_mfma_f32_16x16x32_bf16 v[88:91], v[76:79], v[214:217], v[88:91]
	s_setprio 0
	s_setprio 1
	v_mfma_f32_16x16x32_bf16 v[132:135], v[162:165], v[186:189], v[132:135]
	v_mfma_f32_16x16x32_bf16 v[128:131], v[178:181], v[186:189], v[128:131]
	v_mfma_f32_16x16x32_bf16 v[116:119], v[162:165], v[194:197], v[116:119]
	v_mfma_f32_16x16x32_bf16 v[112:115], v[178:181], v[194:197], v[112:115]
	v_mfma_f32_16x16x32_bf16 v[100:103], v[162:165], v[202:205], v[100:103]
	v_mfma_f32_16x16x32_bf16 v[96:99], v[178:181], v[202:205], v[96:99]
	v_mfma_f32_16x16x32_bf16 v[84:87], v[162:165], v[210:213], v[84:87]
	v_mfma_f32_16x16x32_bf16 v[80:83], v[178:181], v[210:213], v[80:83]
	v_mfma_f32_16x16x32_bf16 v[132:135], v[166:169], v[190:193], v[132:135]
	v_mfma_f32_16x16x32_bf16 v[128:131], v[182:185], v[190:193], v[128:131]
	v_mfma_f32_16x16x32_bf16 v[116:119], v[166:169], v[198:201], v[116:119]
	v_mfma_f32_16x16x32_bf16 v[112:115], v[182:185], v[198:201], v[112:115]
	v_mfma_f32_16x16x32_bf16 v[100:103], v[166:169], v[206:209], v[100:103]
	v_mfma_f32_16x16x32_bf16 v[96:99], v[182:185], v[206:209], v[96:99]
	v_mfma_f32_16x16x32_bf16 v[84:87], v[166:169], v[214:217], v[84:87]
	v_mfma_f32_16x16x32_bf16 v[80:83], v[182:185], v[214:217], v[80:83]
	s_setprio 0
	s_barrier
; #define PG8_STAGE(bufoff, gbase, voff) do { _Pragma("unroll") for (int _i = 0; _i < 2; ++_i) \
;         __builtin_amdgcn_global_load_lds((const unsigned*)((const char*)(gbase) + (voff)[_i]), (PG8_LAS unsigned*)(lds + (bufoff) + ldsw + _i * 8192), 16, 0, 0); } while (0)
; #define PG8_LDA(dst, b, h) do { _Pragma("unroll") for (int m = 0; m < 4; ++m) _Pragma("unroll") for (int k = 0; k < 2; ++k) dst[m][k] = *(const PG8_LAS bf16x8*)(lds + PG8_SA(b, h) + aoff + m * 2048 + k * 1024); } while (0)
; #define PG8_MMA(ai, bj, At, Bt) do { __builtin_amdgcn_s_setprio(1); _Pragma("unroll") for (int m = 0; m < 4; ++m) _Pragma("unroll") for (int n = 0; n < 2; ++n) _Pragma("unroll") for (int k = 0; k < 2; ++k) \
;         acc[ai][bj][m][n] = __builtin_amdgcn_mfma_f32_16x16x32_bf16(Bt[n][k], At[m][k], acc[ai][bj][m][n], 0, 0, 0); __builtin_amdgcn_s_setprio(0); } while (0)
; #define PG8_WAIT_V(n) asm volatile("s_waitcnt vmcnt(" #n ")" ::: "memory")
; #define PG8_WAIT_L(n) asm volatile("s_waitcnt lgkmcnt(" #n ")" ::: "memory")
; #define PG8_BAR __builtin_amdgcn_s_barrier()
; #define PG8_SCHED __builtin_amdgcn_sched_barrier(0)
; template <class Epi, class Sched, bool ALIGN_EPI = false, bool SP2 = false>
; __device__ __forceinline__ void gemm_phase(PG8_LAS unsigned char* lds, const Gemm g, const Sched& S, const Epi& E) {
;     ...
;             PG8_LDA(At, 1, 1); PG8_STAGE(PG8_SB(1, 0), b3, voffB); PG8_STAGE(PG8_SB(1, 1), b3 + hstep, voffB); PG8_STAGE(PG8_SA(1, 0), a3, voffA);
;             PG8_WAIT_V(8); PG8_WAIT_L(0); PG8_BAR; PG8_MMA(1, 0, At, B0); PG8_MMA(1, 1, At, B1); PG8_BAR; PG8_SCHED;
	s_add_i32 s38, s76, s41
	v_lshl_add_u64 v[218:219], v[218:219], 0, s[18:19]
	s_mov_b32 m0, s38
	ds_read_b128 v[186:189], v175 offset:49152
	ds_read_b128 v[190:193], v175 offset:50176
	ds_read_b128 v[194:197], v175 offset:51200
	ds_read_b128 v[198:201], v175 offset:52224
	ds_read_b128 v[202:205], v175 offset:53248
	ds_read_b128 v[206:209], v175 offset:54272
	ds_read_b128 v[210:213], v175 offset:55296
	ds_read_b128 v[214:217], v175 offset:56320
	global_load_lds_dwordx4 v[218:219], off
	s_add_i32 m0, s38, 0x2000
	s_add_u32 s36, s36, 0x40080
	v_lshl_add_u64 v[218:219], v[220:221], 0, s[18:19]
	s_addc_u32 s37, s37, 0
	s_add_i32 s38, s77, s41
	global_load_lds_dwordx4 v[218:219], off
	v_lshl_add_u64 v[218:219], s[36:37], 0, v[146:147]
	s_mov_b32 m0, s38
	s_nop 0
	global_load_lds_dwordx4 v[218:219], off
	v_lshl_add_u64 v[218:219], s[36:37], 0, v[150:151]
	s_add_i32 m0, s38, 0x2000
	s_nop 0
	global_load_lds_dwordx4 v[218:219], off
	v_lshl_add_u64 v[218:219], v[222:223], 0, s[18:19]
	s_mov_b32 m0, s53
	s_nop 0
	global_load_lds_dwordx4 v[218:219], off
	v_lshl_add_u64 v[218:219], v[224:225], 0, s[18:19]
	s_mov_b32 m0, s60
	s_nop 0
	global_load_lds_dwordx4 v[218:219], off
	s_waitcnt vmcnt(8)
	s_waitcnt lgkmcnt(0)
	s_barrier
	s_setprio 1
	s_waitcnt lgkmcnt(0)
	v_mfma_f32_16x16x32_bf16 v[68:71], v[56:59], v[186:189], v[68:71]
	v_mfma_f32_16x16x32_bf16 v[64:67], v[72:75], v[186:189], v[64:67]
	v_mfma_f32_16x16x32_bf16 v[44:47], v[56:59], v[194:197], v[44:47]
	v_mfma_f32_16x16x32_bf16 v[40:43], v[72:75], v[194:197], v[40:43]
	v_mfma_f32_16x16x32_bf16 v[28:31], v[56:59], v[202:205], v[28:31]
	v_mfma_f32_16x16x32_bf16 v[24:27], v[72:75], v[202:205], v[24:27]
	v_mfma_f32_16x16x32_bf16 v[12:15], v[56:59], v[210:213], v[12:15]
	v_mfma_f32_16x16x32_bf16 v[8:11], v[72:75], v[210:213], v[8:11]
	v_mfma_f32_16x16x32_bf16 v[68:71], v[60:63], v[190:193], v[68:71]
	v_mfma_f32_16x16x32_bf16 v[64:67], v[76:79], v[190:193], v[64:67]
	v_mfma_f32_16x16x32_bf16 v[44:47], v[60:63], v[198:201], v[44:47]
	v_mfma_f32_16x16x32_bf16 v[40:43], v[76:79], v[198:201], v[40:43]
	v_mfma_f32_16x16x32_bf16 v[28:31], v[60:63], v[206:209], v[28:31]
	v_mfma_f32_16x16x32_bf16 v[24:27], v[76:79], v[206:209], v[24:27]
	v_mfma_f32_16x16x32_bf16 v[12:15], v[60:63], v[214:217], v[12:15]
	v_mfma_f32_16x16x32_bf16 v[8:11], v[76:79], v[214:217], v[8:11]
	s_setprio 0
	s_setprio 1
	v_mfma_f32_16x16x32_bf16 v[52:55], v[162:165], v[186:189], v[52:55]
	v_mfma_f32_16x16x32_bf16 v[48:51], v[178:181], v[186:189], v[48:51]
	v_mfma_f32_16x16x32_bf16 v[36:39], v[162:165], v[194:197], v[36:39]
	v_mfma_f32_16x16x32_bf16 v[32:35], v[178:181], v[194:197], v[32:35]
	v_mfma_f32_16x16x32_bf16 v[20:23], v[162:165], v[202:205], v[20:23]
	v_mfma_f32_16x16x32_bf16 v[16:19], v[178:181], v[202:205], v[16:19]
	v_mfma_f32_16x16x32_bf16 v[4:7], v[162:165], v[210:213], v[4:7]
	v_mfma_f32_16x16x32_bf16 v[0:3], v[178:181], v[210:213], v[0:3]
	v_mfma_f32_16x16x32_bf16 v[52:55], v[166:169], v[190:193], v[52:55]
	v_mfma_f32_16x16x32_bf16 v[48:51], v[182:185], v[190:193], v[48:51]
	v_mfma_f32_16x16x32_bf16 v[36:39], v[166:169], v[198:201], v[36:39]
	v_mfma_f32_16x16x32_bf16 v[32:35], v[182:185], v[198:201], v[32:35]
	v_mfma_f32_16x16x32_bf16 v[20:23], v[166:169], v[206:209], v[20:23]
	v_mfma_f32_16x16x32_bf16 v[16:19], v[182:185], v[206:209], v[16:19]
	v_mfma_f32_16x16x32_bf16 v[4:7], v[166:169], v[214:217], v[4:7]
	v_mfma_f32_16x16x32_bf16 v[0:3], v[182:185], v[214:217], v[0:3]
	s_setprio 0
	s_barrier
	s_mov_b32 s99, 0
	s_add_i32 s75, s75, 2
	s_add_u32 s34, s34, 0x100
	s_addc_u32 s35, s35, 0
	s_add_u32 s73, s73, 0x100
	s_addc_u32 s74, s74, 0
	s_cmp_gt_u32 s75, 13
	s_cbranch_scc0 .LBB0_1423
	s_and_b64 vcc, exec, s[20:21]
	s_cbranch_vccz .LBB0_1426
	s_barrier

; #define PG8_STAGE(bufoff, gbase, voff) do { _Pragma("unroll") for (int _i = 0; _i < 2; ++_i) \
;         __builtin_amdgcn_global_load_lds((const unsigned*)((const char*)(gbase) + (voff)[_i]), (PG8_LAS unsigned*)(lds + (bufoff) + ldsw + _i * 8192), 16, 0, 0); } while (0)
; #define PG8_WAIT_V(n) asm volatile("s_waitcnt vmcnt(" #n ")" ::: "memory")
; #define PG8_BAR __builtin_amdgcn_s_barrier()
; template <class Epi, class Sched, bool ALIGN_EPI = false, bool SP2 = false>
; __device__ __forceinline__ void gemm_phase(PG8_LAS unsigned char* lds, const Gemm g, const Sched& S, const Epi& E) {
;     ...
;     const int tid = tid_, wid = __builtin_amdgcn_readfirstlane(tid >> 6), lane = tid & 63, wr = wid >> 2, wc = wid & 3, fr = lane & 15, fq = lane >> 4;
;     const int K = g.K, nt = K / BK;
;     unsigned voffA[2], voffB[2];
; #pragma unroll
;     for (int i = 0; i < 2; ++i) { int R, C; stage_rc(tid * 16 + i * 8192, R, C); const int Rb = Epi::PERM ? ((R & ~31) + perm32(R & 31)) : R;
;         voffA[i] = (unsigned)(R * K + C) * 2u; voffB[i] = (unsigned)(Rb * K + C) * 2u; }
;     const size_t kstep = (size_t)(BK * 2);
;     const size_t hstep = (size_t)HALF * K * 2;
;     const size_t tstep = 2 * hstep;
;     const unsigned ldsw = (unsigned)wid * 1024u;
;     const int aoff = lds_byte(wr * 64 + fr, fq * 8), boff = lds_byte(wc * 32 + fr, fq * 8);
;     ...
;         PG8_STAGE(PG8_SB(0, 0), cB, voffB); PG8_STAGE(PG8_SB(0, 1), cB + hstep, voffB); PG8_STAGE(PG8_SA(0, 0), cA, voffA); PG8_STAGE(PG8_SA(0, 1), cA + hstep, voffA);
;         if (wr == 1) PG8_BAR;
;         PG8_WAIT_V(2); PG8_BAR;
;         PG8_STAGE(PG8_SB(1, 0), cB + kstep, voffB); PG8_STAGE(PG8_SA(1, 0), cA + kstep, voffA); PG8_STAGE(PG8_SB(1, 1), cB + hstep + kstep, voffB);
;         PG8_WAIT_V(6); PG8_BAR;
.LBB0_1534:
	s_and_b64 s[8:9], s[70:71], exec
	s_cselect_b32 s48, 0xf5, s3
	s_add_u32 s8, s86, 0x1ed00000
	s_addc_u32 s9, s87, 0
	s_lshl_b32 s14, s14, 5
	s_and_b32 s22, s14, 0x60
	s_mov_b64 s[14:15], 0x80
	s_add_i32 m0, s29, 0x18000
	v_lshl_add_u64 v[6:7], v[6:7], 0, s[14:15]
	s_lshl_b32 s17, s16, 13
	s_lshl_b32 s23, s22, 7
	s_waitcnt vmcnt(2)
	s_barrier
	global_load_lds_dwordx4 v[6:7], off
	v_lshl_add_u64 v[4:5], v[4:5], 0, s[14:15]
	s_add_i32 m0, s29, 0x1a000
	s_add_i32 s49, s29, 0x8000
	s_add_i32 s50, s29, 0xa000
	global_load_lds_dwordx4 v[4:5], off
	v_lshl_add_u64 v[0:1], v[0:1], 0, s[14:15]
	s_mov_b32 m0, s49
	s_add_u32 s18, s34, 0x40080
	global_load_lds_dwordx4 v[0:1], off
	v_lshl_add_u64 v[0:1], v[2:3], 0, s[14:15]
	s_mov_b32 m0, s50
	s_addc_u32 s19, s35, 0
	global_load_lds_dwordx4 v[0:1], off
	s_add_i32 m0, s29, 0x1c000
	v_lshl_add_u64 v[0:1], s[18:19], 0, v[132:133]
	global_load_lds_dwordx4 v[0:1], off
	v_lshl_add_u64 v[0:1], s[18:19], 0, v[128:129]
	s_add_i32 m0, s29, 0x1e000
	s_cmpk_lt_u32 s5, 0x100
	global_load_lds_dwordx4 v[0:1], off
	v_lshrrev_b32_e32 v1, 1, v9
	v_and_b32_e32 v1, 24, v1
	v_and_b32_e32 v0, 15, v9
	v_lshlrev_b32_e32 v2, 1, v1
	v_lshl_or_b32 v148, s16, 6, v0
	v_lshl_or_b32 v0, v0, 6, v2
	v_lshlrev_b32_e32 v2, 2, v9
	v_and_b32_e32 v2, 32, v2
	v_bitop3_b32 v3, v0, s17, v2 bitop3:0xde
	v_bitop3_b32 v149, v0, s23, v2 bitop3:0xde
	v_lshlrev_b32_e32 v0, 14, v13
	v_and_b32_e32 v0, 0xffff8000, v0
	v_or_b32_e32 v150, s22, v1
	v_lshl_add_u32 v0, v12, 11, v0
	v_and_b32_e32 v1, 1, v13
	v_lshl_or_b32 v0, v1, 6, v0
	v_lshl_add_u32 v136, v14, 1, v0
	v_lshlrev_b32_e32 v0, 14, v8
	v_and_b32_e32 v0, 0xffff8000, v0
	s_waitcnt vmcnt(6)
	v_lshl_add_u32 v0, v10, 11, v0
	v_and_b32_e32 v1, 1, v8
	s_cselect_b64 s[16:17], -1, 0
	v_lshl_or_b32 v0, v1, 6, v0
	s_add_i32 s52, 0, 0x10000
	s_add_i32 s53, 0, 0x14000
	s_sext_i32_i8 s60, s4
	s_ashr_i32 s51, s48, 31
	v_mov_b32_e32 v137, v133
	v_lshl_add_u32 v138, v11, 1, v0
	v_mov_b32_e32 v139, v133
	v_mov_b64_e32 v[140:141], 0x1040
	v_mov_b64_e32 v[142:143], 0x103f
	v_add_u32_e32 v151, s52, v149
	v_add_u32_e32 v152, s53, v149
	v_add_u32_e32 v153, 0, v3
	v_mov_b32_e32 v154, 0x358637bd
	s_barrier
	s_mov_b32 s99, 0
	s_branch .LBB0_1537

; #define PG8_BAR __builtin_amdgcn_s_barrier()
; template <class Epi, class Sched, bool ALIGN_EPI = false, bool SP2 = false>
; __device__ __forceinline__ void gemm_phase(PG8_LAS unsigned char* lds, const Gemm g, const Sched& S, const Epi& E) {
;     ...
;         if (!has_next) break;
; #pragma unroll
;         for (int a = 0; a < 2; ++a)
; #pragma unroll
;             for (int b = 0; b < 2; ++b)
; #pragma unroll
;                 for (int m = 0; m < 4; ++m)
; #pragma unroll
;                     for (int n = 0; n < 2; ++n) acc[a][b][m][n] = (f32x4){0.f, 0.f, 0.f, 0.f};
;         cur = nxt; cA = nA; cB = nB; ++ui;
;         if constexpr (ALIGN_EPI) { if (wr == 1) PG8_BAR; }
.LBB0_1536:
	s_mov_b32 s99, 1
	s_andn2_b64 vcc, exec, s[4:5]
	s_mov_b32 s60, s18
	s_mov_b32 s28, s22
	s_mov_b64 s[34:35], s[26:27]
	s_mov_b64 s[30:31], s[24:25]
	s_cbranch_vccz .LBB0_1546

; #define PG8_STAGE(bufoff, gbase, voff) do { _Pragma("unroll") for (int _i = 0; _i < 2; ++_i) \
;         __builtin_amdgcn_global_load_lds((const unsigned*)((const char*)(gbase) + (voff)[_i]), (PG8_LAS unsigned*)(lds + (bufoff) + ldsw + _i * 8192), 16, 0, 0); } while (0)
; #define PG8_LDA(dst, b, h) do { _Pragma("unroll") for (int m = 0; m < 4; ++m) _Pragma("unroll") for (int k = 0; k < 2; ++k) dst[m][k] = *(const PG8_LAS bf16x8*)(lds + PG8_SA(b, h) + aoff + m * 2048 + k * 1024); } while (0)
; #define PG8_LDB(dst, b, h) do { _Pragma("unroll") for (int n = 0; n < 2; ++n) _Pragma("unroll") for (int k = 0; k < 2; ++k) dst[n][k] = *(const PG8_LAS bf16x8*)(lds + PG8_SB(b, h) + boff + n * 2048 + k * 1024); } while (0)
; #define PG8_MMA(ai, bj, At, Bt) do { __builtin_amdgcn_s_setprio(1); _Pragma("unroll") for (int m = 0; m < 4; ++m) _Pragma("unroll") for (int n = 0; n < 2; ++n) _Pragma("unroll") for (int k = 0; k < 2; ++k) \
;         acc[ai][bj][m][n] = __builtin_amdgcn_mfma_f32_16x16x32_bf16(Bt[n][k], At[m][k], acc[ai][bj][m][n], 0, 0, 0); __builtin_amdgcn_s_setprio(0); } while (0)
; #define PG8_WAIT_V(n) asm volatile("s_waitcnt vmcnt(" #n ")" ::: "memory")
; #define PG8_WAIT_L(n) asm volatile("s_waitcnt lgkmcnt(" #n ")" ::: "memory")
; #define PG8_BAR __builtin_amdgcn_s_barrier()
; template <class Epi, class Sched, bool ALIGN_EPI = false, bool SP2 = false>
; __device__ __forceinline__ void gemm_phase(PG8_LAS unsigned char* lds, const Gemm g, const Sched& S, const Epi& E) {
;     ...
;         const bool has_next = S.next(ui + 1, nxt);
;         const char* nA = has_next ? (const char*)g.A + (size_t)nxt.pm * tstep : cA; const char* nB = has_next ? (const char*)g.Bt + (size_t)nxt.pn * tstep : cB;
;         for (int t = 0; t < nt; t += 2) {
;             const bool last = (t == nt - 2);
;             const char* a1 = cA + (size_t)(t + 1) * kstep;
;             const char* a2 = last ? nA : cA + (size_t)(t + 2) * kstep; const char* b2 = last ? nB : cB + (size_t)(t + 2) * kstep;
;             const char* a3 = a2 + kstep; const char* b3 = b2 + kstep;
;             if (last && has_next) S.a_ready(nxt);
;             if constexpr (SP2) {
;             PG8_LDB(B0, 0, 0); PG8_LDB(B1, 0, 1); PG8_SCHED; PG8_LDA(At, 0, 0); PG8_STAGE(PG8_SA(1, 1), a1 + hstep, voffA);
;             PG8_WAIT_V(8); PG8_WAIT_L(0); PG8_BAR; PG8_MMA(0, 0, At, B0); PG8_MMA(0, 1, At, B1); PG8_BAR; PG8_SCHED;
.LBB0_1540:
	ds_read_b128 v[144:147], v151
	ds_read_b128 v[156:159], v151 offset:1024
	ds_read_b128 v[160:163], v151 offset:2048
	ds_read_b128 v[164:167], v151 offset:3072
	ds_read_b128 v[168:171], v152
	ds_read_b128 v[172:175], v152 offset:1024
	ds_read_b128 v[176:179], v152 offset:2048
	ds_read_b128 v[180:183], v152 offset:3072
	s_add_u32 s34, s30, 0xfffc0080
	s_addc_u32 s35, s31, -1
	s_cmp_eq_u32 s65, 12
	s_cselect_b32 s37, s23, s35
	s_cselect_b32 s36, s61, s34
	s_cselect_b32 s35, s19, s64
	s_cselect_b32 s34, s62, s63
	v_lshl_add_u64 v[216:217], s[30:31], 0, v[136:137]
	s_add_i32 m0, s29, 0xc000
	ds_read_b128 v[184:187], v153
	ds_read_b128 v[188:191], v153 offset:1024
	ds_read_b128 v[192:195], v153 offset:2048
	ds_read_b128 v[196:199], v153 offset:3072
	ds_read_b128 v[200:203], v153 offset:4096
	ds_read_b128 v[204:207], v153 offset:5120
	ds_read_b128 v[208:211], v153 offset:6144
	ds_read_b128 v[212:215], v153 offset:7168
	global_load_lds_dwordx4 v[216:217], off
	v_lshl_add_u64 v[216:217], s[30:31], 0, v[138:139]
	s_add_i32 m0, s29, 0xe000
	s_nop 0
	global_load_lds_dwordx4 v[216:217], off
	s_cmp_eq_u32 s99, 1
	s_cbranch_scc1 .Lrw_P5_0
	s_waitcnt vmcnt(8)
	s_branch .Lrj_P5_0

; #define PG8_STAGE(bufoff, gbase, voff) do { _Pragma("unroll") for (int _i = 0; _i < 2; ++_i) \
;         __builtin_amdgcn_global_load_lds((const unsigned*)((const char*)(gbase) + (voff)[_i]), (PG8_LAS unsigned*)(lds + (bufoff) + ldsw + _i * 8192), 16, 0, 0); } while (0)
; #define PG8_LDA(dst, b, h) do { _Pragma("unroll") for (int m = 0; m < 4; ++m) _Pragma("unroll") for (int k = 0; k < 2; ++k) dst[m][k] = *(const PG8_LAS bf16x8*)(lds + PG8_SA(b, h) + aoff + m * 2048 + k * 1024); } while (0)
; #define PG8_MMA(ai, bj, At, Bt) do { __builtin_amdgcn_s_setprio(1); _Pragma("unroll") for (int m = 0; m < 4; ++m) _Pragma("unroll") for (int n = 0; n < 2; ++n) _Pragma("unroll") for (int k = 0; k < 2; ++k) \
;         acc[ai][bj][m][n] = __builtin_amdgcn_mfma_f32_16x16x32_bf16(Bt[n][k], At[m][k], acc[ai][bj][m][n], 0, 0, 0); __builtin_amdgcn_s_setprio(0); } while (0)
; #define PG8_WAIT_V(n) asm volatile("s_waitcnt vmcnt(" #n ")" ::: "memory")
; #define PG8_WAIT_L(n) asm volatile("s_waitcnt lgkmcnt(" #n ")" ::: "memory")
; #define PG8_BAR __builtin_amdgcn_s_barrier()
; #define PG8_SCHED __builtin_amdgcn_sched_barrier(0)
; template <class Epi, class Sched, bool ALIGN_EPI = false, bool SP2 = false>
; __device__ __forceinline__ void gemm_phase(PG8_LAS unsigned char* lds, const Gemm g, const Sched& S, const Epi& E) {
;     ...
;             PG8_WAIT_V(8); PG8_WAIT_L(0); PG8_BAR; PG8_MMA(0, 0, At, B0); PG8_MMA(0, 1, At, B1); PG8_BAR; PG8_SCHED;
;             PG8_LDA(At, 0, 1); PG8_STAGE(PG8_SB(0, 0), b2, voffB); PG8_STAGE(PG8_SB(0, 1), b2 + hstep, voffB); PG8_STAGE(PG8_SA(0, 0), a2, voffA);
;             PG8_WAIT_V(8); PG8_WAIT_L(0); PG8_BAR; PG8_MMA(1, 0, At, B0); PG8_MMA(1, 1, At, B1); PG8_BAR; PG8_SCHED;
.Lrj_P5_0:
	s_waitcnt lgkmcnt(0)
	s_barrier
	s_setprio 1
	s_waitcnt lgkmcnt(0)
	v_mfma_f32_16x16x32_bf16 v[124:127], v[144:147], v[184:187], v[124:127]
	v_mfma_f32_16x16x32_bf16 v[120:123], v[160:163], v[184:187], v[120:123]
	v_mfma_f32_16x16x32_bf16 v[108:111], v[144:147], v[192:195], v[108:111]
	v_mfma_f32_16x16x32_bf16 v[104:107], v[160:163], v[192:195], v[104:107]
	v_mfma_f32_16x16x32_bf16 v[92:95], v[144:147], v[200:203], v[92:95]
	v_mfma_f32_16x16x32_bf16 v[88:91], v[160:163], v[200:203], v[88:91]
	v_mfma_f32_16x16x32_bf16 v[76:79], v[144:147], v[208:211], v[76:79]
	v_mfma_f32_16x16x32_bf16 v[72:75], v[160:163], v[208:211], v[72:75]
	v_mfma_f32_16x16x32_bf16 v[124:127], v[156:159], v[188:191], v[124:127]
	v_mfma_f32_16x16x32_bf16 v[120:123], v[164:167], v[188:191], v[120:123]
	v_mfma_f32_16x16x32_bf16 v[108:111], v[156:159], v[196:199], v[108:111]
	v_mfma_f32_16x16x32_bf16 v[104:107], v[164:167], v[196:199], v[104:107]
	v_mfma_f32_16x16x32_bf16 v[92:95], v[156:159], v[204:207], v[92:95]
	v_mfma_f32_16x16x32_bf16 v[88:91], v[164:167], v[204:207], v[88:91]
	v_mfma_f32_16x16x32_bf16 v[76:79], v[156:159], v[212:215], v[76:79]
	v_mfma_f32_16x16x32_bf16 v[72:75], v[164:167], v[212:215], v[72:75]
	s_setprio 0
	s_setprio 1
	v_mfma_f32_16x16x32_bf16 v[116:119], v[168:171], v[184:187], v[116:119]
	v_mfma_f32_16x16x32_bf16 v[112:115], v[176:179], v[184:187], v[112:115]
	v_mfma_f32_16x16x32_bf16 v[100:103], v[168:171], v[192:195], v[100:103]
	v_mfma_f32_16x16x32_bf16 v[96:99], v[176:179], v[192:195], v[96:99]
	v_mfma_f32_16x16x32_bf16 v[84:87], v[168:171], v[200:203], v[84:87]
	v_mfma_f32_16x16x32_bf16 v[80:83], v[176:179], v[200:203], v[80:83]
	v_mfma_f32_16x16x32_bf16 v[68:71], v[168:171], v[208:211], v[68:71]
	v_mfma_f32_16x16x32_bf16 v[64:67], v[176:179], v[208:211], v[64:67]
	v_mfma_f32_16x16x32_bf16 v[116:119], v[172:175], v[188:191], v[116:119]
	v_mfma_f32_16x16x32_bf16 v[112:115], v[180:183], v[188:191], v[112:115]
	v_mfma_f32_16x16x32_bf16 v[100:103], v[172:175], v[196:199], v[100:103]
	v_mfma_f32_16x16x32_bf16 v[96:99], v[180:183], v[196:199], v[96:99]
	v_mfma_f32_16x16x32_bf16 v[84:87], v[172:175], v[204:207], v[84:87]
	v_mfma_f32_16x16x32_bf16 v[80:83], v[180:183], v[204:207], v[80:83]
	v_mfma_f32_16x16x32_bf16 v[68:71], v[172:175], v[212:215], v[68:71]
	v_mfma_f32_16x16x32_bf16 v[64:67], v[180:183], v[212:215], v[64:67]
	s_setprio 0
	s_barrier
	s_add_i32 s66, s52, s39
	v_lshl_add_u64 v[216:217], s[34:35], 0, v[132:133]
	s_mov_b32 m0, s66
	ds_read_b128 v[184:187], v153 offset:16384
	ds_read_b128 v[188:191], v153 offset:17408
	ds_read_b128 v[192:195], v153 offset:18432
	ds_read_b128 v[196:199], v153 offset:19456
	ds_read_b128 v[200:203], v153 offset:20480
	ds_read_b128 v[204:207], v153 offset:21504
	ds_read_b128 v[208:211], v153 offset:22528
	ds_read_b128 v[212:215], v153 offset:23552
	global_load_lds_dwordx4 v[216:217], off
	s_add_i32 m0, s66, 0x2000
	s_add_u32 s66, s34, 0x40000
	v_lshl_add_u64 v[218:219], s[34:35], 0, v[128:129]
	s_addc_u32 s67, s35, 0
	s_add_i32 s68, s53, s39
	global_load_lds_dwordx4 v[218:219], off
	v_lshl_add_u64 v[220:221], s[66:67], 0, v[132:133]
	s_mov_b32 m0, s68
	v_lshl_add_u64 v[222:223], s[36:37], 0, v[130:131]
	global_load_lds_dwordx4 v[220:221], off
	v_lshl_add_u64 v[220:221], s[66:67], 0, v[128:129]
	s_add_i32 m0, s68, 0x2000
	s_nop 0
	global_load_lds_dwordx4 v[220:221], off
	v_lshl_add_u64 v[220:221], s[36:37], 0, v[134:135]
	s_mov_b32 m0, s29
	s_nop 0
	global_load_lds_dwordx4 v[220:221], off
	s_mov_b32 m0, s42
	s_nop 0
	global_load_lds_dwordx4 v[222:223], off
	s_cmp_eq_u32 s99, 1
	s_cbranch_scc1 .Lrw_P5_1
	s_waitcnt vmcnt(8)
	s_branch .Lrj_P5_1

; #define PG8_STAGE(bufoff, gbase, voff) do { _Pragma("unroll") for (int _i = 0; _i < 2; ++_i) \
;         __builtin_amdgcn_global_load_lds((const unsigned*)((const char*)(gbase) + (voff)[_i]), (PG8_LAS unsigned*)(lds + (bufoff) + ldsw + _i * 8192), 16, 0, 0); } while (0)
; #define PG8_LDA(dst, b, h) do { _Pragma("unroll") for (int m = 0; m < 4; ++m) _Pragma("unroll") for (int k = 0; k < 2; ++k) dst[m][k] = *(const PG8_LAS bf16x8*)(lds + PG8_SA(b, h) + aoff + m * 2048 + k * 1024); } while (0)
; #define PG8_LDB(dst, b, h) do { _Pragma("unroll") for (int n = 0; n < 2; ++n) _Pragma("unroll") for (int k = 0; k < 2; ++k) dst[n][k] = *(const PG8_LAS bf16x8*)(lds + PG8_SB(b, h) + boff + n * 2048 + k * 1024); } while (0)
; #define PG8_MMA(ai, bj, At, Bt) do { __builtin_amdgcn_s_setprio(1); _Pragma("unroll") for (int m = 0; m < 4; ++m) _Pragma("unroll") for (int n = 0; n < 2; ++n) _Pragma("unroll") for (int k = 0; k < 2; ++k) \
;         acc[ai][bj][m][n] = __builtin_amdgcn_mfma_f32_16x16x32_bf16(Bt[n][k], At[m][k], acc[ai][bj][m][n], 0, 0, 0); __builtin_amdgcn_s_setprio(0); } while (0)
; #define PG8_WAIT_V(n) asm volatile("s_waitcnt vmcnt(" #n ")" ::: "memory")
; #define PG8_WAIT_L(n) asm volatile("s_waitcnt lgkmcnt(" #n ")" ::: "memory")
; #define PG8_BAR __builtin_amdgcn_s_barrier()
; #define PG8_SCHED __builtin_amdgcn_sched_barrier(0)
; template <class Epi, class Sched, bool ALIGN_EPI = false, bool SP2 = false>
; __device__ __forceinline__ void gemm_phase(PG8_LAS unsigned char* lds, const Gemm g, const Sched& S, const Epi& E) {
;     ...
;             PG8_WAIT_V(8); PG8_WAIT_L(0); PG8_BAR; PG8_MMA(1, 0, At, B0); PG8_MMA(1, 1, At, B1); PG8_BAR; PG8_SCHED;
;             PG8_LDB(B0, 1, 0); PG8_LDB(B1, 1, 1); PG8_SCHED; PG8_LDA(At, 1, 0); PG8_STAGE(PG8_SA(0, 1), a2 + hstep, voffA);
;             PG8_WAIT_V(8); PG8_WAIT_L(0); PG8_BAR; PG8_MMA(0, 0, At, B0); PG8_MMA(0, 1, At, B1); PG8_BAR; PG8_SCHED;
.Lrj_P5_1:
	s_waitcnt lgkmcnt(0)
	s_barrier
	s_setprio 1
	s_waitcnt lgkmcnt(0)
	v_mfma_f32_16x16x32_bf16 v[60:63], v[144:147], v[184:187], v[60:63]
	v_mfma_f32_16x16x32_bf16 v[56:59], v[160:163], v[184:187], v[56:59]
	v_mfma_f32_16x16x32_bf16 v[44:47], v[144:147], v[192:195], v[44:47]
	v_mfma_f32_16x16x32_bf16 v[40:43], v[160:163], v[192:195], v[40:43]
	v_mfma_f32_16x16x32_bf16 v[28:31], v[144:147], v[200:203], v[28:31]
	v_mfma_f32_16x16x32_bf16 v[24:27], v[160:163], v[200:203], v[24:27]
	v_mfma_f32_16x16x32_bf16 v[12:15], v[144:147], v[208:211], v[12:15]
	v_mfma_f32_16x16x32_bf16 v[8:11], v[160:163], v[208:211], v[8:11]
	v_mfma_f32_16x16x32_bf16 v[60:63], v[156:159], v[188:191], v[60:63]
	v_mfma_f32_16x16x32_bf16 v[56:59], v[164:167], v[188:191], v[56:59]
	v_mfma_f32_16x16x32_bf16 v[44:47], v[156:159], v[196:199], v[44:47]
	v_mfma_f32_16x16x32_bf16 v[40:43], v[164:167], v[196:199], v[40:43]
	v_mfma_f32_16x16x32_bf16 v[28:31], v[156:159], v[204:207], v[28:31]
	v_mfma_f32_16x16x32_bf16 v[24:27], v[164:167], v[204:207], v[24:27]
	v_mfma_f32_16x16x32_bf16 v[12:15], v[156:159], v[212:215], v[12:15]
	v_mfma_f32_16x16x32_bf16 v[8:11], v[164:167], v[212:215], v[8:11]
	s_setprio 0
	s_setprio 1
	v_mfma_f32_16x16x32_bf16 v[52:55], v[168:171], v[184:187], v[52:55]
	v_mfma_f32_16x16x32_bf16 v[48:51], v[176:179], v[184:187], v[48:51]
	v_mfma_f32_16x16x32_bf16 v[36:39], v[168:171], v[192:195], v[36:39]
	v_mfma_f32_16x16x32_bf16 v[32:35], v[176:179], v[192:195], v[32:35]
	v_mfma_f32_16x16x32_bf16 v[20:23], v[168:171], v[200:203], v[20:23]
	v_mfma_f32_16x16x32_bf16 v[16:19], v[176:179], v[200:203], v[16:19]
	v_mfma_f32_16x16x32_bf16 v[4:7], v[168:171], v[208:211], v[4:7]
	v_mfma_f32_16x16x32_bf16 v[0:3], v[176:179], v[208:211], v[0:3]
	v_mfma_f32_16x16x32_bf16 v[52:55], v[172:175], v[188:191], v[52:55]
	v_mfma_f32_16x16x32_bf16 v[48:51], v[180:183], v[188:191], v[48:51]
	v_mfma_f32_16x16x32_bf16 v[36:39], v[172:175], v[196:199], v[36:39]
	v_mfma_f32_16x16x32_bf16 v[32:35], v[180:183], v[196:199], v[32:35]
	v_mfma_f32_16x16x32_bf16 v[20:23], v[172:175], v[204:207], v[20:23]
	v_mfma_f32_16x16x32_bf16 v[16:19], v[180:183], v[204:207], v[16:19]
	v_mfma_f32_16x16x32_bf16 v[4:7], v[172:175], v[212:215], v[4:7]
	v_mfma_f32_16x16x32_bf16 v[0:3], v[180:183], v[212:215], v[0:3]
	s_setprio 0
	s_barrier
	s_add_i32 s66, 0, 0x18000
	v_add_u32_e32 v155, s66, v149
	s_add_i32 s67, 0, 0x1c000
	ds_read_b128 v[144:147], v155
	ds_read_b128 v[156:159], v155 offset:1024
	ds_read_b128 v[160:163], v155 offset:2048
	ds_read_b128 v[164:167], v155 offset:3072
	v_add_u32_e32 v155, s67, v149
	ds_read_b128 v[168:171], v155
	ds_read_b128 v[172:175], v155 offset:1024
	ds_read_b128 v[176:179], v155 offset:2048
	ds_read_b128 v[180:183], v155 offset:3072
	s_add_u32 s36, s36, 0x40000
	s_addc_u32 s37, s37, 0
	s_mov_b32 m0, s43
	v_lshl_add_u64 v[224:225], s[36:37], 0, v[134:135]
	ds_read_b128 v[184:187], v153 offset:32768
	ds_read_b128 v[188:191], v153 offset:33792
	ds_read_b128 v[192:195], v153 offset:34816
	ds_read_b128 v[196:199], v153 offset:35840
	ds_read_b128 v[200:203], v153 offset:36864
	ds_read_b128 v[204:207], v153 offset:37888
	ds_read_b128 v[208:211], v153 offset:38912
	ds_read_b128 v[212:215], v153 offset:39936
	global_load_lds_dwordx4 v[224:225], off
	v_lshl_add_u64 v[224:225], s[36:37], 0, v[130:131]
	s_mov_b32 m0, s46
	s_nop 0
	global_load_lds_dwordx4 v[224:225], off
	s_waitcnt vmcnt(8)
	s_waitcnt lgkmcnt(0)
	s_barrier
	s_setprio 1
	s_waitcnt lgkmcnt(0)
	v_mfma_f32_16x16x32_bf16 v[124:127], v[144:147], v[184:187], v[124:127]
	v_mfma_f32_16x16x32_bf16 v[120:123], v[160:163], v[184:187], v[120:123]
	v_mfma_f32_16x16x32_bf16 v[108:111], v[144:147], v[192:195], v[108:111]
	v_mfma_f32_16x16x32_bf16 v[104:107], v[160:163], v[192:195], v[104:107]
	v_mfma_f32_16x16x32_bf16 v[92:95], v[144:147], v[200:203], v[92:95]
	v_mfma_f32_16x16x32_bf16 v[88:91], v[160:163], v[200:203], v[88:91]
	v_mfma_f32_16x16x32_bf16 v[76:79], v[144:147], v[208:211], v[76:79]
	v_mfma_f32_16x16x32_bf16 v[72:75], v[160:163], v[208:211], v[72:75]
	v_mfma_f32_16x16x32_bf16 v[124:127], v[156:159], v[188:191], v[124:127]
	v_mfma_f32_16x16x32_bf16 v[120:123], v[164:167], v[188:191], v[120:123]
	v_mfma_f32_16x16x32_bf16 v[108:111], v[156:159], v[196:199], v[108:111]
	v_mfma_f32_16x16x32_bf16 v[104:107], v[164:167], v[196:199], v[104:107]
	v_mfma_f32_16x16x32_bf16 v[92:95], v[156:159], v[204:207], v[92:95]
	v_mfma_f32_16x16x32_bf16 v[88:91], v[164:167], v[204:207], v[88:91]
	v_mfma_f32_16x16x32_bf16 v[76:79], v[156:159], v[212:215], v[76:79]
	v_mfma_f32_16x16x32_bf16 v[72:75], v[164:167], v[212:215], v[72:75]
	s_setprio 0
	s_setprio 1
	v_mfma_f32_16x16x32_bf16 v[116:119], v[168:171], v[184:187], v[116:119]
	v_mfma_f32_16x16x32_bf16 v[112:115], v[176:179], v[184:187], v[112:115]
	v_mfma_f32_16x16x32_bf16 v[100:103], v[168:171], v[192:195], v[100:103]
	v_mfma_f32_16x16x32_bf16 v[96:99], v[176:179], v[192:195], v[96:99]
	v_mfma_f32_16x16x32_bf16 v[84:87], v[168:171], v[200:203], v[84:87]
	v_mfma_f32_16x16x32_bf16 v[80:83], v[176:179], v[200:203], v[80:83]
	v_mfma_f32_16x16x32_bf16 v[68:71], v[168:171], v[208:211], v[68:71]
	v_mfma_f32_16x16x32_bf16 v[64:67], v[176:179], v[208:211], v[64:67]
	v_mfma_f32_16x16x32_bf16 v[116:119], v[172:175], v[188:191], v[116:119]
	v_mfma_f32_16x16x32_bf16 v[112:115], v[180:183], v[188:191], v[112:115]
	v_mfma_f32_16x16x32_bf16 v[100:103], v[172:175], v[196:199], v[100:103]
	v_mfma_f32_16x16x32_bf16 v[96:99], v[180:183], v[196:199], v[96:99]
	v_mfma_f32_16x16x32_bf16 v[84:87], v[172:175], v[204:207], v[84:87]
	v_mfma_f32_16x16x32_bf16 v[80:83], v[180:183], v[204:207], v[80:83]
	v_mfma_f32_16x16x32_bf16 v[68:71], v[172:175], v[212:215], v[68:71]
	v_mfma_f32_16x16x32_bf16 v[64:67], v[180:183], v[212:215], v[64:67]
	s_setprio 0
	s_barrier
; #define PG8_STAGE(bufoff, gbase, voff) do { _Pragma("unroll") for (int _i = 0; _i < 2; ++_i) \
;         __builtin_amdgcn_global_load_lds((const unsigned*)((const char*)(gbase) + (voff)[_i]), (PG8_LAS unsigned*)(lds + (bufoff) + ldsw + _i * 8192), 16, 0, 0); } while (0)
; #define PG8_LDA(dst, b, h) do { _Pragma("unroll") for (int m = 0; m < 4; ++m) _Pragma("unroll") for (int k = 0; k < 2; ++k) dst[m][k] = *(const PG8_LAS bf16x8*)(lds + PG8_SA(b, h) + aoff + m * 2048 + k * 1024); } while (0)
; #define PG8_MMA(ai, bj, At, Bt) do { __builtin_amdgcn_s_setprio(1); _Pragma("unroll") for (int m = 0; m < 4; ++m) _Pragma("unroll") for (int n = 0; n < 2; ++n) _Pragma("unroll") for (int k = 0; k < 2; ++k) \
;         acc[ai][bj][m][n] = __builtin_amdgcn_mfma_f32_16x16x32_bf16(Bt[n][k], At[m][k], acc[ai][bj][m][n], 0, 0, 0); __builtin_amdgcn_s_setprio(0); } while (0)
; #define PG8_WAIT_V(n) asm volatile("s_waitcnt vmcnt(" #n ")" ::: "memory")
; #define PG8_WAIT_L(n) asm volatile("s_waitcnt lgkmcnt(" #n ")" ::: "memory")
; #define PG8_BAR __builtin_amdgcn_s_barrier()
; #define PG8_SCHED __builtin_amdgcn_sched_barrier(0)
; template <class Epi, class Sched, bool ALIGN_EPI = false, bool SP2 = false>
; __device__ __forceinline__ void gemm_phase(PG8_LAS unsigned char* lds, const Gemm g, const Sched& S, const Epi& E) {
;     ...
;             PG8_LDA(At, 1, 1); PG8_STAGE(PG8_SB(1, 0), b3, voffB); PG8_STAGE(PG8_SB(1, 1), b3 + hstep, voffB); PG8_STAGE(PG8_SA(1, 0), a3, voffA);
;             PG8_WAIT_V(8); PG8_WAIT_L(0); PG8_BAR; PG8_MMA(1, 0, At, B0); PG8_MMA(1, 1, At, B1); PG8_BAR; PG8_SCHED;
;     __device__ __forceinline__ void operator()(const f32x4 (&acc)[2][2][4][2], const Unit& u, int wr, int wc, int fr, int fq) const {
;         const int rbase = u.pm * 256 + wr * 64 + fr, cb = u.pn * 256 + wc * 32 + fq * 8;
; #pragma unroll
;         for (int ai = 0; ai < 2; ++ai)
; #pragma unroll
;             for (int m = 0; m < 4; ++m) { const int row = rbase + ai * 128 + m * 16; const f32x4* sp = (const f32x4*)(SSP + (size_t)row * 16);
;                 const f32x4 s4 = (sp[0] + sp[1]) + (sp[2] + sp[3]); const float rstd = __builtin_amdgcn_rsqf(((s4[0] + s4[1]) + (s4[2] + s4[3])) * (1.0f / 1024.0f) + EPS);
	s_add_i32 s36, s66, s39
	v_lshl_add_u64 v[216:217], v[216:217], 0, s[14:15]
	s_mov_b32 m0, s36
	ds_read_b128 v[184:187], v153 offset:49152
	ds_read_b128 v[188:191], v153 offset:50176
	ds_read_b128 v[192:195], v153 offset:51200
	ds_read_b128 v[196:199], v153 offset:52224
	ds_read_b128 v[200:203], v153 offset:53248
	ds_read_b128 v[204:207], v153 offset:54272
	ds_read_b128 v[208:211], v153 offset:55296
	ds_read_b128 v[212:215], v153 offset:56320
	global_load_lds_dwordx4 v[216:217], off
	s_add_i32 m0, s36, 0x2000
	s_add_u32 s34, s34, 0x40080
	v_lshl_add_u64 v[216:217], v[218:219], 0, s[14:15]
	s_addc_u32 s35, s35, 0
	s_add_i32 s36, s67, s39
	global_load_lds_dwordx4 v[216:217], off
	v_lshl_add_u64 v[216:217], s[34:35], 0, v[132:133]
	s_mov_b32 m0, s36
	s_nop 0
	global_load_lds_dwordx4 v[216:217], off
	v_lshl_add_u64 v[216:217], s[34:35], 0, v[128:129]
	s_add_i32 m0, s36, 0x2000
	s_nop 0
	global_load_lds_dwordx4 v[216:217], off
	v_lshl_add_u64 v[216:217], v[220:221], 0, s[14:15]
	s_mov_b32 m0, s49
	s_nop 0
	global_load_lds_dwordx4 v[216:217], off
	v_lshl_add_u64 v[216:217], v[222:223], 0, s[14:15]
	s_mov_b32 m0, s50
	s_nop 0
	global_load_lds_dwordx4 v[216:217], off
	s_waitcnt vmcnt(8)
	s_waitcnt lgkmcnt(0)
	s_barrier
	s_setprio 1
	s_waitcnt lgkmcnt(0)
	v_mfma_f32_16x16x32_bf16 v[60:63], v[144:147], v[184:187], v[60:63]
	v_mfma_f32_16x16x32_bf16 v[56:59], v[160:163], v[184:187], v[56:59]
	v_mfma_f32_16x16x32_bf16 v[44:47], v[144:147], v[192:195], v[44:47]
	v_mfma_f32_16x16x32_bf16 v[40:43], v[160:163], v[192:195], v[40:43]
	v_mfma_f32_16x16x32_bf16 v[28:31], v[144:147], v[200:203], v[28:31]
	v_mfma_f32_16x16x32_bf16 v[24:27], v[160:163], v[200:203], v[24:27]
	v_mfma_f32_16x16x32_bf16 v[12:15], v[144:147], v[208:211], v[12:15]
	v_mfma_f32_16x16x32_bf16 v[8:11], v[160:163], v[208:211], v[8:11]
	v_mfma_f32_16x16x32_bf16 v[60:63], v[156:159], v[188:191], v[60:63]
	v_mfma_f32_16x16x32_bf16 v[56:59], v[164:167], v[188:191], v[56:59]
	v_mfma_f32_16x16x32_bf16 v[44:47], v[156:159], v[196:199], v[44:47]
	v_mfma_f32_16x16x32_bf16 v[40:43], v[164:167], v[196:199], v[40:43]
	v_mfma_f32_16x16x32_bf16 v[28:31], v[156:159], v[204:207], v[28:31]
	v_mfma_f32_16x16x32_bf16 v[24:27], v[164:167], v[204:207], v[24:27]
	v_mfma_f32_16x16x32_bf16 v[12:15], v[156:159], v[212:215], v[12:15]
	v_mfma_f32_16x16x32_bf16 v[8:11], v[164:167], v[212:215], v[8:11]
	s_setprio 0
	s_setprio 1
	v_mfma_f32_16x16x32_bf16 v[52:55], v[168:171], v[184:187], v[52:55]
	v_mfma_f32_16x16x32_bf16 v[48:51], v[176:179], v[184:187], v[48:51]
	v_mfma_f32_16x16x32_bf16 v[36:39], v[168:171], v[192:195], v[36:39]
	v_mfma_f32_16x16x32_bf16 v[32:35], v[176:179], v[192:195], v[32:35]
	v_mfma_f32_16x16x32_bf16 v[20:23], v[168:171], v[200:203], v[20:23]
	v_mfma_f32_16x16x32_bf16 v[16:19], v[176:179], v[200:203], v[16:19]
	v_mfma_f32_16x16x32_bf16 v[4:7], v[168:171], v[208:211], v[4:7]
	v_mfma_f32_16x16x32_bf16 v[0:3], v[176:179], v[208:211], v[0:3]
	v_mfma_f32_16x16x32_bf16 v[52:55], v[172:175], v[188:191], v[52:55]
	v_mfma_f32_16x16x32_bf16 v[48:51], v[180:183], v[188:191], v[48:51]
	v_mfma_f32_16x16x32_bf16 v[36:39], v[172:175], v[196:199], v[36:39]
	v_mfma_f32_16x16x32_bf16 v[32:35], v[180:183], v[196:199], v[32:35]
	v_mfma_f32_16x16x32_bf16 v[20:23], v[172:175], v[204:207], v[20:23]
	v_mfma_f32_16x16x32_bf16 v[16:19], v[180:183], v[204:207], v[16:19]
	v_mfma_f32_16x16x32_bf16 v[4:7], v[172:175], v[212:215], v[4:7]
	v_mfma_f32_16x16x32_bf16 v[0:3], v[180:183], v[212:215], v[0:3]
	s_setprio 0
	s_barrier
	s_mov_b32 s99, 0
	s_add_i32 s65, s65, 2
	s_add_u32 s30, s30, 0x100
	s_addc_u32 s31, s31, 0
	s_add_u32 s63, s63, 0x100
	s_addc_u32 s64, s64, 0
	s_cmp_gt_u32 s65, 13
	s_cbranch_scc0 .LBB0_1540
	s_and_b64 vcc, exec, s[16:17]
	s_cbranch_vccz .LBB0_1543
	s_barrier
.LBB0_1543:
	v_lshl_add_u32 v146, s28, 8, v148
	v_ashrrev_i32_e32 v147, 31, v146
	v_lshlrev_b64 v[144:145], 6, v[146:147]
	v_lshl_add_u64 v[144:145], s[12:13], 0, v[144:145]
	global_load_dwordx4 v[156:159], v[144:145], off
	global_load_dwordx4 v[160:163], v[144:145], off offset:16
	global_load_dwordx4 v[164:167], v[144:145], off offset:32
	global_load_dwordx4 v[168:171], v[144:145], off offset:48
	v_lshlrev_b64 v[174:175], 13, v[146:147]
	v_lshl_or_b32 v144, s60, 8, v150
	v_ashrrev_i32_e32 v145, 31, v144
	v_or_b32_e32 v172, 16, v146
	v_lshlrev_b64 v[144:145], 1, v[144:145]
	v_lshl_add_u64 v[174:175], s[8:9], 0, v[174:175]
	v_ashrrev_i32_e32 v173, 31, v172
	s_andn2_b64 vcc, exec, s[4:5]
	s_mov_b64 s[4:5], -1
	s_waitcnt vmcnt(0)
; __device__ __forceinline__ u32x4 pack8(const f32x4 a, const f32x4 b) { u32x4 w; w.x = cvt_pk_bf16(a[0], a[1]); w.y = cvt_pk_bf16(a[2], a[3]); w.z = cvt_pk_bf16(b[0], b[1]); w.w = cvt_pk_bf16(b[2], b[3]); return w; }
;     __device__ __forceinline__ void operator()(const f32x4 (&acc)[2][2][4][2], const Unit& u, int wr, int wc, int fr, int fq) const {
;     ...
;             for (int m = 0; m < 4; ++m) { const int row = rbase + ai * 128 + m * 16; const f32x4* sp = (const f32x4*)(SSP + (size_t)row * 16);
;                 const f32x4 s4 = (sp[0] + sp[1]) + (sp[2] + sp[3]); const float rstd = __builtin_amdgcn_rsqf(((s4[0] + s4[1]) + (s4[2] + s4[3])) * (1.0f / 1024.0f) + EPS);
; #pragma unroll
;                 for (int bj = 0; bj < 2; ++bj) { f32x4 v0 = acc[ai][bj][m][0] * rstd, v1 = acc[ai][bj][m][1] * rstd;
; #pragma unroll
;                     for (int i = 0; i < 4; ++i) { const float a = fmaxf(v0[i], 0.f), b = fmaxf(v1[i], 0.f); v0[i] = a * a; v1[i] = b * b; }
;                     *(u32x4*)(Z + (size_t)row * FF + cb + bj * 128) = pack8(v0, v1); }
;                 asm volatile("" ::: "memory"); }
	v_pk_add_f32 v[158:159], v[158:159], v[162:163]
	v_pk_add_f32 v[156:157], v[156:157], v[160:161]
	v_pk_add_f32 v[160:161], v[166:167], v[170:171]
	v_pk_add_f32 v[162:163], v[164:165], v[168:169]
	v_pk_add_f32 v[158:159], v[158:159], v[160:161]
	v_pk_add_f32 v[156:157], v[156:157], v[162:163]
	s_nop 0
	v_pk_mov_b32 v[160:161], v[156:157], v[158:159] op_sel:[1,0]
	v_mov_b32_e32 v157, v159
	v_pk_add_f32 v[156:157], v[160:161], v[156:157]
	v_lshl_add_u64 v[160:161], v[174:175], 0, v[144:145]
	v_add_f32_e32 v147, v156, v157
	v_fmamk_f32 v147, v147, 0x3a800000, v154
	v_rsq_f32_e32 v156, v147
	v_lshlrev_b64 v[158:159], 6, v[172:173]
	v_lshl_add_u64 v[158:159], s[12:13], 0, v[158:159]
	v_pk_mul_f32 v[126:127], v[126:127], v[156:157] op_sel_hi:[1,0]
	v_pk_mul_f32 v[124:125], v[124:125], v[156:157] op_sel_hi:[1,0]
	v_pk_mul_f32 v[122:123], v[122:123], v[156:157] op_sel_hi:[1,0]
	v_pk_mul_f32 v[120:121], v[120:121], v[156:157] op_sel_hi:[1,0]
	v_pk_mul_f32 v[114:115], v[114:115], v[156:157] op_sel_hi:[1,0]
	v_pk_mul_f32 v[112:113], v[112:113], v[156:157] op_sel_hi:[1,0]
	v_pk_mul_f32 v[118:119], v[118:119], v[156:157] op_sel_hi:[1,0]
	v_pk_mul_f32 v[116:117], v[116:117], v[156:157] op_sel_hi:[1,0]
	v_max_f32_e32 v124, 0, v124
	v_max_f32_e32 v120, 0, v120
	v_max_f32_e32 v125, 0, v125
	v_max_f32_e32 v121, 0, v121
	v_max_f32_e32 v126, 0, v126
	v_max_f32_e32 v122, 0, v122
	v_max_f32_e32 v127, 0, v127
	v_max_f32_e32 v123, 0, v123
	v_max_f32_e32 v112, 0, v112
	v_max_f32_e32 v113, 0, v113
	v_max_f32_e32 v114, 0, v114
	v_max_f32_e32 v115, 0, v115
	v_max_f32_e32 v116, 0, v116
	v_max_f32_e32 v117, 0, v117
	v_max_f32_e32 v118, 0, v118
	v_max_f32_e32 v119, 0, v119
	v_mul_f32_e32 v124, v124, v124
	v_mul_f32_e32 v120, v120, v120
	v_mul_f32_e32 v125, v125, v125
	v_mul_f32_e32 v121, v121, v121
	v_mul_f32_e32 v126, v126, v126
	v_mul_f32_e32 v122, v122, v122
	v_mul_f32_e32 v127, v127, v127
	v_mul_f32_e32 v123, v123, v123
	v_mul_f32_e32 v147, v112, v112
	v_mul_f32_e32 v155, v113, v113
	v_mul_f32_e32 v156, v114, v114
	v_mul_f32_e32 v157, v115, v115
	v_cvt_pk_bf16_f32 v112, v124, v125
	v_cvt_pk_bf16_f32 v113, v126, v127
	v_cvt_pk_bf16_f32 v114, v120, v121
	v_cvt_pk_bf16_f32 v115, v122, v123
	v_mul_f32_e32 v116, v116, v116
	v_mul_f32_e32 v117, v117, v117
	v_mul_f32_e32 v118, v118, v118
	v_mul_f32_e32 v119, v119, v119
	global_store_dwordx4 v[160:161], v[112:115], off
	s_nop 1
	v_cvt_pk_bf16_f32 v112, v116, v117
	v_cvt_pk_bf16_f32 v113, v118, v119
	v_cvt_pk_bf16_f32 v114, v147, v155
	v_cvt_pk_bf16_f32 v115, v156, v157
	global_store_dwordx4 v[160:161], v[112:115], off offset:256
	global_load_dwordx4 v[112:115], v[158:159], off
	global_load_dwordx4 v[116:119], v[158:159], off offset:16
	global_load_dwordx4 v[120:123], v[158:159], off offset:32
	global_load_dwordx4 v[124:127], v[158:159], off offset:48
	v_lshlrev_b64 v[158:159], 13, v[172:173]
	v_or_b32_e32 v156, 32, v146
	v_ashrrev_i32_e32 v157, 31, v156
	v_lshlrev_b64 v[160:161], 6, v[156:157]
	s_waitcnt vmcnt(2)
	v_pk_add_f32 v[114:115], v[114:115], v[118:119]
	v_pk_add_f32 v[112:113], v[112:113], v[116:117]
	s_waitcnt vmcnt(0)
	v_pk_add_f32 v[116:117], v[122:123], v[126:127]
	v_pk_add_f32 v[118:119], v[120:121], v[124:125]
	v_pk_add_f32 v[114:115], v[114:115], v[116:117]
	v_pk_add_f32 v[112:113], v[112:113], v[118:119]
	s_nop 0
	v_pk_mov_b32 v[116:117], v[112:113], v[114:115] op_sel:[1,0]
	v_mov_b32_e32 v113, v115
	v_pk_add_f32 v[112:113], v[116:117], v[112:113]
	v_lshl_add_u64 v[114:115], s[8:9], 0, v[158:159]
	v_add_f32_e32 v112, v112, v113
	v_fmamk_f32 v112, v112, 0x3a800000, v154
	v_rsq_f32_e32 v112, v112
	v_lshl_add_u64 v[114:115], v[114:115], 0, v[144:145]
	v_lshl_add_u64 v[116:117], s[12:13], 0, v[160:161]
	v_pk_mul_f32 v[110:111], v[110:111], v[112:113] op_sel_hi:[1,0]
	v_pk_mul_f32 v[108:109], v[108:109], v[112:113] op_sel_hi:[1,0]
	v_pk_mul_f32 v[106:107], v[106:107], v[112:113] op_sel_hi:[1,0]
	v_pk_mul_f32 v[104:105], v[104:105], v[112:113] op_sel_hi:[1,0]
	v_pk_mul_f32 v[98:99], v[98:99], v[112:113] op_sel_hi:[1,0]
	v_pk_mul_f32 v[96:97], v[96:97], v[112:113] op_sel_hi:[1,0]
	v_pk_mul_f32 v[102:103], v[102:103], v[112:113] op_sel_hi:[1,0]
	v_pk_mul_f32 v[100:101], v[100:101], v[112:113] op_sel_hi:[1,0]
	v_max_f32_e32 v108, 0, v108
	v_max_f32_e32 v104, 0, v104
	v_max_f32_e32 v109, 0, v109
	v_max_f32_e32 v105, 0, v105
	v_max_f32_e32 v110, 0, v110
	v_max_f32_e32 v106, 0, v106
	v_max_f32_e32 v111, 0, v111
	v_max_f32_e32 v107, 0, v107
	v_max_f32_e32 v96, 0, v96
	v_max_f32_e32 v97, 0, v97
	v_max_f32_e32 v98, 0, v98
	v_max_f32_e32 v99, 0, v99
	v_max_f32_e32 v100, 0, v100
	v_max_f32_e32 v101, 0, v101
	v_max_f32_e32 v102, 0, v102
	v_max_f32_e32 v103, 0, v103
	v_mul_f32_e32 v108, v108, v108
	v_mul_f32_e32 v104, v104, v104
	v_mul_f32_e32 v109, v109, v109
	v_mul_f32_e32 v105, v105, v105
	v_mul_f32_e32 v110, v110, v110
	v_mul_f32_e32 v106, v106, v106
	v_mul_f32_e32 v111, v111, v111
	v_mul_f32_e32 v107, v107, v107
	v_mul_f32_e32 v112, v96, v96
	v_mul_f32_e32 v113, v97, v97
	v_mul_f32_e32 v118, v98, v98
	v_mul_f32_e32 v119, v99, v99
	v_cvt_pk_bf16_f32 v96, v108, v109
	v_cvt_pk_bf16_f32 v97, v110, v111
	v_cvt_pk_bf16_f32 v98, v104, v105
	v_cvt_pk_bf16_f32 v99, v106, v107
	v_mul_f32_e32 v100, v100, v100
	v_mul_f32_e32 v101, v101, v101
	v_mul_f32_e32 v102, v102, v102
	v_mul_f32_e32 v103, v103, v103
	global_store_dwordx4 v[114:115], v[96:99], off
	s_nop 1
	v_cvt_pk_bf16_f32 v96, v100, v101
	v_cvt_pk_bf16_f32 v97, v102, v103
	v_cvt_pk_bf16_f32 v98, v112, v113
	v_cvt_pk_bf16_f32 v99, v118, v119
	global_store_dwordx4 v[114:115], v[96:99], off offset:256
	global_load_dwordx4 v[96:99], v[116:117], off
	global_load_dwordx4 v[100:103], v[116:117], off offset:16
	global_load_dwordx4 v[104:107], v[116:117], off offset:32
	global_load_dwordx4 v[108:111], v[116:117], off offset:48
	v_lshlrev_b64 v[114:115], 13, v[156:157]
	v_or_b32_e32 v112, 48, v146
	v_ashrrev_i32_e32 v113, 31, v112
	v_lshlrev_b64 v[116:117], 6, v[112:113]
	s_waitcnt vmcnt(2)
; __device__ __forceinline__ u32x4 pack8(const f32x4 a, const f32x4 b) { u32x4 w; w.x = cvt_pk_bf16(a[0], a[1]); w.y = cvt_pk_bf16(a[2], a[3]); w.z = cvt_pk_bf16(b[0], b[1]); w.w = cvt_pk_bf16(b[2], b[3]); return w; }
;     __device__ __forceinline__ void operator()(const f32x4 (&acc)[2][2][4][2], const Unit& u, int wr, int wc, int fr, int fq) const {
;     ...
;             for (int m = 0; m < 4; ++m) { const int row = rbase + ai * 128 + m * 16; const f32x4* sp = (const f32x4*)(SSP + (size_t)row * 16);
;                 const f32x4 s4 = (sp[0] + sp[1]) + (sp[2] + sp[3]); const float rstd = __builtin_amdgcn_rsqf(((s4[0] + s4[1]) + (s4[2] + s4[3])) * (1.0f / 1024.0f) + EPS);
; #pragma unroll
;                 for (int bj = 0; bj < 2; ++bj) { f32x4 v0 = acc[ai][bj][m][0] * rstd, v1 = acc[ai][bj][m][1] * rstd;
; #pragma unroll
;                     for (int i = 0; i < 4; ++i) { const float a = fmaxf(v0[i], 0.f), b = fmaxf(v1[i], 0.f); v0[i] = a * a; v1[i] = b * b; }
;                     *(u32x4*)(Z + (size_t)row * FF + cb + bj * 128) = pack8(v0, v1); }
;                 asm volatile("" ::: "memory"); }
	v_pk_add_f32 v[98:99], v[98:99], v[102:103]
	v_pk_add_f32 v[96:97], v[96:97], v[100:101]
	s_waitcnt vmcnt(0)
	v_pk_add_f32 v[100:101], v[106:107], v[110:111]
	v_pk_add_f32 v[102:103], v[104:105], v[108:109]
	v_pk_add_f32 v[98:99], v[98:99], v[100:101]
	v_pk_add_f32 v[96:97], v[96:97], v[102:103]
	s_nop 0
	v_pk_mov_b32 v[100:101], v[96:97], v[98:99] op_sel:[1,0]
	v_mov_b32_e32 v97, v99
	v_pk_add_f32 v[96:97], v[100:101], v[96:97]
	v_lshl_add_u64 v[98:99], s[8:9], 0, v[114:115]
	v_add_f32_e32 v96, v96, v97
	v_fmamk_f32 v96, v96, 0x3a800000, v154
	v_rsq_f32_e32 v96, v96
	v_lshl_add_u64 v[98:99], v[98:99], 0, v[144:145]
	v_lshl_add_u64 v[100:101], s[12:13], 0, v[116:117]
	v_pk_mul_f32 v[94:95], v[94:95], v[96:97] op_sel_hi:[1,0]
	v_pk_mul_f32 v[92:93], v[92:93], v[96:97] op_sel_hi:[1,0]
	v_pk_mul_f32 v[90:91], v[90:91], v[96:97] op_sel_hi:[1,0]
	v_pk_mul_f32 v[88:89], v[88:89], v[96:97] op_sel_hi:[1,0]
	v_pk_mul_f32 v[82:83], v[82:83], v[96:97] op_sel_hi:[1,0]
	v_pk_mul_f32 v[80:81], v[80:81], v[96:97] op_sel_hi:[1,0]
	v_pk_mul_f32 v[86:87], v[86:87], v[96:97] op_sel_hi:[1,0]
	v_pk_mul_f32 v[84:85], v[84:85], v[96:97] op_sel_hi:[1,0]
	v_max_f32_e32 v92, 0, v92
	v_max_f32_e32 v88, 0, v88
	v_max_f32_e32 v93, 0, v93
	v_max_f32_e32 v89, 0, v89
	v_max_f32_e32 v94, 0, v94
	v_max_f32_e32 v90, 0, v90
	v_max_f32_e32 v95, 0, v95
	v_max_f32_e32 v91, 0, v91
	v_max_f32_e32 v80, 0, v80
	v_max_f32_e32 v81, 0, v81
	v_max_f32_e32 v82, 0, v82
	v_max_f32_e32 v83, 0, v83
	v_max_f32_e32 v84, 0, v84
	v_max_f32_e32 v85, 0, v85
	v_max_f32_e32 v86, 0, v86
	v_max_f32_e32 v87, 0, v87
	v_mul_f32_e32 v92, v92, v92
	v_mul_f32_e32 v88, v88, v88
	v_mul_f32_e32 v93, v93, v93
	v_mul_f32_e32 v89, v89, v89
	v_mul_f32_e32 v94, v94, v94
	v_mul_f32_e32 v90, v90, v90
	v_mul_f32_e32 v95, v95, v95
	v_mul_f32_e32 v91, v91, v91
	v_mul_f32_e32 v96, v80, v80
	v_mul_f32_e32 v97, v81, v81
	v_mul_f32_e32 v102, v82, v82
	v_mul_f32_e32 v103, v83, v83
	v_cvt_pk_bf16_f32 v80, v92, v93
	v_cvt_pk_bf16_f32 v81, v94, v95
	v_cvt_pk_bf16_f32 v82, v88, v89
	v_cvt_pk_bf16_f32 v83, v90, v91
	v_mul_f32_e32 v84, v84, v84
	v_mul_f32_e32 v85, v85, v85
	v_mul_f32_e32 v86, v86, v86
	v_mul_f32_e32 v87, v87, v87
	global_store_dwordx4 v[98:99], v[80:83], off
	s_nop 1
	v_cvt_pk_bf16_f32 v80, v84, v85
	v_cvt_pk_bf16_f32 v81, v86, v87
	v_cvt_pk_bf16_f32 v82, v96, v97
	v_cvt_pk_bf16_f32 v83, v102, v103
	global_store_dwordx4 v[98:99], v[80:83], off offset:256
	global_load_dwordx4 v[80:83], v[100:101], off
	global_load_dwordx4 v[84:87], v[100:101], off offset:16
	global_load_dwordx4 v[88:91], v[100:101], off offset:32
	global_load_dwordx4 v[92:95], v[100:101], off offset:48
	v_lshlrev_b64 v[98:99], 13, v[112:113]
	v_add_u32_e32 v96, 0x80, v146
	v_ashrrev_i32_e32 v97, 31, v96
	v_lshlrev_b64 v[100:101], 6, v[96:97]
	s_waitcnt vmcnt(2)
	v_pk_add_f32 v[82:83], v[82:83], v[86:87]
	v_pk_add_f32 v[80:81], v[80:81], v[84:85]
	s_waitcnt vmcnt(0)
	v_pk_add_f32 v[84:85], v[90:91], v[94:95]
	v_pk_add_f32 v[86:87], v[88:89], v[92:93]
	v_pk_add_f32 v[82:83], v[82:83], v[84:85]
	v_pk_add_f32 v[80:81], v[80:81], v[86:87]
	s_nop 0
	v_pk_mov_b32 v[84:85], v[80:81], v[82:83] op_sel:[1,0]
	v_mov_b32_e32 v81, v83
	v_pk_add_f32 v[80:81], v[84:85], v[80:81]
	v_lshl_add_u64 v[82:83], s[8:9], 0, v[98:99]
	v_add_f32_e32 v80, v80, v81
	v_fmamk_f32 v80, v80, 0x3a800000, v154
	v_rsq_f32_e32 v80, v80
	v_lshl_add_u64 v[82:83], v[82:83], 0, v[144:145]
	v_lshl_add_u64 v[84:85], s[12:13], 0, v[100:101]
	v_pk_mul_f32 v[78:79], v[78:79], v[80:81] op_sel_hi:[1,0]
	v_pk_mul_f32 v[76:77], v[76:77], v[80:81] op_sel_hi:[1,0]
	v_pk_mul_f32 v[74:75], v[74:75], v[80:81] op_sel_hi:[1,0]
	v_pk_mul_f32 v[72:73], v[72:73], v[80:81] op_sel_hi:[1,0]
	v_pk_mul_f32 v[66:67], v[66:67], v[80:81] op_sel_hi:[1,0]
	v_pk_mul_f32 v[64:65], v[64:65], v[80:81] op_sel_hi:[1,0]
	v_pk_mul_f32 v[70:71], v[70:71], v[80:81] op_sel_hi:[1,0]
	v_pk_mul_f32 v[68:69], v[68:69], v[80:81] op_sel_hi:[1,0]
	v_max_f32_e32 v76, 0, v76
	v_max_f32_e32 v72, 0, v72
	v_max_f32_e32 v77, 0, v77
	v_max_f32_e32 v73, 0, v73
	v_max_f32_e32 v78, 0, v78
	v_max_f32_e32 v74, 0, v74
	v_max_f32_e32 v79, 0, v79
	v_max_f32_e32 v75, 0, v75
	v_max_f32_e32 v64, 0, v64
	v_max_f32_e32 v65, 0, v65
	v_max_f32_e32 v66, 0, v66
	v_max_f32_e32 v67, 0, v67
	v_max_f32_e32 v68, 0, v68
	v_max_f32_e32 v69, 0, v69
	v_max_f32_e32 v70, 0, v70
	v_max_f32_e32 v71, 0, v71
	v_mul_f32_e32 v76, v76, v76
	v_mul_f32_e32 v72, v72, v72
	v_mul_f32_e32 v77, v77, v77
	v_mul_f32_e32 v73, v73, v73
	v_mul_f32_e32 v78, v78, v78
	v_mul_f32_e32 v74, v74, v74
	v_mul_f32_e32 v79, v79, v79
	v_mul_f32_e32 v75, v75, v75
	v_mul_f32_e32 v80, v64, v64
	v_mul_f32_e32 v81, v65, v65
	v_mul_f32_e32 v86, v66, v66
	v_mul_f32_e32 v87, v67, v67
	v_cvt_pk_bf16_f32 v64, v76, v77
	v_cvt_pk_bf16_f32 v65, v78, v79
	v_cvt_pk_bf16_f32 v66, v72, v73
	v_cvt_pk_bf16_f32 v67, v74, v75
	v_mul_f32_e32 v68, v68, v68
	v_mul_f32_e32 v69, v69, v69
	v_mul_f32_e32 v70, v70, v70
	v_mul_f32_e32 v71, v71, v71
	global_store_dwordx4 v[82:83], v[64:67], off
	s_nop 1
	v_cvt_pk_bf16_f32 v64, v68, v69
	v_cvt_pk_bf16_f32 v65, v70, v71
	v_cvt_pk_bf16_f32 v66, v80, v81
	v_cvt_pk_bf16_f32 v67, v86, v87
	global_store_dwordx4 v[82:83], v[64:67], off offset:256
	global_load_dwordx4 v[64:67], v[84:85], off
	global_load_dwordx4 v[68:71], v[84:85], off offset:16
	global_load_dwordx4 v[72:75], v[84:85], off offset:32
	global_load_dwordx4 v[76:79], v[84:85], off offset:48
	v_lshlrev_b64 v[82:83], 13, v[96:97]
	v_add_u32_e32 v80, 0x90, v146
	v_ashrrev_i32_e32 v81, 31, v80
	v_lshlrev_b64 v[84:85], 6, v[80:81]
	s_waitcnt vmcnt(2)
	v_pk_add_f32 v[66:67], v[66:67], v[70:71]
	v_pk_add_f32 v[64:65], v[64:65], v[68:69]
	s_waitcnt vmcnt(0)
; __device__ __forceinline__ u32x4 pack8(const f32x4 a, const f32x4 b) { u32x4 w; w.x = cvt_pk_bf16(a[0], a[1]); w.y = cvt_pk_bf16(a[2], a[3]); w.z = cvt_pk_bf16(b[0], b[1]); w.w = cvt_pk_bf16(b[2], b[3]); return w; }
;     __device__ __forceinline__ void operator()(const f32x4 (&acc)[2][2][4][2], const Unit& u, int wr, int wc, int fr, int fq) const {
;     ...
;             for (int m = 0; m < 4; ++m) { const int row = rbase + ai * 128 + m * 16; const f32x4* sp = (const f32x4*)(SSP + (size_t)row * 16);
;                 const f32x4 s4 = (sp[0] + sp[1]) + (sp[2] + sp[3]); const float rstd = __builtin_amdgcn_rsqf(((s4[0] + s4[1]) + (s4[2] + s4[3])) * (1.0f / 1024.0f) + EPS);
; #pragma unroll
;                 for (int bj = 0; bj < 2; ++bj) { f32x4 v0 = acc[ai][bj][m][0] * rstd, v1 = acc[ai][bj][m][1] * rstd;
; #pragma unroll
;                     for (int i = 0; i < 4; ++i) { const float a = fmaxf(v0[i], 0.f), b = fmaxf(v1[i], 0.f); v0[i] = a * a; v1[i] = b * b; }
;                     *(u32x4*)(Z + (size_t)row * FF + cb + bj * 128) = pack8(v0, v1); }
;                 asm volatile("" ::: "memory"); }
	v_pk_add_f32 v[68:69], v[74:75], v[78:79]
	v_pk_add_f32 v[70:71], v[72:73], v[76:77]
	v_pk_add_f32 v[66:67], v[66:67], v[68:69]
	v_pk_add_f32 v[64:65], v[64:65], v[70:71]
	s_nop 0
	v_pk_mov_b32 v[68:69], v[64:65], v[66:67] op_sel:[1,0]
	v_mov_b32_e32 v65, v67
	v_pk_add_f32 v[64:65], v[68:69], v[64:65]
	v_lshl_add_u64 v[66:67], s[8:9], 0, v[82:83]
	v_add_f32_e32 v64, v64, v65
	v_fmamk_f32 v64, v64, 0x3a800000, v154
	v_rsq_f32_e32 v64, v64
	v_lshl_add_u64 v[66:67], v[66:67], 0, v[144:145]
	v_lshl_add_u64 v[68:69], s[12:13], 0, v[84:85]
	v_pk_mul_f32 v[62:63], v[62:63], v[64:65] op_sel_hi:[1,0]
	v_pk_mul_f32 v[60:61], v[60:61], v[64:65] op_sel_hi:[1,0]
	v_pk_mul_f32 v[58:59], v[58:59], v[64:65] op_sel_hi:[1,0]
	v_pk_mul_f32 v[56:57], v[56:57], v[64:65] op_sel_hi:[1,0]
	v_pk_mul_f32 v[50:51], v[50:51], v[64:65] op_sel_hi:[1,0]
	v_pk_mul_f32 v[48:49], v[48:49], v[64:65] op_sel_hi:[1,0]
	v_pk_mul_f32 v[54:55], v[54:55], v[64:65] op_sel_hi:[1,0]
	v_pk_mul_f32 v[52:53], v[52:53], v[64:65] op_sel_hi:[1,0]
	v_max_f32_e32 v60, 0, v60
	v_max_f32_e32 v56, 0, v56
	v_max_f32_e32 v61, 0, v61
	v_max_f32_e32 v57, 0, v57
	v_max_f32_e32 v62, 0, v62
	v_max_f32_e32 v58, 0, v58
	v_max_f32_e32 v63, 0, v63
	v_max_f32_e32 v59, 0, v59
	v_max_f32_e32 v48, 0, v48
	v_max_f32_e32 v49, 0, v49
	v_max_f32_e32 v50, 0, v50
	v_max_f32_e32 v51, 0, v51
	v_max_f32_e32 v52, 0, v52
	v_max_f32_e32 v53, 0, v53
	v_max_f32_e32 v54, 0, v54
	v_max_f32_e32 v55, 0, v55
	v_mul_f32_e32 v60, v60, v60
	v_mul_f32_e32 v56, v56, v56
	v_mul_f32_e32 v61, v61, v61
	v_mul_f32_e32 v57, v57, v57
	v_mul_f32_e32 v62, v62, v62
	v_mul_f32_e32 v58, v58, v58
	v_mul_f32_e32 v63, v63, v63
	v_mul_f32_e32 v59, v59, v59
	v_mul_f32_e32 v64, v48, v48
	v_mul_f32_e32 v65, v49, v49
	v_mul_f32_e32 v70, v50, v50
	v_mul_f32_e32 v71, v51, v51
	v_cvt_pk_bf16_f32 v48, v60, v61
	v_cvt_pk_bf16_f32 v49, v62, v63
	v_cvt_pk_bf16_f32 v50, v56, v57
	v_cvt_pk_bf16_f32 v51, v58, v59
	v_mul_f32_e32 v52, v52, v52
	v_mul_f32_e32 v53, v53, v53
	v_mul_f32_e32 v54, v54, v54
	v_mul_f32_e32 v55, v55, v55
	global_store_dwordx4 v[66:67], v[48:51], off
	s_nop 1
	v_cvt_pk_bf16_f32 v48, v52, v53
	v_cvt_pk_bf16_f32 v49, v54, v55
	v_cvt_pk_bf16_f32 v50, v64, v65
	v_cvt_pk_bf16_f32 v51, v70, v71
	global_store_dwordx4 v[66:67], v[48:51], off offset:256
	global_load_dwordx4 v[48:51], v[68:69], off
	global_load_dwordx4 v[52:55], v[68:69], off offset:16
	global_load_dwordx4 v[56:59], v[68:69], off offset:32
	global_load_dwordx4 v[60:63], v[68:69], off offset:48
	v_lshlrev_b64 v[66:67], 13, v[80:81]
	v_add_u32_e32 v64, 0xa0, v146
	v_ashrrev_i32_e32 v65, 31, v64
	v_lshlrev_b64 v[68:69], 6, v[64:65]
	s_waitcnt vmcnt(2)
	v_pk_add_f32 v[50:51], v[50:51], v[54:55]
	v_pk_add_f32 v[48:49], v[48:49], v[52:53]
	s_waitcnt vmcnt(0)
	v_pk_add_f32 v[52:53], v[58:59], v[62:63]
	v_pk_add_f32 v[54:55], v[56:57], v[60:61]
	v_pk_add_f32 v[50:51], v[50:51], v[52:53]
	v_pk_add_f32 v[48:49], v[48:49], v[54:55]
	s_nop 0
	v_pk_mov_b32 v[52:53], v[48:49], v[50:51] op_sel:[1,0]
	v_mov_b32_e32 v49, v51
	v_pk_add_f32 v[48:49], v[52:53], v[48:49]
	v_lshl_add_u64 v[50:51], s[8:9], 0, v[66:67]
	v_add_f32_e32 v48, v48, v49
	v_fmamk_f32 v48, v48, 0x3a800000, v154
	v_rsq_f32_e32 v48, v48
	v_lshl_add_u64 v[50:51], v[50:51], 0, v[144:145]
	v_lshl_add_u64 v[52:53], s[12:13], 0, v[68:69]
	v_pk_mul_f32 v[46:47], v[46:47], v[48:49] op_sel_hi:[1,0]
	v_pk_mul_f32 v[44:45], v[44:45], v[48:49] op_sel_hi:[1,0]
	v_pk_mul_f32 v[42:43], v[42:43], v[48:49] op_sel_hi:[1,0]
	v_pk_mul_f32 v[40:41], v[40:41], v[48:49] op_sel_hi:[1,0]
	v_pk_mul_f32 v[34:35], v[34:35], v[48:49] op_sel_hi:[1,0]
	v_pk_mul_f32 v[32:33], v[32:33], v[48:49] op_sel_hi:[1,0]
	v_pk_mul_f32 v[38:39], v[38:39], v[48:49] op_sel_hi:[1,0]
	v_pk_mul_f32 v[36:37], v[36:37], v[48:49] op_sel_hi:[1,0]
	v_max_f32_e32 v44, 0, v44
	v_max_f32_e32 v40, 0, v40
	v_max_f32_e32 v45, 0, v45
	v_max_f32_e32 v41, 0, v41
	v_max_f32_e32 v46, 0, v46
	v_max_f32_e32 v42, 0, v42
	v_max_f32_e32 v47, 0, v47
	v_max_f32_e32 v43, 0, v43
	v_max_f32_e32 v32, 0, v32
	v_max_f32_e32 v33, 0, v33
	v_max_f32_e32 v34, 0, v34
	v_max_f32_e32 v35, 0, v35
	v_max_f32_e32 v36, 0, v36
	v_max_f32_e32 v37, 0, v37
	v_max_f32_e32 v38, 0, v38
	v_max_f32_e32 v39, 0, v39
	v_mul_f32_e32 v44, v44, v44
	v_mul_f32_e32 v40, v40, v40
	v_mul_f32_e32 v45, v45, v45
	v_mul_f32_e32 v41, v41, v41
	v_mul_f32_e32 v46, v46, v46
	v_mul_f32_e32 v42, v42, v42
	v_mul_f32_e32 v47, v47, v47
	v_mul_f32_e32 v43, v43, v43
	v_mul_f32_e32 v48, v32, v32
	v_mul_f32_e32 v49, v33, v33
	v_mul_f32_e32 v54, v34, v34
	v_mul_f32_e32 v55, v35, v35
	v_cvt_pk_bf16_f32 v32, v44, v45
	v_cvt_pk_bf16_f32 v33, v46, v47
	v_cvt_pk_bf16_f32 v34, v40, v41
	v_cvt_pk_bf16_f32 v35, v42, v43
	v_mul_f32_e32 v36, v36, v36
	v_mul_f32_e32 v37, v37, v37
	v_mul_f32_e32 v38, v38, v38
	v_mul_f32_e32 v39, v39, v39
	global_store_dwordx4 v[50:51], v[32:35], off
	s_nop 1
	v_cvt_pk_bf16_f32 v32, v36, v37
	v_cvt_pk_bf16_f32 v33, v38, v39
	v_cvt_pk_bf16_f32 v34, v48, v49
	v_cvt_pk_bf16_f32 v35, v54, v55
	global_store_dwordx4 v[50:51], v[32:35], off offset:256
	global_load_dwordx4 v[32:35], v[52:53], off
	global_load_dwordx4 v[36:39], v[52:53], off offset:16
	global_load_dwordx4 v[40:43], v[52:53], off offset:32
	global_load_dwordx4 v[44:47], v[52:53], off offset:48
	v_lshlrev_b64 v[50:51], 13, v[64:65]
	v_add_u32_e32 v48, 0xb0, v146
	v_ashrrev_i32_e32 v49, 31, v48
	v_lshlrev_b64 v[52:53], 6, v[48:49]
	s_waitcnt vmcnt(2)
; __device__ __forceinline__ u32x4 pack8(const f32x4 a, const f32x4 b) { u32x4 w; w.x = cvt_pk_bf16(a[0], a[1]); w.y = cvt_pk_bf16(a[2], a[3]); w.z = cvt_pk_bf16(b[0], b[1]); w.w = cvt_pk_bf16(b[2], b[3]); return w; }
;     __device__ __forceinline__ void operator()(const f32x4 (&acc)[2][2][4][2], const Unit& u, int wr, int wc, int fr, int fq) const {
;     ...
;             for (int m = 0; m < 4; ++m) { const int row = rbase + ai * 128 + m * 16; const f32x4* sp = (const f32x4*)(SSP + (size_t)row * 16);
;                 const f32x4 s4 = (sp[0] + sp[1]) + (sp[2] + sp[3]); const float rstd = __builtin_amdgcn_rsqf(((s4[0] + s4[1]) + (s4[2] + s4[3])) * (1.0f / 1024.0f) + EPS);
; #pragma unroll
;                 for (int bj = 0; bj < 2; ++bj) { f32x4 v0 = acc[ai][bj][m][0] * rstd, v1 = acc[ai][bj][m][1] * rstd;
; #pragma unroll
;                     for (int i = 0; i < 4; ++i) { const float a = fmaxf(v0[i], 0.f), b = fmaxf(v1[i], 0.f); v0[i] = a * a; v1[i] = b * b; }
;                     *(u32x4*)(Z + (size_t)row * FF + cb + bj * 128) = pack8(v0, v1); }
;                 asm volatile("" ::: "memory"); }
	v_pk_add_f32 v[34:35], v[34:35], v[38:39]
	v_pk_add_f32 v[32:33], v[32:33], v[36:37]
	s_waitcnt vmcnt(0)
	v_pk_add_f32 v[36:37], v[42:43], v[46:47]
	v_pk_add_f32 v[38:39], v[40:41], v[44:45]
	v_pk_add_f32 v[34:35], v[34:35], v[36:37]
	v_pk_add_f32 v[32:33], v[32:33], v[38:39]
	s_nop 0
	v_pk_mov_b32 v[36:37], v[32:33], v[34:35] op_sel:[1,0]
	v_mov_b32_e32 v33, v35
	v_pk_add_f32 v[32:33], v[36:37], v[32:33]
	v_lshl_add_u64 v[34:35], s[8:9], 0, v[50:51]
	v_add_f32_e32 v32, v32, v33
	v_fmamk_f32 v32, v32, 0x3a800000, v154
	v_rsq_f32_e32 v32, v32
	v_lshl_add_u64 v[34:35], v[34:35], 0, v[144:145]
	v_lshl_add_u64 v[36:37], s[12:13], 0, v[52:53]
	v_pk_mul_f32 v[30:31], v[30:31], v[32:33] op_sel_hi:[1,0]
	v_pk_mul_f32 v[28:29], v[28:29], v[32:33] op_sel_hi:[1,0]
	v_pk_mul_f32 v[26:27], v[26:27], v[32:33] op_sel_hi:[1,0]
	v_pk_mul_f32 v[24:25], v[24:25], v[32:33] op_sel_hi:[1,0]
	v_pk_mul_f32 v[18:19], v[18:19], v[32:33] op_sel_hi:[1,0]
	v_pk_mul_f32 v[16:17], v[16:17], v[32:33] op_sel_hi:[1,0]
	v_pk_mul_f32 v[22:23], v[22:23], v[32:33] op_sel_hi:[1,0]
	v_pk_mul_f32 v[20:21], v[20:21], v[32:33] op_sel_hi:[1,0]
	v_max_f32_e32 v28, 0, v28
	v_max_f32_e32 v24, 0, v24
	v_max_f32_e32 v29, 0, v29
	v_max_f32_e32 v25, 0, v25
	v_max_f32_e32 v30, 0, v30
	v_max_f32_e32 v26, 0, v26
	v_max_f32_e32 v31, 0, v31
	v_max_f32_e32 v27, 0, v27
	v_max_f32_e32 v16, 0, v16
	v_max_f32_e32 v17, 0, v17
	v_max_f32_e32 v18, 0, v18
	v_max_f32_e32 v19, 0, v19
	v_max_f32_e32 v20, 0, v20
	v_max_f32_e32 v21, 0, v21
	v_max_f32_e32 v22, 0, v22
	v_max_f32_e32 v23, 0, v23
	v_mul_f32_e32 v28, v28, v28
	v_mul_f32_e32 v24, v24, v24
	v_mul_f32_e32 v29, v29, v29
	v_mul_f32_e32 v25, v25, v25
	v_mul_f32_e32 v30, v30, v30
	v_mul_f32_e32 v26, v26, v26
	v_mul_f32_e32 v31, v31, v31
	v_mul_f32_e32 v27, v27, v27
	v_mul_f32_e32 v32, v16, v16
	v_mul_f32_e32 v33, v17, v17
	v_mul_f32_e32 v38, v18, v18
	v_mul_f32_e32 v39, v19, v19
	v_cvt_pk_bf16_f32 v16, v28, v29
	v_cvt_pk_bf16_f32 v17, v30, v31
	v_cvt_pk_bf16_f32 v18, v24, v25
	v_cvt_pk_bf16_f32 v19, v26, v27
	v_mul_f32_e32 v20, v20, v20
	v_mul_f32_e32 v21, v21, v21
	v_mul_f32_e32 v22, v22, v22
	v_mul_f32_e32 v23, v23, v23
	global_store_dwordx4 v[34:35], v[16:19], off
	s_nop 1
	v_cvt_pk_bf16_f32 v16, v20, v21
	v_cvt_pk_bf16_f32 v17, v22, v23
	v_cvt_pk_bf16_f32 v18, v32, v33
	v_cvt_pk_bf16_f32 v19, v38, v39
	global_store_dwordx4 v[34:35], v[16:19], off offset:256
	global_load_dwordx4 v[16:19], v[36:37], off
	global_load_dwordx4 v[20:23], v[36:37], off offset:16
	global_load_dwordx4 v[24:27], v[36:37], off offset:32
	global_load_dwordx4 v[28:31], v[36:37], off offset:48
	s_waitcnt vmcnt(2)
	v_pk_add_f32 v[18:19], v[18:19], v[22:23]
	v_pk_add_f32 v[16:17], v[16:17], v[20:21]
	s_waitcnt vmcnt(0)
	v_pk_add_f32 v[20:21], v[26:27], v[30:31]
	v_pk_add_f32 v[22:23], v[24:25], v[28:29]
	v_pk_add_f32 v[18:19], v[18:19], v[20:21]
	v_pk_add_f32 v[16:17], v[16:17], v[22:23]
	s_nop 0
	v_pk_mov_b32 v[20:21], v[16:17], v[18:19] op_sel:[1,0]
	v_mov_b32_e32 v17, v19
	v_pk_add_f32 v[16:17], v[20:21], v[16:17]
	v_lshlrev_b64 v[18:19], 13, v[48:49]
	v_add_f32_e32 v16, v16, v17
	v_fmamk_f32 v16, v16, 0x3a800000, v154
	v_rsq_f32_e32 v16, v16
	v_lshl_add_u64 v[18:19], s[8:9], 0, v[18:19]
	v_lshl_add_u64 v[18:19], v[18:19], 0, v[144:145]
	v_pk_mul_f32 v[14:15], v[14:15], v[16:17] op_sel_hi:[1,0]
	v_pk_mul_f32 v[12:13], v[12:13], v[16:17] op_sel_hi:[1,0]
	v_pk_mul_f32 v[10:11], v[10:11], v[16:17] op_sel_hi:[1,0]
	v_pk_mul_f32 v[8:9], v[8:9], v[16:17] op_sel_hi:[1,0]
	v_pk_mul_f32 v[2:3], v[2:3], v[16:17] op_sel_hi:[1,0]
	v_pk_mul_f32 v[0:1], v[0:1], v[16:17] op_sel_hi:[1,0]
	v_pk_mul_f32 v[6:7], v[6:7], v[16:17] op_sel_hi:[1,0]
	v_pk_mul_f32 v[4:5], v[4:5], v[16:17] op_sel_hi:[1,0]
	v_max_f32_e32 v12, 0, v12
	v_max_f32_e32 v8, 0, v8
	v_max_f32_e32 v13, 0, v13
	v_max_f32_e32 v9, 0, v9
	v_max_f32_e32 v14, 0, v14
	v_max_f32_e32 v10, 0, v10
	v_max_f32_e32 v15, 0, v15
	v_max_f32_e32 v11, 0, v11
	v_max_f32_e32 v0, 0, v0
	v_max_f32_e32 v1, 0, v1
	v_max_f32_e32 v2, 0, v2
	v_max_f32_e32 v3, 0, v3
	v_max_f32_e32 v4, 0, v4
	v_max_f32_e32 v5, 0, v5
	v_max_f32_e32 v6, 0, v6
	v_max_f32_e32 v7, 0, v7
	v_mul_f32_e32 v12, v12, v12
	v_mul_f32_e32 v8, v8, v8
	v_mul_f32_e32 v13, v13, v13
	v_mul_f32_e32 v9, v9, v9
	v_mul_f32_e32 v14, v14, v14
	v_mul_f32_e32 v10, v10, v10
	v_mul_f32_e32 v15, v15, v15
	v_mul_f32_e32 v11, v11, v11
	v_mul_f32_e32 v16, v0, v0
	v_mul_f32_e32 v17, v1, v1
	v_mul_f32_e32 v20, v2, v2
	v_mul_f32_e32 v21, v3, v3
	v_cvt_pk_bf16_f32 v0, v12, v13
	v_cvt_pk_bf16_f32 v1, v14, v15
	v_cvt_pk_bf16_f32 v2, v8, v9
	v_cvt_pk_bf16_f32 v3, v10, v11
	v_mul_f32_e32 v4, v4, v4
	v_mul_f32_e32 v5, v5, v5
	v_mul_f32_e32 v6, v6, v6
	v_mul_f32_e32 v7, v7, v7
	global_store_dwordx4 v[18:19], v[0:3], off
	s_nop 1
	v_cvt_pk_bf16_f32 v0, v4, v5
	v_cvt_pk_bf16_f32 v1, v6, v7
	v_cvt_pk_bf16_f32 v2, v16, v17
	v_cvt_pk_bf16_f32 v3, v20, v21
	global_store_dwordx4 v[18:19], v[0:3], off offset:256
	s_cbranch_vccnz .LBB0_1536
	s_andn2_b64 vcc, exec, s[6:7]
	s_cbranch_vccnz .LBB0_1535
	s_barrier
	s_branch .LBB0_1535

; #define PG8_STAGE(bufoff, gbase, voff) do { _Pragma("unroll") for (int _i = 0; _i < 2; ++_i) \
;         __builtin_amdgcn_global_load_lds((const unsigned*)((const char*)(gbase) + (voff)[_i]), (PG8_LAS unsigned*)(lds + (bufoff) + ldsw + _i * 8192), 16, 0, 0); } while (0)
; #define PG8_WAIT_V(n) asm volatile("s_waitcnt vmcnt(" #n ")" ::: "memory")
; #define PG8_BAR __builtin_amdgcn_s_barrier()
; template <class Epi, class Sched, bool ALIGN_EPI = false, bool SP2 = false>
; __device__ __forceinline__ void gemm_phase(PG8_LAS unsigned char* lds, const Gemm g, const Sched& S, const Epi& E) {
;     ...
;     for (int i = 0; i < 2; ++i) { int R, C; stage_rc(tid * 16 + i * 8192, R, C); const int Rb = Epi::PERM ? ((R & ~31) + perm32(R & 31)) : R;
;         voffA[i] = (unsigned)(R * K + C) * 2u; voffB[i] = (unsigned)(Rb * K + C) * 2u; }
;     const size_t kstep = (size_t)(BK * 2);
;     const size_t hstep = (size_t)HALF * K * 2;
;     const size_t tstep = 2 * hstep;
;     const unsigned ldsw = (unsigned)wid * 1024u;
;     const int aoff = lds_byte(wr * 64 + fr, fq * 8), boff = lds_byte(wc * 32 + fr, fq * 8);
;     ...
;         PG8_STAGE(PG8_SB(0, 0), cB, voffB); PG8_STAGE(PG8_SB(0, 1), cB + hstep, voffB); PG8_STAGE(PG8_SA(0, 0), cA, voffA); PG8_STAGE(PG8_SA(0, 1), cA + hstep, voffA);
;         if (wr == 1) PG8_BAR;
;         PG8_WAIT_V(2); PG8_BAR;
;         PG8_STAGE(PG8_SB(1, 0), cB + kstep, voffB); PG8_STAGE(PG8_SA(1, 0), cA + kstep, voffA); PG8_STAGE(PG8_SB(1, 1), cB + hstep + kstep, voffB);
;         PG8_WAIT_V(6); PG8_BAR;
.LBB0_2130:
	s_and_b64 s[10:11], s[70:71], exec
	s_cselect_b32 s3, 0xd0, s3
	s_lshl_b32 s6, s6, 5
	s_and_b32 s12, s6, 0x60
	s_mov_b64 s[6:7], 0x80
	s_add_i32 m0, s27, 0x18000
	v_lshl_add_u64 v[6:7], v[6:7], 0, s[6:7]
	s_lshl_b32 s9, s8, 13
	s_lshl_b32 s13, s12, 7
	s_waitcnt vmcnt(2)
	s_barrier
	global_load_lds_dwordx4 v[6:7], off
	v_lshl_add_u64 v[4:5], v[4:5], 0, s[6:7]
	s_add_i32 m0, s27, 0x1a000
	s_add_i32 s48, s27, 0x8000
	s_add_i32 s49, s27, 0xa000
	global_load_lds_dwordx4 v[4:5], off
	v_lshl_add_u64 v[0:1], v[0:1], 0, s[6:7]
	s_mov_b32 m0, s48
	s_add_u32 s10, s30, 0x100080
	global_load_lds_dwordx4 v[0:1], off
	v_lshl_add_u64 v[0:1], v[2:3], 0, s[6:7]
	s_mov_b32 m0, s49
	s_addc_u32 s11, s31, 0
	global_load_lds_dwordx4 v[0:1], off
	s_add_i32 m0, s27, 0x1c000
	v_lshl_add_u64 v[0:1], s[10:11], 0, v[132:133]
	global_load_lds_dwordx4 v[0:1], off
	v_lshl_add_u64 v[0:1], s[10:11], 0, v[128:129]
	s_add_i32 m0, s27, 0x1e000
	s_cmpk_lt_u32 s1, 0x100
	global_load_lds_dwordx4 v[0:1], off
	v_lshrrev_b32_e32 v1, 1, v9
	v_and_b32_e32 v1, 24, v1
	v_and_b32_e32 v0, 15, v9
	v_lshlrev_b32_e32 v2, 1, v1
	v_lshl_or_b32 v146, s8, 6, v0
	v_lshl_or_b32 v0, v0, 6, v2
	v_lshlrev_b32_e32 v2, 2, v9
	v_and_b32_e32 v2, 32, v2
	v_bitop3_b32 v3, v0, s9, v2 bitop3:0xde
	v_bitop3_b32 v147, v0, s13, v2 bitop3:0xde
	v_lshlrev_b32_e32 v0, 16, v13
	v_and_b32_e32 v0, 0xfffe0000, v0
	v_or_b32_e32 v148, s12, v1
	v_lshl_add_u32 v0, v12, 13, v0
	v_and_b32_e32 v1, 1, v13
	v_lshl_or_b32 v0, v1, 6, v0
	v_lshl_add_u32 v136, v14, 1, v0
	v_lshlrev_b32_e32 v0, 16, v8
	v_and_b32_e32 v0, 0xfffe0000, v0
	s_waitcnt vmcnt(6)
	v_lshl_add_u32 v0, v10, 13, v0
	v_and_b32_e32 v1, 1, v8
	s_cselect_b64 s[8:9], -1, 0
	v_lshl_or_b32 v0, v1, 6, v0
	s_add_i32 s51, 0, 0x10000
	s_add_i32 s52, 0, 0x14000
	s_sext_i32_i8 s63, s0
	s_ashr_i32 s50, s3, 31
	v_mov_b32_e32 v137, v133
	v_lshl_add_u32 v138, v11, 1, v0
	v_mov_b32_e32 v139, v133
	v_mov_b64_e32 v[140:141], 0x410
	v_mov_b64_e32 v[142:143], 0x40f
	v_add_u32_e32 v149, s51, v147
	v_add_u32_e32 v150, s52, v147
	v_add_u32_e32 v151, 0, v3
	s_mov_b64 s[10:11], 0x80000
	s_mov_b32 s53, 0x80000
	s_mov_b64 s[12:13], 0x90000
	s_mov_b32 s60, 0x90000
	s_mov_b64 s[14:15], 0xa0000
	s_mov_b32 s61, 0xa0000
	s_mov_b64 s[16:17], 0xb0000
	s_mov_b32 s62, 0xb0000
	s_barrier
	s_mov_b32 s99, 0
	s_branch .LBB0_2133

; #define PG8_BAR __builtin_amdgcn_s_barrier()
; template <class Epi, class Sched, bool ALIGN_EPI = false, bool SP2 = false>
; __device__ __forceinline__ void gemm_phase(PG8_LAS unsigned char* lds, const Gemm g, const Sched& S, const Epi& E) {
;     ...
;         if (!has_next) break;
; #pragma unroll
;         for (int a = 0; a < 2; ++a)
; #pragma unroll
;             for (int b = 0; b < 2; ++b)
; #pragma unroll
;                 for (int m = 0; m < 4; ++m)
; #pragma unroll
;                     for (int n = 0; n < 2; ++n) acc[a][b][m][n] = (f32x4){0.f, 0.f, 0.f, 0.f};
;         cur = nxt; cA = nA; cB = nB; ++ui;
;         if constexpr (ALIGN_EPI) { if (wr == 1) PG8_BAR; }
;     }
.LBB0_2132:
	s_mov_b32 s99, 1
	s_andn2_b64 vcc, exec, s[0:1]
	s_mov_b32 s63, s18
	s_mov_b32 s26, s20
	s_mov_b64 s[30:31], s[24:25]
	s_mov_b64 s[28:29], s[22:23]
	s_cbranch_vccz .LBB0_2142

; #define PG8_STAGE(bufoff, gbase, voff) do { _Pragma("unroll") for (int _i = 0; _i < 2; ++_i) \
;         __builtin_amdgcn_global_load_lds((const unsigned*)((const char*)(gbase) + (voff)[_i]), (PG8_LAS unsigned*)(lds + (bufoff) + ldsw + _i * 8192), 16, 0, 0); } while (0)
; #define PG8_LDA(dst, b, h) do { _Pragma("unroll") for (int m = 0; m < 4; ++m) _Pragma("unroll") for (int k = 0; k < 2; ++k) dst[m][k] = *(const PG8_LAS bf16x8*)(lds + PG8_SA(b, h) + aoff + m * 2048 + k * 1024); } while (0)
; #define PG8_LDB(dst, b, h) do { _Pragma("unroll") for (int n = 0; n < 2; ++n) _Pragma("unroll") for (int k = 0; k < 2; ++k) dst[n][k] = *(const PG8_LAS bf16x8*)(lds + PG8_SB(b, h) + boff + n * 2048 + k * 1024); } while (0)
; #define PG8_MMA(ai, bj, At, Bt) do { __builtin_amdgcn_s_setprio(1); _Pragma("unroll") for (int m = 0; m < 4; ++m) _Pragma("unroll") for (int n = 0; n < 2; ++n) _Pragma("unroll") for (int k = 0; k < 2; ++k) \
;         acc[ai][bj][m][n] = __builtin_amdgcn_mfma_f32_16x16x32_bf16(Bt[n][k], At[m][k], acc[ai][bj][m][n], 0, 0, 0); __builtin_amdgcn_s_setprio(0); } while (0)
; #define PG8_WAIT_V(n) asm volatile("s_waitcnt vmcnt(" #n ")" ::: "memory")
; #define PG8_WAIT_L(n) asm volatile("s_waitcnt lgkmcnt(" #n ")" ::: "memory")
; #define PG8_BAR __builtin_amdgcn_s_barrier()
; template <class Epi, class Sched, bool ALIGN_EPI = false, bool SP2 = false>
; __device__ __forceinline__ void gemm_phase(PG8_LAS unsigned char* lds, const Gemm g, const Sched& S, const Epi& E) {
;     ...
;         const bool has_next = S.next(ui + 1, nxt);
;         const char* nA = has_next ? (const char*)g.A + (size_t)nxt.pm * tstep : cA; const char* nB = has_next ? (const char*)g.Bt + (size_t)nxt.pn * tstep : cB;
;         for (int t = 0; t < nt; t += 2) {
;             const bool last = (t == nt - 2);
;             const char* a1 = cA + (size_t)(t + 1) * kstep;
;             const char* a2 = last ? nA : cA + (size_t)(t + 2) * kstep; const char* b2 = last ? nB : cB + (size_t)(t + 2) * kstep;
;             const char* a3 = a2 + kstep; const char* b3 = b2 + kstep;
;             if (last && has_next) S.a_ready(nxt);
;             if constexpr (SP2) {
;             PG8_LDB(B0, 0, 0); PG8_LDB(B1, 0, 1); PG8_SCHED; PG8_LDA(At, 0, 0); PG8_STAGE(PG8_SA(1, 1), a1 + hstep, voffA);
;             PG8_WAIT_V(8); PG8_WAIT_L(0); PG8_BAR; PG8_MMA(0, 0, At, B0); PG8_MMA(0, 1, At, B1); PG8_BAR; PG8_SCHED;
.LBB0_2136:
	ds_read_b128 v[152:155], v149
	ds_read_b128 v[156:159], v149 offset:1024
	ds_read_b128 v[160:163], v149 offset:2048
	ds_read_b128 v[164:167], v149 offset:3072
	ds_read_b128 v[168:171], v150
	ds_read_b128 v[172:175], v150 offset:1024
	ds_read_b128 v[176:179], v150 offset:2048
	ds_read_b128 v[180:183], v150 offset:3072
	s_add_u32 s30, s28, 0xfff00080
	s_addc_u32 s31, s29, -1
	s_cmp_eq_u32 s68, 60
	s_cselect_b32 s35, s21, s31
	s_cselect_b32 s34, s64, s30
	s_cselect_b32 s31, s19, s67
	s_cselect_b32 s30, s65, s66
	v_lshl_add_u64 v[144:145], s[28:29], 0, v[136:137]
	s_add_i32 m0, s27, 0xc000
	ds_read_b128 v[184:187], v151
	ds_read_b128 v[188:191], v151 offset:1024
	ds_read_b128 v[192:195], v151 offset:2048
	ds_read_b128 v[196:199], v151 offset:3072
	ds_read_b128 v[200:203], v151 offset:4096
	ds_read_b128 v[204:207], v151 offset:5120
	ds_read_b128 v[208:211], v151 offset:6144
	ds_read_b128 v[212:215], v151 offset:7168
	global_load_lds_dwordx4 v[144:145], off
	v_lshl_add_u64 v[144:145], s[28:29], 0, v[138:139]
	s_add_i32 m0, s27, 0xe000
	s_nop 0
	global_load_lds_dwordx4 v[144:145], off
	s_cmp_eq_u32 s99, 1
	s_cbranch_scc1 .Lrw_P6_0
	s_waitcnt vmcnt(8)
	s_branch .Lrj_P6_0

; #define PG8_STAGE(bufoff, gbase, voff) do { _Pragma("unroll") for (int _i = 0; _i < 2; ++_i) \
;         __builtin_amdgcn_global_load_lds((const unsigned*)((const char*)(gbase) + (voff)[_i]), (PG8_LAS unsigned*)(lds + (bufoff) + ldsw + _i * 8192), 16, 0, 0); } while (0)
; #define PG8_LDA(dst, b, h) do { _Pragma("unroll") for (int m = 0; m < 4; ++m) _Pragma("unroll") for (int k = 0; k < 2; ++k) dst[m][k] = *(const PG8_LAS bf16x8*)(lds + PG8_SA(b, h) + aoff + m * 2048 + k * 1024); } while (0)
; #define PG8_MMA(ai, bj, At, Bt) do { __builtin_amdgcn_s_setprio(1); _Pragma("unroll") for (int m = 0; m < 4; ++m) _Pragma("unroll") for (int n = 0; n < 2; ++n) _Pragma("unroll") for (int k = 0; k < 2; ++k) \
;         acc[ai][bj][m][n] = __builtin_amdgcn_mfma_f32_16x16x32_bf16(Bt[n][k], At[m][k], acc[ai][bj][m][n], 0, 0, 0); __builtin_amdgcn_s_setprio(0); } while (0)
; #define PG8_WAIT_V(n) asm volatile("s_waitcnt vmcnt(" #n ")" ::: "memory")
; #define PG8_WAIT_L(n) asm volatile("s_waitcnt lgkmcnt(" #n ")" ::: "memory")
; #define PG8_BAR __builtin_amdgcn_s_barrier()
; #define PG8_SCHED __builtin_amdgcn_sched_barrier(0)
; template <class Epi, class Sched, bool ALIGN_EPI = false, bool SP2 = false>
; __device__ __forceinline__ void gemm_phase(PG8_LAS unsigned char* lds, const Gemm g, const Sched& S, const Epi& E) {
;     ...
;             PG8_WAIT_V(8); PG8_WAIT_L(0); PG8_BAR; PG8_MMA(0, 0, At, B0); PG8_MMA(0, 1, At, B1); PG8_BAR; PG8_SCHED;
;             PG8_LDA(At, 0, 1); PG8_STAGE(PG8_SB(0, 0), b2, voffB); PG8_STAGE(PG8_SB(0, 1), b2 + hstep, voffB); PG8_STAGE(PG8_SA(0, 0), a2, voffA);
;             PG8_WAIT_V(8); PG8_WAIT_L(0); PG8_BAR; PG8_MMA(1, 0, At, B0); PG8_MMA(1, 1, At, B1); PG8_BAR; PG8_SCHED;
.Lrj_P6_0:
	s_waitcnt lgkmcnt(0)
	s_barrier
	s_setprio 1
	s_waitcnt lgkmcnt(0)
	v_mfma_f32_16x16x32_bf16 v[124:127], v[152:155], v[184:187], v[124:127]
	v_mfma_f32_16x16x32_bf16 v[120:123], v[160:163], v[184:187], v[120:123]
	v_mfma_f32_16x16x32_bf16 v[108:111], v[152:155], v[192:195], v[108:111]
	v_mfma_f32_16x16x32_bf16 v[104:107], v[160:163], v[192:195], v[104:107]
	v_mfma_f32_16x16x32_bf16 v[92:95], v[152:155], v[200:203], v[92:95]
	v_mfma_f32_16x16x32_bf16 v[88:91], v[160:163], v[200:203], v[88:91]
	v_mfma_f32_16x16x32_bf16 v[76:79], v[152:155], v[208:211], v[76:79]
	v_mfma_f32_16x16x32_bf16 v[72:75], v[160:163], v[208:211], v[72:75]
	v_mfma_f32_16x16x32_bf16 v[124:127], v[156:159], v[188:191], v[124:127]
	v_mfma_f32_16x16x32_bf16 v[120:123], v[164:167], v[188:191], v[120:123]
	v_mfma_f32_16x16x32_bf16 v[108:111], v[156:159], v[196:199], v[108:111]
	v_mfma_f32_16x16x32_bf16 v[104:107], v[164:167], v[196:199], v[104:107]
	v_mfma_f32_16x16x32_bf16 v[92:95], v[156:159], v[204:207], v[92:95]
	v_mfma_f32_16x16x32_bf16 v[88:91], v[164:167], v[204:207], v[88:91]
	v_mfma_f32_16x16x32_bf16 v[76:79], v[156:159], v[212:215], v[76:79]
	v_mfma_f32_16x16x32_bf16 v[72:75], v[164:167], v[212:215], v[72:75]
	s_setprio 0
	s_setprio 1
	v_mfma_f32_16x16x32_bf16 v[116:119], v[168:171], v[184:187], v[116:119]
	v_mfma_f32_16x16x32_bf16 v[112:115], v[176:179], v[184:187], v[112:115]
	v_mfma_f32_16x16x32_bf16 v[100:103], v[168:171], v[192:195], v[100:103]
	v_mfma_f32_16x16x32_bf16 v[96:99], v[176:179], v[192:195], v[96:99]
	v_mfma_f32_16x16x32_bf16 v[84:87], v[168:171], v[200:203], v[84:87]
	v_mfma_f32_16x16x32_bf16 v[80:83], v[176:179], v[200:203], v[80:83]
	v_mfma_f32_16x16x32_bf16 v[68:71], v[168:171], v[208:211], v[68:71]
	v_mfma_f32_16x16x32_bf16 v[64:67], v[176:179], v[208:211], v[64:67]
	v_mfma_f32_16x16x32_bf16 v[116:119], v[172:175], v[188:191], v[116:119]
	v_mfma_f32_16x16x32_bf16 v[112:115], v[180:183], v[188:191], v[112:115]
	v_mfma_f32_16x16x32_bf16 v[100:103], v[172:175], v[196:199], v[100:103]
	v_mfma_f32_16x16x32_bf16 v[96:99], v[180:183], v[196:199], v[96:99]
	v_mfma_f32_16x16x32_bf16 v[84:87], v[172:175], v[204:207], v[84:87]
	v_mfma_f32_16x16x32_bf16 v[80:83], v[180:183], v[204:207], v[80:83]
	v_mfma_f32_16x16x32_bf16 v[68:71], v[172:175], v[212:215], v[68:71]
	v_mfma_f32_16x16x32_bf16 v[64:67], v[180:183], v[212:215], v[64:67]
	s_setprio 0
	s_barrier
	s_add_i32 s69, s51, s39
	v_lshl_add_u64 v[144:145], s[30:31], 0, v[132:133]
	s_mov_b32 m0, s69
	ds_read_b128 v[184:187], v151 offset:16384
	ds_read_b128 v[188:191], v151 offset:17408
	ds_read_b128 v[192:195], v151 offset:18432
	ds_read_b128 v[196:199], v151 offset:19456
	ds_read_b128 v[200:203], v151 offset:20480
	ds_read_b128 v[204:207], v151 offset:21504
	ds_read_b128 v[208:211], v151 offset:22528
	ds_read_b128 v[212:215], v151 offset:23552
	global_load_lds_dwordx4 v[144:145], off
	s_add_i32 m0, s69, 0x2000
	s_add_u32 s70, s30, 0x100000
	v_lshl_add_u64 v[216:217], s[30:31], 0, v[128:129]
	s_addc_u32 s71, s31, 0
	s_add_i32 s69, s52, s39
	global_load_lds_dwordx4 v[216:217], off
	v_lshl_add_u64 v[218:219], s[70:71], 0, v[132:133]
	s_mov_b32 m0, s69
	v_lshl_add_u64 v[220:221], s[34:35], 0, v[130:131]
	global_load_lds_dwordx4 v[218:219], off
	v_lshl_add_u64 v[218:219], s[70:71], 0, v[128:129]
	s_add_i32 m0, s69, 0x2000
	s_nop 0
	global_load_lds_dwordx4 v[218:219], off
	v_lshl_add_u64 v[218:219], s[34:35], 0, v[134:135]
	s_mov_b32 m0, s27
	s_nop 0
	global_load_lds_dwordx4 v[218:219], off
	s_mov_b32 m0, s42
	s_nop 0
	global_load_lds_dwordx4 v[220:221], off
	s_cmp_eq_u32 s99, 1
	s_cbranch_scc1 .Lrw_P6_1
	s_waitcnt vmcnt(8)
	s_branch .Lrj_P6_1

; #define PG8_STAGE(bufoff, gbase, voff) do { _Pragma("unroll") for (int _i = 0; _i < 2; ++_i) \
;         __builtin_amdgcn_global_load_lds((const unsigned*)((const char*)(gbase) + (voff)[_i]), (PG8_LAS unsigned*)(lds + (bufoff) + ldsw + _i * 8192), 16, 0, 0); } while (0)
; #define PG8_LDA(dst, b, h) do { _Pragma("unroll") for (int m = 0; m < 4; ++m) _Pragma("unroll") for (int k = 0; k < 2; ++k) dst[m][k] = *(const PG8_LAS bf16x8*)(lds + PG8_SA(b, h) + aoff + m * 2048 + k * 1024); } while (0)
; #define PG8_LDB(dst, b, h) do { _Pragma("unroll") for (int n = 0; n < 2; ++n) _Pragma("unroll") for (int k = 0; k < 2; ++k) dst[n][k] = *(const PG8_LAS bf16x8*)(lds + PG8_SB(b, h) + boff + n * 2048 + k * 1024); } while (0)
; #define PG8_MMA(ai, bj, At, Bt) do { __builtin_amdgcn_s_setprio(1); _Pragma("unroll") for (int m = 0; m < 4; ++m) _Pragma("unroll") for (int n = 0; n < 2; ++n) _Pragma("unroll") for (int k = 0; k < 2; ++k) \
;         acc[ai][bj][m][n] = __builtin_amdgcn_mfma_f32_16x16x32_bf16(Bt[n][k], At[m][k], acc[ai][bj][m][n], 0, 0, 0); __builtin_amdgcn_s_setprio(0); } while (0)
; #define PG8_WAIT_V(n) asm volatile("s_waitcnt vmcnt(" #n ")" ::: "memory")
; #define PG8_WAIT_L(n) asm volatile("s_waitcnt lgkmcnt(" #n ")" ::: "memory")
; #define PG8_BAR __builtin_amdgcn_s_barrier()
; #define PG8_SCHED __builtin_amdgcn_sched_barrier(0)
; template <class Epi, class Sched, bool ALIGN_EPI = false, bool SP2 = false>
; __device__ __forceinline__ void gemm_phase(PG8_LAS unsigned char* lds, const Gemm g, const Sched& S, const Epi& E) {
;     ...
;             PG8_WAIT_V(8); PG8_WAIT_L(0); PG8_BAR; PG8_MMA(1, 0, At, B0); PG8_MMA(1, 1, At, B1); PG8_BAR; PG8_SCHED;
;             PG8_LDB(B0, 1, 0); PG8_LDB(B1, 1, 1); PG8_SCHED; PG8_LDA(At, 1, 0); PG8_STAGE(PG8_SA(0, 1), a2 + hstep, voffA);
;             PG8_WAIT_V(8); PG8_WAIT_L(0); PG8_BAR; PG8_MMA(0, 0, At, B0); PG8_MMA(0, 1, At, B1); PG8_BAR; PG8_SCHED;
.Lrj_P6_1:
	s_waitcnt lgkmcnt(0)
	s_barrier
	s_setprio 1
	s_waitcnt lgkmcnt(0)
	v_mfma_f32_16x16x32_bf16 v[60:63], v[152:155], v[184:187], v[60:63]
	v_mfma_f32_16x16x32_bf16 v[56:59], v[160:163], v[184:187], v[56:59]
	v_mfma_f32_16x16x32_bf16 v[44:47], v[152:155], v[192:195], v[44:47]
	v_mfma_f32_16x16x32_bf16 v[40:43], v[160:163], v[192:195], v[40:43]
	v_mfma_f32_16x16x32_bf16 v[28:31], v[152:155], v[200:203], v[28:31]
	v_mfma_f32_16x16x32_bf16 v[24:27], v[160:163], v[200:203], v[24:27]
	v_mfma_f32_16x16x32_bf16 v[12:15], v[152:155], v[208:211], v[12:15]
	v_mfma_f32_16x16x32_bf16 v[8:11], v[160:163], v[208:211], v[8:11]
	v_mfma_f32_16x16x32_bf16 v[60:63], v[156:159], v[188:191], v[60:63]
	v_mfma_f32_16x16x32_bf16 v[56:59], v[164:167], v[188:191], v[56:59]
	v_mfma_f32_16x16x32_bf16 v[44:47], v[156:159], v[196:199], v[44:47]
	v_mfma_f32_16x16x32_bf16 v[40:43], v[164:167], v[196:199], v[40:43]
	v_mfma_f32_16x16x32_bf16 v[28:31], v[156:159], v[204:207], v[28:31]
	v_mfma_f32_16x16x32_bf16 v[24:27], v[164:167], v[204:207], v[24:27]
	v_mfma_f32_16x16x32_bf16 v[12:15], v[156:159], v[212:215], v[12:15]
	v_mfma_f32_16x16x32_bf16 v[8:11], v[164:167], v[212:215], v[8:11]
	s_setprio 0
	s_setprio 1
	v_mfma_f32_16x16x32_bf16 v[52:55], v[168:171], v[184:187], v[52:55]
	v_mfma_f32_16x16x32_bf16 v[48:51], v[176:179], v[184:187], v[48:51]
	v_mfma_f32_16x16x32_bf16 v[36:39], v[168:171], v[192:195], v[36:39]
	v_mfma_f32_16x16x32_bf16 v[32:35], v[176:179], v[192:195], v[32:35]
	v_mfma_f32_16x16x32_bf16 v[20:23], v[168:171], v[200:203], v[20:23]
	v_mfma_f32_16x16x32_bf16 v[16:19], v[176:179], v[200:203], v[16:19]
	v_mfma_f32_16x16x32_bf16 v[4:7], v[168:171], v[208:211], v[4:7]
	v_mfma_f32_16x16x32_bf16 v[0:3], v[176:179], v[208:211], v[0:3]
	v_mfma_f32_16x16x32_bf16 v[52:55], v[172:175], v[188:191], v[52:55]
	v_mfma_f32_16x16x32_bf16 v[48:51], v[180:183], v[188:191], v[48:51]
	v_mfma_f32_16x16x32_bf16 v[36:39], v[172:175], v[196:199], v[36:39]
	v_mfma_f32_16x16x32_bf16 v[32:35], v[180:183], v[196:199], v[32:35]
	v_mfma_f32_16x16x32_bf16 v[20:23], v[172:175], v[204:207], v[20:23]
	v_mfma_f32_16x16x32_bf16 v[16:19], v[180:183], v[204:207], v[16:19]
	v_mfma_f32_16x16x32_bf16 v[4:7], v[172:175], v[212:215], v[4:7]
	v_mfma_f32_16x16x32_bf16 v[0:3], v[180:183], v[212:215], v[0:3]
	s_setprio 0
	s_barrier
	s_add_i32 s69, 0, 0x18000
	s_add_i32 s70, 0, 0x1c000
	v_add_u32_e32 v164, s69, v147
	v_add_u32_e32 v180, s70, v147
	ds_read_b128 v[152:155], v164
	ds_read_b128 v[156:159], v164 offset:1024
	ds_read_b128 v[160:163], v164 offset:2048
	ds_read_b128 v[164:167], v164 offset:3072
	ds_read_b128 v[168:171], v180
	ds_read_b128 v[172:175], v180 offset:1024
	ds_read_b128 v[176:179], v180 offset:2048
	ds_read_b128 v[180:183], v180 offset:3072
	s_add_u32 s34, s34, 0x100000
	s_addc_u32 s35, s35, 0
	s_mov_b32 m0, s43
	v_lshl_add_u64 v[222:223], s[34:35], 0, v[134:135]
	ds_read_b128 v[184:187], v151 offset:32768
	ds_read_b128 v[188:191], v151 offset:33792
	ds_read_b128 v[192:195], v151 offset:34816
	ds_read_b128 v[196:199], v151 offset:35840
	ds_read_b128 v[200:203], v151 offset:36864
	ds_read_b128 v[204:207], v151 offset:37888
	ds_read_b128 v[208:211], v151 offset:38912
	ds_read_b128 v[212:215], v151 offset:39936
	global_load_lds_dwordx4 v[222:223], off
	v_lshl_add_u64 v[222:223], s[34:35], 0, v[130:131]
	s_mov_b32 m0, s46
	s_nop 0
	global_load_lds_dwordx4 v[222:223], off
	s_waitcnt vmcnt(8)
	s_waitcnt lgkmcnt(0)
	s_barrier
	s_setprio 1
	s_waitcnt lgkmcnt(0)
	v_mfma_f32_16x16x32_bf16 v[124:127], v[152:155], v[184:187], v[124:127]
	v_mfma_f32_16x16x32_bf16 v[120:123], v[160:163], v[184:187], v[120:123]
	v_mfma_f32_16x16x32_bf16 v[108:111], v[152:155], v[192:195], v[108:111]
	v_mfma_f32_16x16x32_bf16 v[104:107], v[160:163], v[192:195], v[104:107]
	v_mfma_f32_16x16x32_bf16 v[92:95], v[152:155], v[200:203], v[92:95]
	v_mfma_f32_16x16x32_bf16 v[88:91], v[160:163], v[200:203], v[88:91]
	v_mfma_f32_16x16x32_bf16 v[76:79], v[152:155], v[208:211], v[76:79]
	v_mfma_f32_16x16x32_bf16 v[72:75], v[160:163], v[208:211], v[72:75]
	v_mfma_f32_16x16x32_bf16 v[124:127], v[156:159], v[188:191], v[124:127]
	v_mfma_f32_16x16x32_bf16 v[120:123], v[164:167], v[188:191], v[120:123]
	v_mfma_f32_16x16x32_bf16 v[108:111], v[156:159], v[196:199], v[108:111]
	v_mfma_f32_16x16x32_bf16 v[104:107], v[164:167], v[196:199], v[104:107]
	v_mfma_f32_16x16x32_bf16 v[92:95], v[156:159], v[204:207], v[92:95]
	v_mfma_f32_16x16x32_bf16 v[88:91], v[164:167], v[204:207], v[88:91]
	v_mfma_f32_16x16x32_bf16 v[76:79], v[156:159], v[212:215], v[76:79]
	v_mfma_f32_16x16x32_bf16 v[72:75], v[164:167], v[212:215], v[72:75]
	s_setprio 0
	s_setprio 1
	v_mfma_f32_16x16x32_bf16 v[116:119], v[168:171], v[184:187], v[116:119]
	v_mfma_f32_16x16x32_bf16 v[112:115], v[176:179], v[184:187], v[112:115]
	v_mfma_f32_16x16x32_bf16 v[100:103], v[168:171], v[192:195], v[100:103]
	v_mfma_f32_16x16x32_bf16 v[96:99], v[176:179], v[192:195], v[96:99]
	v_mfma_f32_16x16x32_bf16 v[84:87], v[168:171], v[200:203], v[84:87]
	v_mfma_f32_16x16x32_bf16 v[80:83], v[176:179], v[200:203], v[80:83]
	v_mfma_f32_16x16x32_bf16 v[68:71], v[168:171], v[208:211], v[68:71]
	v_mfma_f32_16x16x32_bf16 v[64:67], v[176:179], v[208:211], v[64:67]
	v_mfma_f32_16x16x32_bf16 v[116:119], v[172:175], v[188:191], v[116:119]
	v_mfma_f32_16x16x32_bf16 v[112:115], v[180:183], v[188:191], v[112:115]
	v_mfma_f32_16x16x32_bf16 v[100:103], v[172:175], v[196:199], v[100:103]
	v_mfma_f32_16x16x32_bf16 v[96:99], v[180:183], v[196:199], v[96:99]
	v_mfma_f32_16x16x32_bf16 v[84:87], v[172:175], v[204:207], v[84:87]
	v_mfma_f32_16x16x32_bf16 v[80:83], v[180:183], v[204:207], v[80:83]
	v_mfma_f32_16x16x32_bf16 v[68:71], v[172:175], v[212:215], v[68:71]
	v_mfma_f32_16x16x32_bf16 v[64:67], v[180:183], v[212:215], v[64:67]
	s_setprio 0
	s_barrier
; #define PG8_STAGE(bufoff, gbase, voff) do { _Pragma("unroll") for (int _i = 0; _i < 2; ++_i) \
;         __builtin_amdgcn_global_load_lds((const unsigned*)((const char*)(gbase) + (voff)[_i]), (PG8_LAS unsigned*)(lds + (bufoff) + ldsw + _i * 8192), 16, 0, 0); } while (0)
; #define PG8_LDA(dst, b, h) do { _Pragma("unroll") for (int m = 0; m < 4; ++m) _Pragma("unroll") for (int k = 0; k < 2; ++k) dst[m][k] = *(const PG8_LAS bf16x8*)(lds + PG8_SA(b, h) + aoff + m * 2048 + k * 1024); } while (0)
; #define PG8_MMA(ai, bj, At, Bt) do { __builtin_amdgcn_s_setprio(1); _Pragma("unroll") for (int m = 0; m < 4; ++m) _Pragma("unroll") for (int n = 0; n < 2; ++n) _Pragma("unroll") for (int k = 0; k < 2; ++k) \
;         acc[ai][bj][m][n] = __builtin_amdgcn_mfma_f32_16x16x32_bf16(Bt[n][k], At[m][k], acc[ai][bj][m][n], 0, 0, 0); __builtin_amdgcn_s_setprio(0); } while (0)
; #define PG8_WAIT_V(n) asm volatile("s_waitcnt vmcnt(" #n ")" ::: "memory")
; #define PG8_WAIT_L(n) asm volatile("s_waitcnt lgkmcnt(" #n ")" ::: "memory")
; #define PG8_BAR __builtin_amdgcn_s_barrier()
; #define PG8_SCHED __builtin_amdgcn_sched_barrier(0)
; template <class Epi, class Sched, bool ALIGN_EPI = false, bool SP2 = false>
; __device__ __forceinline__ void gemm_phase(PG8_LAS unsigned char* lds, const Gemm g, const Sched& S, const Epi& E) {
;     ...
;             PG8_LDA(At, 1, 1); PG8_STAGE(PG8_SB(1, 0), b3, voffB); PG8_STAGE(PG8_SB(1, 1), b3 + hstep, voffB); PG8_STAGE(PG8_SA(1, 0), a3, voffA);
;             PG8_WAIT_V(8); PG8_WAIT_L(0); PG8_BAR; PG8_MMA(1, 0, At, B0); PG8_MMA(1, 1, At, B1); PG8_BAR; PG8_SCHED;
;     ...
;         if constexpr (ALIGN_EPI) { if (wr == 0) PG8_BAR; }
;         if constexpr (!Epi::AFTER_DRAIN) { E(acc, cur, wr, wc, fr, fq); S.done(cur); }
;         if (!has_next) break;
	s_add_i32 s34, s69, s39
	v_lshl_add_u64 v[144:145], v[144:145], 0, s[6:7]
	s_mov_b32 m0, s34
	ds_read_b128 v[184:187], v151 offset:49152
	ds_read_b128 v[188:191], v151 offset:50176
	ds_read_b128 v[192:195], v151 offset:51200
	ds_read_b128 v[196:199], v151 offset:52224
	ds_read_b128 v[200:203], v151 offset:53248
	ds_read_b128 v[204:207], v151 offset:54272
	ds_read_b128 v[208:211], v151 offset:55296
	ds_read_b128 v[212:215], v151 offset:56320
	global_load_lds_dwordx4 v[144:145], off
	s_add_i32 m0, s34, 0x2000
	s_add_u32 s30, s30, 0x100080
	v_lshl_add_u64 v[144:145], v[216:217], 0, s[6:7]
	s_addc_u32 s31, s31, 0
	s_add_i32 s34, s70, s39
	global_load_lds_dwordx4 v[144:145], off
	v_lshl_add_u64 v[144:145], s[30:31], 0, v[132:133]
	s_mov_b32 m0, s34
	s_nop 0
	global_load_lds_dwordx4 v[144:145], off
	v_lshl_add_u64 v[144:145], s[30:31], 0, v[128:129]
	s_add_i32 m0, s34, 0x2000
	s_nop 0
	global_load_lds_dwordx4 v[144:145], off
	v_lshl_add_u64 v[144:145], v[218:219], 0, s[6:7]
	s_mov_b32 m0, s48
	s_nop 0
	global_load_lds_dwordx4 v[144:145], off
	v_lshl_add_u64 v[144:145], v[220:221], 0, s[6:7]
	s_mov_b32 m0, s49
	s_nop 0
	global_load_lds_dwordx4 v[144:145], off
	s_waitcnt vmcnt(8)
	s_waitcnt lgkmcnt(0)
	s_barrier
	s_setprio 1
	s_waitcnt lgkmcnt(0)
	v_mfma_f32_16x16x32_bf16 v[60:63], v[152:155], v[184:187], v[60:63]
	v_mfma_f32_16x16x32_bf16 v[56:59], v[160:163], v[184:187], v[56:59]
	v_mfma_f32_16x16x32_bf16 v[44:47], v[152:155], v[192:195], v[44:47]
	v_mfma_f32_16x16x32_bf16 v[40:43], v[160:163], v[192:195], v[40:43]
	v_mfma_f32_16x16x32_bf16 v[28:31], v[152:155], v[200:203], v[28:31]
	v_mfma_f32_16x16x32_bf16 v[24:27], v[160:163], v[200:203], v[24:27]
	v_mfma_f32_16x16x32_bf16 v[12:15], v[152:155], v[208:211], v[12:15]
	v_mfma_f32_16x16x32_bf16 v[8:11], v[160:163], v[208:211], v[8:11]
	v_mfma_f32_16x16x32_bf16 v[60:63], v[156:159], v[188:191], v[60:63]
	v_mfma_f32_16x16x32_bf16 v[56:59], v[164:167], v[188:191], v[56:59]
	v_mfma_f32_16x16x32_bf16 v[44:47], v[156:159], v[196:199], v[44:47]
	v_mfma_f32_16x16x32_bf16 v[40:43], v[164:167], v[196:199], v[40:43]
	v_mfma_f32_16x16x32_bf16 v[28:31], v[156:159], v[204:207], v[28:31]
	v_mfma_f32_16x16x32_bf16 v[24:27], v[164:167], v[204:207], v[24:27]
	v_mfma_f32_16x16x32_bf16 v[12:15], v[156:159], v[212:215], v[12:15]
	v_mfma_f32_16x16x32_bf16 v[8:11], v[164:167], v[212:215], v[8:11]
	s_setprio 0
	s_setprio 1
	v_mfma_f32_16x16x32_bf16 v[52:55], v[168:171], v[184:187], v[52:55]
	v_mfma_f32_16x16x32_bf16 v[48:51], v[176:179], v[184:187], v[48:51]
	v_mfma_f32_16x16x32_bf16 v[36:39], v[168:171], v[192:195], v[36:39]
	v_mfma_f32_16x16x32_bf16 v[32:35], v[176:179], v[192:195], v[32:35]
	v_mfma_f32_16x16x32_bf16 v[20:23], v[168:171], v[200:203], v[20:23]
	v_mfma_f32_16x16x32_bf16 v[16:19], v[176:179], v[200:203], v[16:19]
	v_mfma_f32_16x16x32_bf16 v[4:7], v[168:171], v[208:211], v[4:7]
	v_mfma_f32_16x16x32_bf16 v[0:3], v[176:179], v[208:211], v[0:3]
	v_mfma_f32_16x16x32_bf16 v[52:55], v[172:175], v[188:191], v[52:55]
	v_mfma_f32_16x16x32_bf16 v[48:51], v[180:183], v[188:191], v[48:51]
	v_mfma_f32_16x16x32_bf16 v[36:39], v[172:175], v[196:199], v[36:39]
	v_mfma_f32_16x16x32_bf16 v[32:35], v[180:183], v[196:199], v[32:35]
	v_mfma_f32_16x16x32_bf16 v[20:23], v[172:175], v[204:207], v[20:23]
	v_mfma_f32_16x16x32_bf16 v[16:19], v[180:183], v[204:207], v[16:19]
	v_mfma_f32_16x16x32_bf16 v[4:7], v[172:175], v[212:215], v[4:7]
	v_mfma_f32_16x16x32_bf16 v[0:3], v[180:183], v[212:215], v[0:3]
	s_setprio 0
	s_barrier
	s_mov_b32 s99, 0
	s_add_i32 s68, s68, 2
	s_add_u32 s28, s28, 0x100
	s_addc_u32 s29, s29, 0
	s_add_u32 s66, s66, 0x100
	s_addc_u32 s67, s67, 0
	s_cmp_gt_u32 s68, 61
	s_cbranch_scc0 .LBB0_2136
	s_and_b64 vcc, exec, s[8:9]
	s_cbranch_vccz .LBB0_2139
	s_barrier
